# MFMAs of each K-loop block reordered into back-to-back same-accumulator chains (k0,k1 adjacent) to use SrcC forwarding; pure reorder
# speedup vs baseline: 1.0100x; 1.0100x over previous
; #define PG8_STAGE(bufoff, gbase, voff) do { _Pragma("unroll") for (int _i = 0; _i < 2; ++_i) \
;         __builtin_amdgcn_global_load_lds((const unsigned*)((const char*)(gbase) + (voff)[_i]), (LAS unsigned*)(lds + (bufoff) + ldsw + _i * 8192), 16, 0, 0); } while (0)
; #define PG8_LDA(dst, b, h) do { _Pragma("unroll") for (int m = 0; m < 4; ++m) _Pragma("unroll") for (int k = 0; k < 2; ++k) dst[m][k] = *(const LAS bf16x8*)(lds + PG8_SA(b, h) + aoffk[k] + m * 2048); } while (0)
; template <class Epi, class Sched, class GemmT>
; __device__ __forceinline__ void gemm_phase(LAS unsigned char* lds, const GemmT& g, const Sched& S, const Epi& E, const int wid) {
;     ...
;             for (int t = 0; t < nt; t += 2) {
;                 const bool last = (t == nt - 2);
;                 const char* a1 = cA + (size_t)(t + 1) * kstep;
;                 const char* a2 = last ? ns.A : cA + (size_t)(t + 2) * kstep; const char* b2 = last ? ns.B : cB + (size_t)(t + 2) * kstep;
;                 const char* a3 = a2 + kstep; const char* b3 = b2 + kstep;
;                 unsigned vA2[2], vB2[2];
; #pragma unroll
;                 for (int i = 0; i < 2; ++i) { vA2[i] = last ? nvA[i] : voffA[i]; vB2[i] = last ? nvB[i] : voffB[i]; }
;                 const size_t hA2 = last ? nhA : hstepA, hB2 = last ? nhB : hstepB;
;                 PG8_LDB(B0, 0, 0); PG8_LDB(B1, 0, 1); PG8_SCHED; PG8_LDA(At, 0, 0); PG8_STAGE(PG8_SA(1, 1), a1 + hstepA, voffA);
;                 PG8_WAIT_V(8); PG8_WAIT_L(0); PG8_BAR; PG8_MMA(0, 0, At, B0); PG8_MMA(0, 1, At, B1); PG8_BAR; PG8_SCHED;
;                 PG8_LDA(At, 0, 1); PG8_STAGE(PG8_SB(0, 0), b2, vB2); PG8_STAGE(PG8_SB(0, 1), b2 + hB2, vB2); PG8_STAGE(PG8_SA(0, 0), a2, vA2);
;                 PG8_WAIT_V(8); PG8_WAIT_L(0); PG8_BAR; PG8_MMA(1, 0, At, B0); PG8_MMA(1, 1, At, B1); PG8_BAR; PG8_SCHED;
;                 PG8_LDB(B0, 1, 0); PG8_LDB(B1, 1, 1); PG8_SCHED; PG8_LDA(At, 1, 0); PG8_STAGE(PG8_SA(0, 1), a2 + hA2, vA2);
;                 PG8_WAIT_V(8); PG8_WAIT_L(0); PG8_BAR; PG8_MMA(0, 0, At, B0); PG8_MMA(0, 1, At, B1); PG8_BAR; PG8_SCHED;
;                 PG8_LDA(At, 1, 1); PG8_STAGE(PG8_SB(1, 0), b3, vB2); PG8_STAGE(PG8_SB(1, 1), b3 + hB2, vB2); PG8_STAGE(PG8_SA(1, 0), a3, vA2);
;                 PG8_WAIT_V(8); PG8_WAIT_L(0); PG8_BAR; PG8_MMA(1, 0, At, B0); PG8_MMA(1, 1, At, B1); PG8_BAR; PG8_SCHED;
;             }
.LBB0_361:
	ds_read_b128 v[24:27], v186
	ds_read_b128 v[28:31], v187
	ds_read_b128 v[16:19], v188
	ds_read_b128 v[20:23], v189
	ds_read_b128 v[8:11], v190
	ds_read_b128 v[12:15], v191
	ds_read_b128 v[0:3], v192
	ds_read_b128 v[4:7], v193
	s_add_u32 s41, s56, 0xfff80080
	s_addc_u32 s48, s57, -1
	s_cmp_eq_u32 s40, 28
	s_cselect_b32 s83, s43, s48
	s_cselect_b32 s82, s42, s41
	s_cselect_b32 s59, s37, s39
	s_cselect_b32 s58, s36, s38
	v_lshl_add_u64 v[230:231], s[56:57], 0, v[160:161]
	s_add_i32 m0, s12, 0xc000
	ds_read_b128 v[174:177], v194
	ds_read_b128 v[204:207], v194 offset:2048
	ds_read_b128 v[178:181], v195
	ds_read_b128 v[208:211], v195 offset:2048
	ds_read_b128 v[212:215], v194 offset:4096
	ds_read_b128 v[220:223], v194 offset:6144
	ds_read_b128 v[216:219], v195 offset:4096
	ds_read_b128 v[224:227], v195 offset:6144
	global_load_lds_dwordx4 v[230:231], off
	v_lshl_add_u64 v[230:231], s[56:57], 0, v[164:165]
	s_add_i32 m0, s12, 0xe000
	s_nop 0
	global_load_lds_dwordx4 v[230:231], off
	s_waitcnt vmcnt(8)
	s_waitcnt lgkmcnt(0)
	s_barrier
	s_setprio 3
	s_waitcnt lgkmcnt(0)
	v_mfma_scale_f32_16x16x128_f8f6f4 v[156:159], v[24:31], v[174:181], v[156:159], v196, v196 op_sel_hi:[0,0,0]
	v_mfma_scale_f32_16x16x128_f8f6f4 v[152:155], v[16:23], v[174:181], v[152:155], v196, v196 op_sel_hi:[0,0,0]
	v_mfma_scale_f32_16x16x128_f8f6f4 v[136:139], v[16:23], v[204:211], v[136:139], v196, v196 op_sel_hi:[0,0,0]
	v_mfma_scale_f32_16x16x128_f8f6f4 v[140:143], v[24:31], v[204:211], v[140:143], v196, v196 op_sel_hi:[0,0,0]
	v_mfma_scale_f32_16x16x128_f8f6f4 v[124:127], v[24:31], v[212:219], v[124:127], v196, v196 op_sel_hi:[0,0,0]
	v_mfma_scale_f32_16x16x128_f8f6f4 v[120:123], v[16:23], v[212:219], v[120:123], v196, v196 op_sel_hi:[0,0,0]
	v_mfma_scale_f32_16x16x128_f8f6f4 v[104:107], v[16:23], v[220:227], v[104:107], v196, v196 op_sel_hi:[0,0,0]
	v_mfma_scale_f32_16x16x128_f8f6f4 v[108:111], v[24:31], v[220:227], v[108:111], v196, v196 op_sel_hi:[0,0,0]
	s_setprio 0
	s_setprio 3
	v_mfma_scale_f32_16x16x128_f8f6f4 v[148:151], v[8:15], v[174:181], v[148:151], v196, v196 op_sel_hi:[0,0,0]
	v_mfma_scale_f32_16x16x128_f8f6f4 v[144:147], v[0:7], v[174:181], v[144:147], v196, v196 op_sel_hi:[0,0,0]
	v_mfma_scale_f32_16x16x128_f8f6f4 v[128:131], v[0:7], v[204:211], v[128:131], v196, v196 op_sel_hi:[0,0,0]
	v_mfma_scale_f32_16x16x128_f8f6f4 v[132:135], v[8:15], v[204:211], v[132:135], v196, v196 op_sel_hi:[0,0,0]
	v_mfma_scale_f32_16x16x128_f8f6f4 v[116:119], v[8:15], v[212:219], v[116:119], v196, v196 op_sel_hi:[0,0,0]
	v_mfma_scale_f32_16x16x128_f8f6f4 v[112:115], v[0:7], v[212:219], v[112:115], v196, v196 op_sel_hi:[0,0,0]
	v_mfma_scale_f32_16x16x128_f8f6f4 v[96:99], v[0:7], v[220:227], v[96:99], v196, v196 op_sel_hi:[0,0,0]
	v_mfma_scale_f32_16x16x128_f8f6f4 v[100:103], v[8:15], v[220:227], v[100:103], v196, v196 op_sel_hi:[0,0,0]
	s_setprio 0
	s_barrier
	s_add_i32 s41, s64, s68
	v_lshl_add_u64 v[174:175], s[58:59], 0, v[162:163]
	s_mov_b32 m0, s41
	ds_read_b128 v[204:207], v194 offset:16384
	ds_read_b128 v[212:215], v194 offset:18432
	ds_read_b128 v[208:211], v195 offset:16384
	ds_read_b128 v[216:219], v195 offset:18432
	ds_read_b128 v[220:223], v194 offset:20480
	ds_read_b128 v[230:233], v194 offset:22528
	ds_read_b128 v[224:227], v195 offset:20480
	ds_read_b128 v[234:237], v195 offset:22528
	global_load_lds_dwordx4 v[174:175], off
	s_add_i32 m0, s41, 0x2000
	s_add_u32 s50, s58, 0x80000
	v_lshl_add_u64 v[176:177], s[58:59], 0, v[166:167]
	s_addc_u32 s51, s59, 0
	s_add_i32 s41, s65, s68
	global_load_lds_dwordx4 v[176:177], off
	v_lshl_add_u64 v[178:179], s[50:51], 0, v[162:163]
	s_mov_b32 m0, s41
	v_lshl_add_u64 v[180:181], s[82:83], 0, v[164:165]
	global_load_lds_dwordx4 v[178:179], off
	v_lshl_add_u64 v[178:179], s[50:51], 0, v[166:167]
	s_add_i32 m0, s41, 0x2000
	s_nop 0
	global_load_lds_dwordx4 v[178:179], off
	v_lshl_add_u64 v[178:179], s[82:83], 0, v[160:161]
	s_mov_b32 m0, s12
	s_nop 0
	global_load_lds_dwordx4 v[178:179], off
	s_mov_b32 m0, s13
	s_nop 0
	global_load_lds_dwordx4 v[180:181], off
	s_waitcnt vmcnt(8)
	s_waitcnt lgkmcnt(0)
	s_barrier
	s_setprio 3
	s_waitcnt lgkmcnt(0)
	v_mfma_scale_f32_16x16x128_f8f6f4 v[84:87], v[24:31], v[204:211], v[84:87], v196, v196 op_sel_hi:[0,0,0]
	v_mfma_scale_f32_16x16x128_f8f6f4 v[80:83], v[16:23], v[204:211], v[80:83], v196, v196 op_sel_hi:[0,0,0]
	v_mfma_scale_f32_16x16x128_f8f6f4 v[64:67], v[16:23], v[212:219], v[64:67], v196, v196 op_sel_hi:[0,0,0]
	v_mfma_scale_f32_16x16x128_f8f6f4 v[68:71], v[24:31], v[212:219], v[68:71], v196, v196 op_sel_hi:[0,0,0]
	v_mfma_scale_f32_16x16x128_f8f6f4 v[52:55], v[24:31], v[220:227], v[52:55], v196, v196 op_sel_hi:[0,0,0]
	v_mfma_scale_f32_16x16x128_f8f6f4 v[48:51], v[16:23], v[220:227], v[48:51], v196, v196 op_sel_hi:[0,0,0]
	v_mfma_scale_f32_16x16x128_f8f6f4 v[32:35], v[16:23], v[230:237], v[32:35], v196, v196 op_sel_hi:[0,0,0]
	v_mfma_scale_f32_16x16x128_f8f6f4 v[36:39], v[24:31], v[230:237], v[36:39], v196, v196 op_sel_hi:[0,0,0]
	s_setprio 0
	s_setprio 3
	v_mfma_scale_f32_16x16x128_f8f6f4 v[92:95], v[8:15], v[204:211], v[92:95], v196, v196 op_sel_hi:[0,0,0]
	v_mfma_scale_f32_16x16x128_f8f6f4 v[88:91], v[0:7], v[204:211], v[88:91], v196, v196 op_sel_hi:[0,0,0]
	v_mfma_scale_f32_16x16x128_f8f6f4 v[72:75], v[0:7], v[212:219], v[72:75], v196, v196 op_sel_hi:[0,0,0]
	v_mfma_scale_f32_16x16x128_f8f6f4 v[76:79], v[8:15], v[212:219], v[76:79], v196, v196 op_sel_hi:[0,0,0]
	v_mfma_scale_f32_16x16x128_f8f6f4 v[60:63], v[8:15], v[220:227], v[60:63], v196, v196 op_sel_hi:[0,0,0]
	v_mfma_scale_f32_16x16x128_f8f6f4 v[56:59], v[0:7], v[220:227], v[56:59], v196, v196 op_sel_hi:[0,0,0]
	v_mfma_scale_f32_16x16x128_f8f6f4 v[40:43], v[0:7], v[230:237], v[40:43], v196, v196 op_sel_hi:[0,0,0]
	v_mfma_scale_f32_16x16x128_f8f6f4 v[44:47], v[8:15], v[230:237], v[44:47], v196, v196 op_sel_hi:[0,0,0]
	s_setprio 0
	s_barrier
; #define PG8_STAGE(bufoff, gbase, voff) do { _Pragma("unroll") for (int _i = 0; _i < 2; ++_i) \
;         __builtin_amdgcn_global_load_lds((const unsigned*)((const char*)(gbase) + (voff)[_i]), (LAS unsigned*)(lds + (bufoff) + ldsw + _i * 8192), 16, 0, 0); } while (0)
; #define PG8_LDA(dst, b, h) do { _Pragma("unroll") for (int m = 0; m < 4; ++m) _Pragma("unroll") for (int k = 0; k < 2; ++k) dst[m][k] = *(const LAS bf16x8*)(lds + PG8_SA(b, h) + aoffk[k] + m * 2048); } while (0)
; template <class Epi, class Sched, class GemmT>
; __device__ __forceinline__ void gemm_phase(LAS unsigned char* lds, const GemmT& g, const Sched& S, const Epi& E, const int wid) {
;     ...
;             for (int t = 0; t < nt; t += 2) {
;                 const bool last = (t == nt - 2);
;                 const char* a1 = cA + (size_t)(t + 1) * kstep;
;                 const char* a2 = last ? ns.A : cA + (size_t)(t + 2) * kstep; const char* b2 = last ? ns.B : cB + (size_t)(t + 2) * kstep;
;                 const char* a3 = a2 + kstep; const char* b3 = b2 + kstep;
;                 unsigned vA2[2], vB2[2];
; #pragma unroll
;                 for (int i = 0; i < 2; ++i) { vA2[i] = last ? nvA[i] : voffA[i]; vB2[i] = last ? nvB[i] : voffB[i]; }
;                 const size_t hA2 = last ? nhA : hstepA, hB2 = last ? nhB : hstepB;
;                 PG8_LDB(B0, 0, 0); PG8_LDB(B1, 0, 1); PG8_SCHED; PG8_LDA(At, 0, 0); PG8_STAGE(PG8_SA(1, 1), a1 + hstepA, voffA);
;                 PG8_WAIT_V(8); PG8_WAIT_L(0); PG8_BAR; PG8_MMA(0, 0, At, B0); PG8_MMA(0, 1, At, B1); PG8_BAR; PG8_SCHED;
;                 PG8_LDA(At, 0, 1); PG8_STAGE(PG8_SB(0, 0), b2, vB2); PG8_STAGE(PG8_SB(0, 1), b2 + hB2, vB2); PG8_STAGE(PG8_SA(0, 0), a2, vA2);
;                 PG8_WAIT_V(8); PG8_WAIT_L(0); PG8_BAR; PG8_MMA(1, 0, At, B0); PG8_MMA(1, 1, At, B1); PG8_BAR; PG8_SCHED;
;                 PG8_LDB(B0, 1, 0); PG8_LDB(B1, 1, 1); PG8_SCHED; PG8_LDA(At, 1, 0); PG8_STAGE(PG8_SA(0, 1), a2 + hA2, vA2);
;                 PG8_WAIT_V(8); PG8_WAIT_L(0); PG8_BAR; PG8_MMA(0, 0, At, B0); PG8_MMA(0, 1, At, B1); PG8_BAR; PG8_SCHED;
;                 PG8_LDA(At, 1, 1); PG8_STAGE(PG8_SB(1, 0), b3, vB2); PG8_STAGE(PG8_SB(1, 1), b3 + hB2, vB2); PG8_STAGE(PG8_SA(1, 0), a3, vA2);
;                 PG8_WAIT_V(8); PG8_WAIT_L(0); PG8_BAR; PG8_MMA(1, 0, At, B0); PG8_MMA(1, 1, At, B1); PG8_BAR; PG8_SCHED;
;             }
	s_add_i32 s41, 0, 0x18000
	s_add_i32 s48, 0, 0x1c000
	v_add_u32_e32 v0, s41, v184
	v_add_u32_e32 v4, s41, v185
	v_add_u32_e32 v16, s48, v184
	v_add_u32_e32 v20, s48, v185
	ds_read_b128 v[0:3], v0
	ds_read_b128 v[4:7], v4
	ds_read_b128 v[8:11], v197
	ds_read_b128 v[12:15], v198
	ds_read_b128 v[16:19], v16
	ds_read_b128 v[20:23], v20
	ds_read_b128 v[24:27], v199
	ds_read_b128 v[28:31], v200
	s_add_u32 s50, s82, 0x80000
	s_addc_u32 s51, s83, 0
	s_mov_b32 m0, s15
	v_lshl_add_u64 v[238:239], s[50:51], 0, v[160:161]
	ds_read_b128 v[204:207], v194 offset:32768
	ds_read_b128 v[212:215], v194 offset:34816
	ds_read_b128 v[208:211], v195 offset:32768
	ds_read_b128 v[216:219], v195 offset:34816
	ds_read_b128 v[220:223], v194 offset:36864
	ds_read_b128 v[230:233], v194 offset:38912
	ds_read_b128 v[224:227], v195 offset:36864
	ds_read_b128 v[234:237], v195 offset:38912
	global_load_lds_dwordx4 v[238:239], off
	v_lshl_add_u64 v[238:239], s[50:51], 0, v[164:165]
	s_mov_b32 m0, s21
	s_nop 0
	global_load_lds_dwordx4 v[238:239], off
	s_waitcnt vmcnt(8)
	s_waitcnt lgkmcnt(0)
	s_barrier
	s_setprio 3
	s_waitcnt lgkmcnt(0)
	v_mfma_scale_f32_16x16x128_f8f6f4 v[156:159], v[0:7], v[204:211], v[156:159], v196, v196 op_sel_hi:[0,0,0]
	v_mfma_scale_f32_16x16x128_f8f6f4 v[152:155], v[8:15], v[204:211], v[152:155], v196, v196 op_sel_hi:[0,0,0]
	v_mfma_scale_f32_16x16x128_f8f6f4 v[136:139], v[8:15], v[212:219], v[136:139], v196, v196 op_sel_hi:[0,0,0]
	v_mfma_scale_f32_16x16x128_f8f6f4 v[140:143], v[0:7], v[212:219], v[140:143], v196, v196 op_sel_hi:[0,0,0]
	v_mfma_scale_f32_16x16x128_f8f6f4 v[124:127], v[0:7], v[220:227], v[124:127], v196, v196 op_sel_hi:[0,0,0]
	v_mfma_scale_f32_16x16x128_f8f6f4 v[120:123], v[8:15], v[220:227], v[120:123], v196, v196 op_sel_hi:[0,0,0]
	v_mfma_scale_f32_16x16x128_f8f6f4 v[104:107], v[8:15], v[230:237], v[104:107], v196, v196 op_sel_hi:[0,0,0]
	v_mfma_scale_f32_16x16x128_f8f6f4 v[108:111], v[0:7], v[230:237], v[108:111], v196, v196 op_sel_hi:[0,0,0]
	s_setprio 0
	s_setprio 3
	v_mfma_scale_f32_16x16x128_f8f6f4 v[148:151], v[16:23], v[204:211], v[148:151], v196, v196 op_sel_hi:[0,0,0]
	v_mfma_scale_f32_16x16x128_f8f6f4 v[144:147], v[24:31], v[204:211], v[144:147], v196, v196 op_sel_hi:[0,0,0]
	v_mfma_scale_f32_16x16x128_f8f6f4 v[128:131], v[24:31], v[212:219], v[128:131], v196, v196 op_sel_hi:[0,0,0]
	v_mfma_scale_f32_16x16x128_f8f6f4 v[132:135], v[16:23], v[212:219], v[132:135], v196, v196 op_sel_hi:[0,0,0]
	v_mfma_scale_f32_16x16x128_f8f6f4 v[116:119], v[16:23], v[220:227], v[116:119], v196, v196 op_sel_hi:[0,0,0]
	v_mfma_scale_f32_16x16x128_f8f6f4 v[112:115], v[24:31], v[220:227], v[112:115], v196, v196 op_sel_hi:[0,0,0]
	v_mfma_scale_f32_16x16x128_f8f6f4 v[96:99], v[24:31], v[230:237], v[96:99], v196, v196 op_sel_hi:[0,0,0]
	v_mfma_scale_f32_16x16x128_f8f6f4 v[100:103], v[16:23], v[230:237], v[100:103], v196, v196 op_sel_hi:[0,0,0]
	s_setprio 0
	s_barrier
	s_add_i32 s41, s41, s68
	v_lshl_add_u64 v[174:175], v[174:175], 0, s[10:11]
	s_mov_b32 m0, s41
	ds_read_b128 v[204:207], v194 offset:49152
	ds_read_b128 v[212:215], v194 offset:51200
	ds_read_b128 v[208:211], v195 offset:49152
	ds_read_b128 v[216:219], v195 offset:51200
	ds_read_b128 v[220:223], v194 offset:53248
	ds_read_b128 v[230:233], v194 offset:55296
	ds_read_b128 v[224:227], v195 offset:53248
	ds_read_b128 v[234:237], v195 offset:55296
	global_load_lds_dwordx4 v[174:175], off
	s_add_i32 m0, s41, 0x2000
	s_add_u32 s50, s58, 0x80080
	v_lshl_add_u64 v[174:175], v[176:177], 0, s[10:11]
	s_addc_u32 s51, s59, 0
	s_add_i32 s41, s48, s68
	global_load_lds_dwordx4 v[174:175], off
	v_lshl_add_u64 v[174:175], s[50:51], 0, v[162:163]
	s_mov_b32 m0, s41
	s_nop 0
	global_load_lds_dwordx4 v[174:175], off
	v_lshl_add_u64 v[174:175], s[50:51], 0, v[166:167]
	s_add_i32 m0, s41, 0x2000
	s_nop 0
	global_load_lds_dwordx4 v[174:175], off
	v_lshl_add_u64 v[174:175], v[178:179], 0, s[10:11]
	s_mov_b32 m0, s35
	s_nop 0
	global_load_lds_dwordx4 v[174:175], off
	v_lshl_add_u64 v[174:175], v[180:181], 0, s[10:11]
	s_mov_b32 m0, s53
	s_nop 0
	global_load_lds_dwordx4 v[174:175], off
	s_waitcnt vmcnt(8)
	s_waitcnt lgkmcnt(0)
	s_barrier
	s_setprio 3
	s_waitcnt lgkmcnt(0)
	v_mfma_scale_f32_16x16x128_f8f6f4 v[84:87], v[0:7], v[204:211], v[84:87], v196, v196 op_sel_hi:[0,0,0]
	v_mfma_scale_f32_16x16x128_f8f6f4 v[80:83], v[8:15], v[204:211], v[80:83], v196, v196 op_sel_hi:[0,0,0]
	v_mfma_scale_f32_16x16x128_f8f6f4 v[64:67], v[8:15], v[212:219], v[64:67], v196, v196 op_sel_hi:[0,0,0]
	v_mfma_scale_f32_16x16x128_f8f6f4 v[68:71], v[0:7], v[212:219], v[68:71], v196, v196 op_sel_hi:[0,0,0]
	v_mfma_scale_f32_16x16x128_f8f6f4 v[52:55], v[0:7], v[220:227], v[52:55], v196, v196 op_sel_hi:[0,0,0]
	v_mfma_scale_f32_16x16x128_f8f6f4 v[48:51], v[8:15], v[220:227], v[48:51], v196, v196 op_sel_hi:[0,0,0]
	v_mfma_scale_f32_16x16x128_f8f6f4 v[32:35], v[8:15], v[230:237], v[32:35], v196, v196 op_sel_hi:[0,0,0]
	v_mfma_scale_f32_16x16x128_f8f6f4 v[36:39], v[0:7], v[230:237], v[36:39], v196, v196 op_sel_hi:[0,0,0]
	s_setprio 0
	s_setprio 3
	v_mfma_scale_f32_16x16x128_f8f6f4 v[92:95], v[16:23], v[204:211], v[92:95], v196, v196 op_sel_hi:[0,0,0]
	v_mfma_scale_f32_16x16x128_f8f6f4 v[88:91], v[24:31], v[204:211], v[88:91], v196, v196 op_sel_hi:[0,0,0]
	v_mfma_scale_f32_16x16x128_f8f6f4 v[72:75], v[24:31], v[212:219], v[72:75], v196, v196 op_sel_hi:[0,0,0]
	v_mfma_scale_f32_16x16x128_f8f6f4 v[76:79], v[16:23], v[212:219], v[76:79], v196, v196 op_sel_hi:[0,0,0]
	v_mfma_scale_f32_16x16x128_f8f6f4 v[60:63], v[16:23], v[220:227], v[60:63], v196, v196 op_sel_hi:[0,0,0]
	v_mfma_scale_f32_16x16x128_f8f6f4 v[56:59], v[24:31], v[220:227], v[56:59], v196, v196 op_sel_hi:[0,0,0]
	v_mfma_scale_f32_16x16x128_f8f6f4 v[40:43], v[24:31], v[230:237], v[40:43], v196, v196 op_sel_hi:[0,0,0]
	v_mfma_scale_f32_16x16x128_f8f6f4 v[44:47], v[16:23], v[230:237], v[44:47], v196, v196 op_sel_hi:[0,0,0]
	s_setprio 0
	s_barrier
	s_add_i32 s40, s40, 2
	s_add_u32 s56, s56, 0x100
	s_addc_u32 s57, s57, 0
	s_add_u32 s38, s38, 0x100
	s_addc_u32 s39, s39, 0
	s_cmp_gt_u32 s40, 29
	s_cbranch_scc0 .LBB0_361
	s_and_b64 vcc, exec, s[16:17]
	s_cbranch_vccz .LBB0_364
	s_barrier

; #define PG8_STAGE(bufoff, gbase, voff) do { _Pragma("unroll") for (int _i = 0; _i < 2; ++_i) \
;         __builtin_amdgcn_global_load_lds((const unsigned*)((const char*)(gbase) + (voff)[_i]), (LAS unsigned*)(lds + (bufoff) + ldsw + _i * 8192), 16, 0, 0); } while (0)
; #define PG8_LDA(dst, b, h) do { _Pragma("unroll") for (int m = 0; m < 4; ++m) _Pragma("unroll") for (int k = 0; k < 2; ++k) dst[m][k] = *(const LAS bf16x8*)(lds + PG8_SA(b, h) + aoffk[k] + m * 2048); } while (0)
; template <class Epi, class Sched, class GemmT>
; __device__ __forceinline__ void gemm_phase(LAS unsigned char* lds, const GemmT& g, const Sched& S, const Epi& E, const int wid) {
;     ...
;             for (int t = 0; t < nt; t += 2) {
;                 const bool last = (t == nt - 2);
;                 const char* a1 = cA + (size_t)(t + 1) * kstep;
;                 const char* a2 = last ? ns.A : cA + (size_t)(t + 2) * kstep; const char* b2 = last ? ns.B : cB + (size_t)(t + 2) * kstep;
;                 const char* a3 = a2 + kstep; const char* b3 = b2 + kstep;
;                 unsigned vA2[2], vB2[2];
; #pragma unroll
;                 for (int i = 0; i < 2; ++i) { vA2[i] = last ? nvA[i] : voffA[i]; vB2[i] = last ? nvB[i] : voffB[i]; }
;                 const size_t hA2 = last ? nhA : hstepA, hB2 = last ? nhB : hstepB;
;                 PG8_LDB(B0, 0, 0); PG8_LDB(B1, 0, 1); PG8_SCHED; PG8_LDA(At, 0, 0); PG8_STAGE(PG8_SA(1, 1), a1 + hstepA, voffA);
;                 PG8_WAIT_V(8); PG8_WAIT_L(0); PG8_BAR; PG8_MMA(0, 0, At, B0); PG8_MMA(0, 1, At, B1); PG8_BAR; PG8_SCHED;
;                 PG8_LDA(At, 0, 1); PG8_STAGE(PG8_SB(0, 0), b2, vB2); PG8_STAGE(PG8_SB(0, 1), b2 + hB2, vB2); PG8_STAGE(PG8_SA(0, 0), a2, vA2);
;                 PG8_WAIT_V(8); PG8_WAIT_L(0); PG8_BAR; PG8_MMA(1, 0, At, B0); PG8_MMA(1, 1, At, B1); PG8_BAR; PG8_SCHED;
;                 PG8_LDB(B0, 1, 0); PG8_LDB(B1, 1, 1); PG8_SCHED; PG8_LDA(At, 1, 0); PG8_STAGE(PG8_SA(0, 1), a2 + hA2, vA2);
;                 PG8_WAIT_V(8); PG8_WAIT_L(0); PG8_BAR; PG8_MMA(0, 0, At, B0); PG8_MMA(0, 1, At, B1); PG8_BAR; PG8_SCHED;
;                 PG8_LDA(At, 1, 1); PG8_STAGE(PG8_SB(1, 0), b3, vB2); PG8_STAGE(PG8_SB(1, 1), b3 + hB2, vB2); PG8_STAGE(PG8_SA(1, 0), a3, vA2);
;                 PG8_WAIT_V(8); PG8_WAIT_L(0); PG8_BAR; PG8_MMA(1, 0, At, B0); PG8_MMA(1, 1, At, B1); PG8_BAR; PG8_SCHED;
;             }
.LBB0_417:
	ds_read_b128 v[140:143], v192
	ds_read_b128 v[144:147], v193
	ds_read_b128 v[148:151], v194
	ds_read_b128 v[152:155], v195
	ds_read_b128 v[156:159], v196
	ds_read_b128 v[160:163], v197
	ds_read_b128 v[164:167], v198
	ds_read_b128 v[168:171], v199
	s_add_u32 s39, s84, 0xfff00080
	s_addc_u32 s40, s85, -1
	s_cmp_eq_u32 s38, 60
	s_cselect_b32 s87, s57, s40
	s_cselect_b32 s86, s56, s39
	s_cselect_b32 s71, s16, s37
	s_cselect_b32 s70, s5, s36
	v_lshl_add_u64 v[176:177], s[84:85], 0, v[128:129]
	s_add_i32 m0, s9, 0xc000
	ds_read_b128 v[172:175], v200
	ds_read_b128 v[208:211], v200 offset:2048
	ds_read_b128 v[212:215], v201
	ds_read_b128 v[216:219], v201 offset:2048
	ds_read_b128 v[220:223], v200 offset:4096
	ds_read_b128 v[224:227], v200 offset:6144
	ds_read_b128 v[230:233], v201 offset:4096
	ds_read_b128 v[234:237], v201 offset:6144
	global_load_lds_dwordx4 v[176:177], off
	v_lshl_add_u64 v[176:177], s[84:85], 0, v[132:133]
	s_add_i32 m0, s9, 0xe000
	s_nop 0
	global_load_lds_dwordx4 v[176:177], off
	s_waitcnt vmcnt(8)
	s_waitcnt lgkmcnt(0)
	s_barrier
	s_setprio 3
	s_waitcnt lgkmcnt(0)
	v_mfma_f32_16x16x32_bf16 v[124:127], v[140:143], v[172:175], v[124:127]
	v_mfma_f32_16x16x32_bf16 v[124:127], v[144:147], v[212:215], v[124:127]
	v_mfma_f32_16x16x32_bf16 v[120:123], v[148:151], v[172:175], v[120:123]
	v_mfma_f32_16x16x32_bf16 v[120:123], v[152:155], v[212:215], v[120:123]
	v_mfma_f32_16x16x32_bf16 v[116:119], v[140:143], v[208:211], v[116:119]
	v_mfma_f32_16x16x32_bf16 v[116:119], v[144:147], v[216:219], v[116:119]
	v_mfma_f32_16x16x32_bf16 v[112:115], v[148:151], v[208:211], v[112:115]
	v_mfma_f32_16x16x32_bf16 v[112:115], v[152:155], v[216:219], v[112:115]
	v_mfma_f32_16x16x32_bf16 v[100:103], v[140:143], v[220:223], v[100:103]
	v_mfma_f32_16x16x32_bf16 v[100:103], v[144:147], v[230:233], v[100:103]
	v_mfma_f32_16x16x32_bf16 v[96:99], v[148:151], v[220:223], v[96:99]
	v_mfma_f32_16x16x32_bf16 v[96:99], v[152:155], v[230:233], v[96:99]
	v_mfma_f32_16x16x32_bf16 v[84:87], v[140:143], v[224:227], v[84:87]
	v_mfma_f32_16x16x32_bf16 v[84:87], v[144:147], v[234:237], v[84:87]
	v_mfma_f32_16x16x32_bf16 v[76:79], v[148:151], v[224:227], v[76:79]
	v_mfma_f32_16x16x32_bf16 v[76:79], v[152:155], v[234:237], v[76:79]
	s_setprio 0
	s_setprio 3
	v_mfma_f32_16x16x32_bf16 v[108:111], v[156:159], v[172:175], v[108:111]
	v_mfma_f32_16x16x32_bf16 v[108:111], v[160:163], v[212:215], v[108:111]
	v_mfma_f32_16x16x32_bf16 v[104:107], v[164:167], v[172:175], v[104:107]
	v_mfma_f32_16x16x32_bf16 v[104:107], v[168:171], v[212:215], v[104:107]
	v_mfma_f32_16x16x32_bf16 v[92:95], v[156:159], v[208:211], v[92:95]
	v_mfma_f32_16x16x32_bf16 v[92:95], v[160:163], v[216:219], v[92:95]
	v_mfma_f32_16x16x32_bf16 v[88:91], v[164:167], v[208:211], v[88:91]
	v_mfma_f32_16x16x32_bf16 v[88:91], v[168:171], v[216:219], v[88:91]
	v_mfma_f32_16x16x32_bf16 v[68:71], v[156:159], v[220:223], v[68:71]
	v_mfma_f32_16x16x32_bf16 v[68:71], v[160:163], v[230:233], v[68:71]
	v_mfma_f32_16x16x32_bf16 v[64:67], v[164:167], v[220:223], v[64:67]
	v_mfma_f32_16x16x32_bf16 v[64:67], v[168:171], v[230:233], v[64:67]
	v_mfma_f32_16x16x32_bf16 v[48:51], v[156:159], v[224:227], v[48:51]
	v_mfma_f32_16x16x32_bf16 v[48:51], v[160:163], v[234:237], v[48:51]
	v_mfma_f32_16x16x32_bf16 v[40:43], v[164:167], v[224:227], v[40:43]
	v_mfma_f32_16x16x32_bf16 v[40:43], v[168:171], v[234:237], v[40:43]
	s_setprio 0
	s_barrier
	s_add_i32 s39, s35, s68
	v_lshl_add_u64 v[176:177], s[70:71], 0, v[130:131]
	s_mov_b32 m0, s39
	ds_read_b128 v[172:175], v200 offset:16384
	ds_read_b128 v[208:211], v200 offset:18432
	ds_read_b128 v[212:215], v201 offset:16384
	ds_read_b128 v[216:219], v201 offset:18432
	ds_read_b128 v[220:223], v200 offset:20480
	ds_read_b128 v[224:227], v200 offset:22528
	ds_read_b128 v[230:233], v201 offset:20480
	ds_read_b128 v[234:237], v201 offset:22528
	global_load_lds_dwordx4 v[176:177], off
	s_add_i32 m0, s39, 0x2000
	s_add_u32 s40, s70, 0x100000
	v_lshl_add_u64 v[180:181], s[70:71], 0, v[134:135]
	s_addc_u32 s41, s71, 0
	s_add_i32 s39, s69, s68
	global_load_lds_dwordx4 v[180:181], off
	v_lshl_add_u64 v[184:185], s[40:41], 0, v[130:131]
	s_mov_b32 m0, s39
	v_lshl_add_u64 v[188:189], s[86:87], 0, v[132:133]
	global_load_lds_dwordx4 v[184:185], off
	v_lshl_add_u64 v[184:185], s[40:41], 0, v[134:135]
	s_add_i32 m0, s39, 0x2000
	s_nop 0
	global_load_lds_dwordx4 v[184:185], off
	v_lshl_add_u64 v[184:185], s[86:87], 0, v[128:129]
	s_mov_b32 m0, s9
	s_nop 0
	global_load_lds_dwordx4 v[184:185], off
	s_mov_b32 m0, s29
	s_nop 0
	global_load_lds_dwordx4 v[188:189], off
	s_waitcnt vmcnt(8)
	s_waitcnt lgkmcnt(0)
	s_barrier
; #define PG8_STAGE(bufoff, gbase, voff) do { _Pragma("unroll") for (int _i = 0; _i < 2; ++_i) \
;         __builtin_amdgcn_global_load_lds((const unsigned*)((const char*)(gbase) + (voff)[_i]), (LAS unsigned*)(lds + (bufoff) + ldsw + _i * 8192), 16, 0, 0); } while (0)
; #define PG8_LDA(dst, b, h) do { _Pragma("unroll") for (int m = 0; m < 4; ++m) _Pragma("unroll") for (int k = 0; k < 2; ++k) dst[m][k] = *(const LAS bf16x8*)(lds + PG8_SA(b, h) + aoffk[k] + m * 2048); } while (0)
; template <class Epi, class Sched, class GemmT>
; __device__ __forceinline__ void gemm_phase(LAS unsigned char* lds, const GemmT& g, const Sched& S, const Epi& E, const int wid) {
;     ...
;             for (int t = 0; t < nt; t += 2) {
;                 const bool last = (t == nt - 2);
;                 const char* a1 = cA + (size_t)(t + 1) * kstep;
;                 const char* a2 = last ? ns.A : cA + (size_t)(t + 2) * kstep; const char* b2 = last ? ns.B : cB + (size_t)(t + 2) * kstep;
;                 const char* a3 = a2 + kstep; const char* b3 = b2 + kstep;
;                 unsigned vA2[2], vB2[2];
; #pragma unroll
;                 for (int i = 0; i < 2; ++i) { vA2[i] = last ? nvA[i] : voffA[i]; vB2[i] = last ? nvB[i] : voffB[i]; }
;                 const size_t hA2 = last ? nhA : hstepA, hB2 = last ? nhB : hstepB;
;                 PG8_LDB(B0, 0, 0); PG8_LDB(B1, 0, 1); PG8_SCHED; PG8_LDA(At, 0, 0); PG8_STAGE(PG8_SA(1, 1), a1 + hstepA, voffA);
;                 PG8_WAIT_V(8); PG8_WAIT_L(0); PG8_BAR; PG8_MMA(0, 0, At, B0); PG8_MMA(0, 1, At, B1); PG8_BAR; PG8_SCHED;
;                 PG8_LDA(At, 0, 1); PG8_STAGE(PG8_SB(0, 0), b2, vB2); PG8_STAGE(PG8_SB(0, 1), b2 + hB2, vB2); PG8_STAGE(PG8_SA(0, 0), a2, vA2);
;                 PG8_WAIT_V(8); PG8_WAIT_L(0); PG8_BAR; PG8_MMA(1, 0, At, B0); PG8_MMA(1, 1, At, B1); PG8_BAR; PG8_SCHED;
;                 PG8_LDB(B0, 1, 0); PG8_LDB(B1, 1, 1); PG8_SCHED; PG8_LDA(At, 1, 0); PG8_STAGE(PG8_SA(0, 1), a2 + hA2, vA2);
;                 PG8_WAIT_V(8); PG8_WAIT_L(0); PG8_BAR; PG8_MMA(0, 0, At, B0); PG8_MMA(0, 1, At, B1); PG8_BAR; PG8_SCHED;
;                 PG8_LDA(At, 1, 1); PG8_STAGE(PG8_SB(1, 0), b3, vB2); PG8_STAGE(PG8_SB(1, 1), b3 + hB2, vB2); PG8_STAGE(PG8_SA(1, 0), a3, vA2);
;                 PG8_WAIT_V(8); PG8_WAIT_L(0); PG8_BAR; PG8_MMA(1, 0, At, B0); PG8_MMA(1, 1, At, B1); PG8_BAR; PG8_SCHED;
;             }
	s_setprio 3
	s_waitcnt lgkmcnt(0)
	v_mfma_f32_16x16x32_bf16 v[28:31], v[140:143], v[172:175], v[28:31]
	v_mfma_f32_16x16x32_bf16 v[28:31], v[144:147], v[212:215], v[28:31]
	v_mfma_f32_16x16x32_bf16 v[24:27], v[148:151], v[172:175], v[24:27]
	v_mfma_f32_16x16x32_bf16 v[24:27], v[152:155], v[212:215], v[24:27]
	v_mfma_f32_16x16x32_bf16 v[20:23], v[140:143], v[208:211], v[20:23]
	v_mfma_f32_16x16x32_bf16 v[20:23], v[144:147], v[216:219], v[20:23]
	v_mfma_f32_16x16x32_bf16 v[16:19], v[148:151], v[208:211], v[16:19]
	v_mfma_f32_16x16x32_bf16 v[16:19], v[152:155], v[216:219], v[16:19]
	v_mfma_f32_16x16x32_bf16 v[12:15], v[140:143], v[220:223], v[12:15]
	v_mfma_f32_16x16x32_bf16 v[12:15], v[144:147], v[230:233], v[12:15]
	v_mfma_f32_16x16x32_bf16 v[8:11], v[148:151], v[220:223], v[8:11]
	v_mfma_f32_16x16x32_bf16 v[8:11], v[152:155], v[230:233], v[8:11]
	v_mfma_f32_16x16x32_bf16 v[4:7], v[140:143], v[224:227], v[4:7]
	v_mfma_f32_16x16x32_bf16 v[4:7], v[144:147], v[234:237], v[4:7]
	v_mfma_f32_16x16x32_bf16 v[0:3], v[148:151], v[224:227], v[0:3]
	v_mfma_f32_16x16x32_bf16 v[0:3], v[152:155], v[234:237], v[0:3]
	s_setprio 0
	s_setprio 3
	v_mfma_f32_16x16x32_bf16 v[80:83], v[156:159], v[172:175], v[80:83]
	v_mfma_f32_16x16x32_bf16 v[80:83], v[160:163], v[212:215], v[80:83]
	v_mfma_f32_16x16x32_bf16 v[72:75], v[164:167], v[172:175], v[72:75]
	v_mfma_f32_16x16x32_bf16 v[72:75], v[168:171], v[212:215], v[72:75]
	v_mfma_f32_16x16x32_bf16 v[60:63], v[156:159], v[208:211], v[60:63]
	v_mfma_f32_16x16x32_bf16 v[60:63], v[160:163], v[216:219], v[60:63]
	v_mfma_f32_16x16x32_bf16 v[56:59], v[164:167], v[208:211], v[56:59]
	v_mfma_f32_16x16x32_bf16 v[56:59], v[168:171], v[216:219], v[56:59]
	v_mfma_f32_16x16x32_bf16 v[52:55], v[156:159], v[220:223], v[52:55]
	v_mfma_f32_16x16x32_bf16 v[52:55], v[160:163], v[230:233], v[52:55]
	v_mfma_f32_16x16x32_bf16 v[44:47], v[164:167], v[220:223], v[44:47]
	v_mfma_f32_16x16x32_bf16 v[44:47], v[168:171], v[230:233], v[44:47]
	v_mfma_f32_16x16x32_bf16 v[36:39], v[156:159], v[224:227], v[36:39]
	v_mfma_f32_16x16x32_bf16 v[36:39], v[160:163], v[234:237], v[36:39]
	v_mfma_f32_16x16x32_bf16 v[32:35], v[164:167], v[224:227], v[32:35]
	v_mfma_f32_16x16x32_bf16 v[32:35], v[168:171], v[234:237], v[32:35]
	s_setprio 0
	s_barrier
	s_add_i32 s39, 0, 0x18000
	s_add_i32 s48, 0, 0x1c000
	v_add_u32_e32 v140, s39, v187
	v_add_u32_e32 v144, s39, v190
	v_add_u32_e32 v156, s48, v187
	v_add_u32_e32 v160, s48, v190
	ds_read_b128 v[140:143], v140
	ds_read_b128 v[144:147], v144
	ds_read_b128 v[148:151], v202
	ds_read_b128 v[152:155], v203
	ds_read_b128 v[156:159], v156
	ds_read_b128 v[160:163], v160
	ds_read_b128 v[164:167], v204
	ds_read_b128 v[168:171], v205
	s_add_u32 s40, s86, 0x100000
	s_addc_u32 s41, s87, 0
	s_mov_b32 m0, s93
	v_lshl_add_u64 v[238:239], s[40:41], 0, v[128:129]
	ds_read_b128 v[172:175], v200 offset:32768
	ds_read_b128 v[208:211], v200 offset:34816
	ds_read_b128 v[212:215], v201 offset:32768
	ds_read_b128 v[216:219], v201 offset:34816
	ds_read_b128 v[220:223], v200 offset:36864
	ds_read_b128 v[224:227], v200 offset:38912
	ds_read_b128 v[230:233], v201 offset:36864
	ds_read_b128 v[234:237], v201 offset:38912
	global_load_lds_dwordx4 v[238:239], off
	v_lshl_add_u64 v[238:239], s[40:41], 0, v[132:133]
	s_mov_b32 m0, s6
	s_nop 0
	global_load_lds_dwordx4 v[238:239], off
	s_waitcnt vmcnt(8)
	s_waitcnt lgkmcnt(0)
	s_barrier
	s_setprio 3
	s_waitcnt lgkmcnt(0)
	v_mfma_f32_16x16x32_bf16 v[124:127], v[140:143], v[172:175], v[124:127]
	v_mfma_f32_16x16x32_bf16 v[124:127], v[144:147], v[212:215], v[124:127]
	v_mfma_f32_16x16x32_bf16 v[120:123], v[148:151], v[172:175], v[120:123]
	v_mfma_f32_16x16x32_bf16 v[120:123], v[152:155], v[212:215], v[120:123]
	v_mfma_f32_16x16x32_bf16 v[116:119], v[140:143], v[208:211], v[116:119]
	v_mfma_f32_16x16x32_bf16 v[116:119], v[144:147], v[216:219], v[116:119]
	v_mfma_f32_16x16x32_bf16 v[112:115], v[148:151], v[208:211], v[112:115]
	v_mfma_f32_16x16x32_bf16 v[112:115], v[152:155], v[216:219], v[112:115]
	v_mfma_f32_16x16x32_bf16 v[100:103], v[140:143], v[220:223], v[100:103]
	v_mfma_f32_16x16x32_bf16 v[100:103], v[144:147], v[230:233], v[100:103]
	v_mfma_f32_16x16x32_bf16 v[96:99], v[148:151], v[220:223], v[96:99]
	v_mfma_f32_16x16x32_bf16 v[96:99], v[152:155], v[230:233], v[96:99]
	v_mfma_f32_16x16x32_bf16 v[84:87], v[140:143], v[224:227], v[84:87]
	v_mfma_f32_16x16x32_bf16 v[84:87], v[144:147], v[234:237], v[84:87]
	v_mfma_f32_16x16x32_bf16 v[76:79], v[148:151], v[224:227], v[76:79]
	v_mfma_f32_16x16x32_bf16 v[76:79], v[152:155], v[234:237], v[76:79]
	s_setprio 0
	s_setprio 3
	v_mfma_f32_16x16x32_bf16 v[108:111], v[156:159], v[172:175], v[108:111]
	v_mfma_f32_16x16x32_bf16 v[108:111], v[160:163], v[212:215], v[108:111]
	v_mfma_f32_16x16x32_bf16 v[104:107], v[164:167], v[172:175], v[104:107]
	v_mfma_f32_16x16x32_bf16 v[104:107], v[168:171], v[212:215], v[104:107]
	v_mfma_f32_16x16x32_bf16 v[92:95], v[156:159], v[208:211], v[92:95]
	v_mfma_f32_16x16x32_bf16 v[92:95], v[160:163], v[216:219], v[92:95]
	v_mfma_f32_16x16x32_bf16 v[88:91], v[164:167], v[208:211], v[88:91]
	v_mfma_f32_16x16x32_bf16 v[88:91], v[168:171], v[216:219], v[88:91]
	v_mfma_f32_16x16x32_bf16 v[68:71], v[156:159], v[220:223], v[68:71]
	v_mfma_f32_16x16x32_bf16 v[68:71], v[160:163], v[230:233], v[68:71]
	v_mfma_f32_16x16x32_bf16 v[64:67], v[164:167], v[220:223], v[64:67]
	v_mfma_f32_16x16x32_bf16 v[64:67], v[168:171], v[230:233], v[64:67]
	v_mfma_f32_16x16x32_bf16 v[48:51], v[156:159], v[224:227], v[48:51]
	v_mfma_f32_16x16x32_bf16 v[48:51], v[160:163], v[234:237], v[48:51]
	v_mfma_f32_16x16x32_bf16 v[40:43], v[164:167], v[224:227], v[40:43]
	v_mfma_f32_16x16x32_bf16 v[40:43], v[168:171], v[234:237], v[40:43]
	s_setprio 0
	s_barrier
; #define PG8_STAGE(bufoff, gbase, voff) do { _Pragma("unroll") for (int _i = 0; _i < 2; ++_i) \
;         __builtin_amdgcn_global_load_lds((const unsigned*)((const char*)(gbase) + (voff)[_i]), (LAS unsigned*)(lds + (bufoff) + ldsw + _i * 8192), 16, 0, 0); } while (0)
; #define PG8_LDA(dst, b, h) do { _Pragma("unroll") for (int m = 0; m < 4; ++m) _Pragma("unroll") for (int k = 0; k < 2; ++k) dst[m][k] = *(const LAS bf16x8*)(lds + PG8_SA(b, h) + aoffk[k] + m * 2048); } while (0)
; template <class Epi, class Sched, class GemmT>
; __device__ __forceinline__ void gemm_phase(LAS unsigned char* lds, const GemmT& g, const Sched& S, const Epi& E, const int wid) {
;     ...
;             for (int t = 0; t < nt; t += 2) {
;                 const bool last = (t == nt - 2);
;                 const char* a1 = cA + (size_t)(t + 1) * kstep;
;                 const char* a2 = last ? ns.A : cA + (size_t)(t + 2) * kstep; const char* b2 = last ? ns.B : cB + (size_t)(t + 2) * kstep;
;                 const char* a3 = a2 + kstep; const char* b3 = b2 + kstep;
;                 unsigned vA2[2], vB2[2];
; #pragma unroll
;                 for (int i = 0; i < 2; ++i) { vA2[i] = last ? nvA[i] : voffA[i]; vB2[i] = last ? nvB[i] : voffB[i]; }
;                 const size_t hA2 = last ? nhA : hstepA, hB2 = last ? nhB : hstepB;
;                 PG8_LDB(B0, 0, 0); PG8_LDB(B1, 0, 1); PG8_SCHED; PG8_LDA(At, 0, 0); PG8_STAGE(PG8_SA(1, 1), a1 + hstepA, voffA);
;                 PG8_WAIT_V(8); PG8_WAIT_L(0); PG8_BAR; PG8_MMA(0, 0, At, B0); PG8_MMA(0, 1, At, B1); PG8_BAR; PG8_SCHED;
;                 PG8_LDA(At, 0, 1); PG8_STAGE(PG8_SB(0, 0), b2, vB2); PG8_STAGE(PG8_SB(0, 1), b2 + hB2, vB2); PG8_STAGE(PG8_SA(0, 0), a2, vA2);
;                 PG8_WAIT_V(8); PG8_WAIT_L(0); PG8_BAR; PG8_MMA(1, 0, At, B0); PG8_MMA(1, 1, At, B1); PG8_BAR; PG8_SCHED;
;                 PG8_LDB(B0, 1, 0); PG8_LDB(B1, 1, 1); PG8_SCHED; PG8_LDA(At, 1, 0); PG8_STAGE(PG8_SA(0, 1), a2 + hA2, vA2);
;                 PG8_WAIT_V(8); PG8_WAIT_L(0); PG8_BAR; PG8_MMA(0, 0, At, B0); PG8_MMA(0, 1, At, B1); PG8_BAR; PG8_SCHED;
;                 PG8_LDA(At, 1, 1); PG8_STAGE(PG8_SB(1, 0), b3, vB2); PG8_STAGE(PG8_SB(1, 1), b3 + hB2, vB2); PG8_STAGE(PG8_SA(1, 0), a3, vA2);
;                 PG8_WAIT_V(8); PG8_WAIT_L(0); PG8_BAR; PG8_MMA(1, 0, At, B0); PG8_MMA(1, 1, At, B1); PG8_BAR; PG8_SCHED;
;             }
	s_add_i32 s39, s39, s68
	v_lshl_add_u64 v[176:177], v[176:177], 0, s[66:67]
	s_mov_b32 m0, s39
	ds_read_b128 v[172:175], v200 offset:49152
	ds_read_b128 v[208:211], v200 offset:51200
	ds_read_b128 v[212:215], v201 offset:49152
	ds_read_b128 v[216:219], v201 offset:51200
	ds_read_b128 v[220:223], v200 offset:53248
	ds_read_b128 v[224:227], v200 offset:55296
	ds_read_b128 v[230:233], v201 offset:53248
	ds_read_b128 v[234:237], v201 offset:55296
	global_load_lds_dwordx4 v[176:177], off
	s_add_i32 m0, s39, 0x2000
	s_add_u32 s40, s70, 0x100080
	v_lshl_add_u64 v[176:177], v[180:181], 0, s[66:67]
	s_addc_u32 s41, s71, 0
	s_add_i32 s39, s48, s68
	global_load_lds_dwordx4 v[176:177], off
	v_lshl_add_u64 v[176:177], s[40:41], 0, v[130:131]
	s_mov_b32 m0, s39
	s_nop 0
	global_load_lds_dwordx4 v[176:177], off
	v_lshl_add_u64 v[176:177], s[40:41], 0, v[134:135]
	s_add_i32 m0, s39, 0x2000
	s_nop 0
	global_load_lds_dwordx4 v[176:177], off
	v_lshl_add_u64 v[176:177], v[184:185], 0, s[66:67]
	s_mov_b32 m0, s7
	s_nop 0
	global_load_lds_dwordx4 v[176:177], off
	v_lshl_add_u64 v[176:177], v[188:189], 0, s[66:67]
	s_mov_b32 m0, s12
	s_nop 0
	global_load_lds_dwordx4 v[176:177], off
	s_waitcnt vmcnt(8)
	s_waitcnt lgkmcnt(0)
	s_barrier
	s_setprio 3
	s_waitcnt lgkmcnt(0)
	v_mfma_f32_16x16x32_bf16 v[28:31], v[140:143], v[172:175], v[28:31]
	v_mfma_f32_16x16x32_bf16 v[28:31], v[144:147], v[212:215], v[28:31]
	v_mfma_f32_16x16x32_bf16 v[24:27], v[148:151], v[172:175], v[24:27]
	v_mfma_f32_16x16x32_bf16 v[24:27], v[152:155], v[212:215], v[24:27]
	v_mfma_f32_16x16x32_bf16 v[20:23], v[140:143], v[208:211], v[20:23]
	v_mfma_f32_16x16x32_bf16 v[20:23], v[144:147], v[216:219], v[20:23]
	v_mfma_f32_16x16x32_bf16 v[16:19], v[148:151], v[208:211], v[16:19]
	v_mfma_f32_16x16x32_bf16 v[16:19], v[152:155], v[216:219], v[16:19]
	v_mfma_f32_16x16x32_bf16 v[12:15], v[140:143], v[220:223], v[12:15]
	v_mfma_f32_16x16x32_bf16 v[12:15], v[144:147], v[230:233], v[12:15]
	v_mfma_f32_16x16x32_bf16 v[8:11], v[148:151], v[220:223], v[8:11]
	v_mfma_f32_16x16x32_bf16 v[8:11], v[152:155], v[230:233], v[8:11]
	v_mfma_f32_16x16x32_bf16 v[4:7], v[140:143], v[224:227], v[4:7]
	v_mfma_f32_16x16x32_bf16 v[4:7], v[144:147], v[234:237], v[4:7]
	v_mfma_f32_16x16x32_bf16 v[0:3], v[148:151], v[224:227], v[0:3]
	v_mfma_f32_16x16x32_bf16 v[0:3], v[152:155], v[234:237], v[0:3]
	s_setprio 0
	s_setprio 3
	v_mfma_f32_16x16x32_bf16 v[80:83], v[156:159], v[172:175], v[80:83]
	v_mfma_f32_16x16x32_bf16 v[80:83], v[160:163], v[212:215], v[80:83]
	v_mfma_f32_16x16x32_bf16 v[72:75], v[164:167], v[172:175], v[72:75]
	v_mfma_f32_16x16x32_bf16 v[72:75], v[168:171], v[212:215], v[72:75]
	v_mfma_f32_16x16x32_bf16 v[60:63], v[156:159], v[208:211], v[60:63]
	v_mfma_f32_16x16x32_bf16 v[60:63], v[160:163], v[216:219], v[60:63]
	v_mfma_f32_16x16x32_bf16 v[56:59], v[164:167], v[208:211], v[56:59]
	v_mfma_f32_16x16x32_bf16 v[56:59], v[168:171], v[216:219], v[56:59]
	v_mfma_f32_16x16x32_bf16 v[52:55], v[156:159], v[220:223], v[52:55]
	v_mfma_f32_16x16x32_bf16 v[52:55], v[160:163], v[230:233], v[52:55]
	v_mfma_f32_16x16x32_bf16 v[44:47], v[164:167], v[220:223], v[44:47]
	v_mfma_f32_16x16x32_bf16 v[44:47], v[168:171], v[230:233], v[44:47]
	v_mfma_f32_16x16x32_bf16 v[36:39], v[156:159], v[224:227], v[36:39]
	v_mfma_f32_16x16x32_bf16 v[36:39], v[160:163], v[234:237], v[36:39]
	v_mfma_f32_16x16x32_bf16 v[32:35], v[164:167], v[224:227], v[32:35]
	v_mfma_f32_16x16x32_bf16 v[32:35], v[168:171], v[234:237], v[32:35]
	s_setprio 0
	s_barrier
	s_add_i32 s38, s38, 2
	s_add_u32 s84, s84, 0x100
	s_addc_u32 s85, s85, 0
	s_add_u32 s36, s36, 0x100
	s_addc_u32 s37, s37, 0
	s_cmp_gt_u32 s38, 61
	s_cbranch_scc0 .LBB0_417
	s_and_b64 vcc, exec, s[20:21]
	s_cbranch_vccz .LBB0_420
	s_barrier

; #define PG8_STAGE(bufoff, gbase, voff) do { _Pragma("unroll") for (int _i = 0; _i < 2; ++_i) \
;         __builtin_amdgcn_global_load_lds((const unsigned*)((const char*)(gbase) + (voff)[_i]), (LAS unsigned*)(lds + (bufoff) + ldsw + _i * 8192), 16, 0, 0); } while (0)
; #define PG8_LDA(dst, b, h) do { _Pragma("unroll") for (int m = 0; m < 4; ++m) _Pragma("unroll") for (int k = 0; k < 2; ++k) dst[m][k] = *(const LAS bf16x8*)(lds + PG8_SA(b, h) + aoffk[k] + m * 2048); } while (0)
; template <class Epi, class Sched, class GemmT>
; __device__ __forceinline__ void gemm_phase(LAS unsigned char* lds, const GemmT& g, const Sched& S, const Epi& E, const int wid) {
;     ...
;             for (int t = 0; t < nt; t += 2) {
;                 const bool last = (t == nt - 2);
;                 const char* a1 = cA + (size_t)(t + 1) * kstep;
;                 const char* a2 = last ? ns.A : cA + (size_t)(t + 2) * kstep; const char* b2 = last ? ns.B : cB + (size_t)(t + 2) * kstep;
;                 const char* a3 = a2 + kstep; const char* b3 = b2 + kstep;
;                 unsigned vA2[2], vB2[2];
; #pragma unroll
;                 for (int i = 0; i < 2; ++i) { vA2[i] = last ? nvA[i] : voffA[i]; vB2[i] = last ? nvB[i] : voffB[i]; }
;                 const size_t hA2 = last ? nhA : hstepA, hB2 = last ? nhB : hstepB;
;                 PG8_LDB(B0, 0, 0); PG8_LDB(B1, 0, 1); PG8_SCHED; PG8_LDA(At, 0, 0); PG8_STAGE(PG8_SA(1, 1), a1 + hstepA, voffA);
;                 PG8_WAIT_V(8); PG8_WAIT_L(0); PG8_BAR; PG8_MMA(0, 0, At, B0); PG8_MMA(0, 1, At, B1); PG8_BAR; PG8_SCHED;
;                 PG8_LDA(At, 0, 1); PG8_STAGE(PG8_SB(0, 0), b2, vB2); PG8_STAGE(PG8_SB(0, 1), b2 + hB2, vB2); PG8_STAGE(PG8_SA(0, 0), a2, vA2);
;                 PG8_WAIT_V(8); PG8_WAIT_L(0); PG8_BAR; PG8_MMA(1, 0, At, B0); PG8_MMA(1, 1, At, B1); PG8_BAR; PG8_SCHED;
;                 PG8_LDB(B0, 1, 0); PG8_LDB(B1, 1, 1); PG8_SCHED; PG8_LDA(At, 1, 0); PG8_STAGE(PG8_SA(0, 1), a2 + hA2, vA2);
;                 PG8_WAIT_V(8); PG8_WAIT_L(0); PG8_BAR; PG8_MMA(0, 0, At, B0); PG8_MMA(0, 1, At, B1); PG8_BAR; PG8_SCHED;
;                 PG8_LDA(At, 1, 1); PG8_STAGE(PG8_SB(1, 0), b3, vB2); PG8_STAGE(PG8_SB(1, 1), b3 + hB2, vB2); PG8_STAGE(PG8_SA(1, 0), a3, vA2);
;                 PG8_WAIT_V(8); PG8_WAIT_L(0); PG8_BAR; PG8_MMA(1, 0, At, B0); PG8_MMA(1, 1, At, B1); PG8_BAR; PG8_SCHED;
;             }
.LBB0_764:
	s_cmp_eq_u32 s43, s56
	s_cselect_b64 vcc, -1, 0
	s_add_i32 s90, s90, 2
	v_add_u32_e32 v131, s62, v208
	s_add_u32 s48, s50, s56
	v_add_u32_e32 v133, s62, v209
	ds_read_b128 v[144:147], v131
	ds_read_b128 v[148:151], v133
	v_add_u32_e32 v131, s63, v208
	s_addc_u32 s49, s51, s57
	v_add_u32_e32 v133, s63, v209
	ds_read_b128 v[152:155], v131
	ds_read_b128 v[156:159], v133
	v_add_u32_e32 v131, s64, v208
	s_add_u32 s58, s48, 0x100
	v_add_u32_e32 v133, s64, v209
	ds_read_b128 v[160:163], v131
	ds_read_b128 v[164:167], v133
	v_add_u32_e32 v131, s65, v208
	s_addc_u32 s59, s49, 0
	v_add_u32_e32 v133, s65, v209
	ds_read_b128 v[168:171], v131
	ds_read_b128 v[172:175], v133
	s_and_b64 s[48:49], vcc, exec
	s_cselect_b32 s59, s19, s59
	s_cselect_b32 s58, s18, s58
	s_add_u32 s60, s85, s56
	s_addc_u32 s61, s89, s57
	s_and_b64 s[48:49], vcc, exec
	v_cndmask_b32_e32 v138, v132, v190, vcc
	v_cndmask_b32_e32 v0, v143, v214, vcc
	v_cndmask_b32_e32 v140, v130, v194, vcc
	v_cndmask_b32_e32 v188, v142, v192, vcc
	s_cselect_b32 s61, s13, s61
	s_cselect_b32 s60, s12, s60
	s_cselect_b32 s91, 0, s45
	s_cselect_b32 s92, s6, s44
	v_lshl_add_u64 v[202:203], v[134:135], 0, s[56:57]
	s_add_i32 m0, s14, 0xc000
	ds_read_b128 v[176:179], v212
	ds_read_b128 v[180:183], v212 offset:2048
	ds_read_b128 v[184:187], v213
	ds_read_b128 v[216:219], v213 offset:2048
	ds_read_b128 v[220:223], v212 offset:4096
	ds_read_b128 v[224:227], v212 offset:6144
	ds_read_b128 v[230:233], v213 offset:4096
	ds_read_b128 v[234:237], v213 offset:6144
	global_load_lds_dwordx4 v[202:203], off
	v_lshl_add_u64 v[202:203], v[136:137], 0, s[56:57]
	s_add_i32 m0, s14, 0xe000
	s_nop 0
	global_load_lds_dwordx4 v[202:203], off
	s_waitcnt vmcnt(8)
	s_waitcnt lgkmcnt(0)
	s_barrier
	s_setprio 3
	s_waitcnt lgkmcnt(0)
	v_mfma_f32_16x16x32_bf16 v[126:129], v[144:147], v[176:179], v[126:129]
	v_mfma_f32_16x16x32_bf16 v[126:129], v[148:151], v[184:187], v[126:129]
	v_mfma_f32_16x16x32_bf16 v[122:125], v[152:155], v[176:179], v[122:125]
	v_mfma_f32_16x16x32_bf16 v[122:125], v[156:159], v[184:187], v[122:125]
	v_mfma_f32_16x16x32_bf16 v[110:113], v[144:147], v[180:183], v[110:113]
	v_mfma_f32_16x16x32_bf16 v[110:113], v[148:151], v[216:219], v[110:113]
	v_mfma_f32_16x16x32_bf16 v[106:109], v[152:155], v[180:183], v[106:109]
	v_mfma_f32_16x16x32_bf16 v[106:109], v[156:159], v[216:219], v[106:109]
	v_mfma_f32_16x16x32_bf16 v[94:97], v[144:147], v[220:223], v[94:97]
	v_mfma_f32_16x16x32_bf16 v[94:97], v[148:151], v[230:233], v[94:97]
	v_mfma_f32_16x16x32_bf16 v[90:93], v[152:155], v[220:223], v[90:93]
	v_mfma_f32_16x16x32_bf16 v[90:93], v[156:159], v[230:233], v[90:93]
	v_mfma_f32_16x16x32_bf16 v[78:81], v[144:147], v[224:227], v[78:81]
	v_mfma_f32_16x16x32_bf16 v[78:81], v[148:151], v[234:237], v[78:81]
	v_mfma_f32_16x16x32_bf16 v[74:77], v[152:155], v[224:227], v[74:77]
	v_mfma_f32_16x16x32_bf16 v[74:77], v[156:159], v[234:237], v[74:77]
	s_setprio 0
	s_setprio 3
	v_mfma_f32_16x16x32_bf16 v[118:121], v[160:163], v[176:179], v[118:121]
	v_mfma_f32_16x16x32_bf16 v[118:121], v[164:167], v[184:187], v[118:121]
	v_mfma_f32_16x16x32_bf16 v[114:117], v[168:171], v[176:179], v[114:117]
	v_mfma_f32_16x16x32_bf16 v[114:117], v[172:175], v[184:187], v[114:117]
	v_mfma_f32_16x16x32_bf16 v[102:105], v[160:163], v[180:183], v[102:105]
	v_mfma_f32_16x16x32_bf16 v[102:105], v[164:167], v[216:219], v[102:105]
	v_mfma_f32_16x16x32_bf16 v[98:101], v[168:171], v[180:183], v[98:101]
	v_mfma_f32_16x16x32_bf16 v[98:101], v[172:175], v[216:219], v[98:101]
	v_mfma_f32_16x16x32_bf16 v[86:89], v[160:163], v[220:223], v[86:89]
	v_mfma_f32_16x16x32_bf16 v[86:89], v[164:167], v[230:233], v[86:89]
	v_mfma_f32_16x16x32_bf16 v[82:85], v[168:171], v[220:223], v[82:85]
	v_mfma_f32_16x16x32_bf16 v[82:85], v[172:175], v[230:233], v[82:85]
	v_mfma_f32_16x16x32_bf16 v[70:73], v[160:163], v[224:227], v[70:73]
	v_mfma_f32_16x16x32_bf16 v[70:73], v[164:167], v[234:237], v[70:73]
	v_mfma_f32_16x16x32_bf16 v[66:69], v[168:171], v[224:227], v[66:69]
	v_mfma_f32_16x16x32_bf16 v[66:69], v[172:175], v[234:237], v[66:69]
	s_setprio 0
	s_barrier
	s_add_i32 s48, s62, s68
	s_mov_b32 m0, s48
	ds_read_b128 v[176:179], v212 offset:16384
	ds_read_b128 v[180:183], v213 offset:16384
	ds_read_b128 v[184:187], v212 offset:18432
	ds_read_b128 v[216:219], v213 offset:18432
	ds_read_b128 v[220:223], v212 offset:20480
	ds_read_b128 v[224:227], v213 offset:20480
	ds_read_b128 v[230:233], v212 offset:22528
	ds_read_b128 v[234:237], v213 offset:22528
	global_load_lds_dwordx4 v0, s[60:61]
	s_add_i32 m0, s48, 0x2000
	v_mov_b32_e32 v189, v1
	s_add_u32 s48, s60, s92
	v_lshl_add_u64 v[202:203], s[60:61], 0, v[0:1]
	v_lshl_add_u64 v[238:239], s[60:61], 0, v[188:189]
	global_load_lds_dwordx4 v188, s[60:61]
	s_addc_u32 s49, s61, s91
	s_add_i32 s60, s64, s68
	s_mov_b32 m0, s60
	v_mov_b32_e32 v139, v1
	global_load_lds_dwordx4 v0, s[48:49]
	s_add_i32 m0, s60, 0x2000
	v_mov_b32_e32 v141, v1
	global_load_lds_dwordx4 v188, s[48:49]
	s_mov_b32 m0, s14
	v_lshl_add_u64 v[240:241], s[48:49], 0, v[0:1]
	global_load_lds_dwordx4 v138, s[58:59]
	s_mov_b32 m0, s15
	v_lshl_add_u64 v[242:243], s[48:49], 0, v[188:189]
	global_load_lds_dwordx4 v140, s[58:59]
	s_waitcnt vmcnt(8)
	s_waitcnt lgkmcnt(0)
	v_lshl_add_u64 v[188:189], s[58:59], 0, v[138:139]
	v_lshl_add_u64 v[244:245], s[58:59], 0, v[140:141]
	s_barrier
; #define PG8_STAGE(bufoff, gbase, voff) do { _Pragma("unroll") for (int _i = 0; _i < 2; ++_i) \
;         __builtin_amdgcn_global_load_lds((const unsigned*)((const char*)(gbase) + (voff)[_i]), (LAS unsigned*)(lds + (bufoff) + ldsw + _i * 8192), 16, 0, 0); } while (0)
; #define PG8_LDA(dst, b, h) do { _Pragma("unroll") for (int m = 0; m < 4; ++m) _Pragma("unroll") for (int k = 0; k < 2; ++k) dst[m][k] = *(const LAS bf16x8*)(lds + PG8_SA(b, h) + aoffk[k] + m * 2048); } while (0)
; template <class Epi, class Sched, class GemmT>
; __device__ __forceinline__ void gemm_phase(LAS unsigned char* lds, const GemmT& g, const Sched& S, const Epi& E, const int wid) {
;     ...
;             for (int t = 0; t < nt; t += 2) {
;                 const bool last = (t == nt - 2);
;                 const char* a1 = cA + (size_t)(t + 1) * kstep;
;                 const char* a2 = last ? ns.A : cA + (size_t)(t + 2) * kstep; const char* b2 = last ? ns.B : cB + (size_t)(t + 2) * kstep;
;                 const char* a3 = a2 + kstep; const char* b3 = b2 + kstep;
;                 unsigned vA2[2], vB2[2];
; #pragma unroll
;                 for (int i = 0; i < 2; ++i) { vA2[i] = last ? nvA[i] : voffA[i]; vB2[i] = last ? nvB[i] : voffB[i]; }
;                 const size_t hA2 = last ? nhA : hstepA, hB2 = last ? nhB : hstepB;
;                 PG8_LDB(B0, 0, 0); PG8_LDB(B1, 0, 1); PG8_SCHED; PG8_LDA(At, 0, 0); PG8_STAGE(PG8_SA(1, 1), a1 + hstepA, voffA);
;                 PG8_WAIT_V(8); PG8_WAIT_L(0); PG8_BAR; PG8_MMA(0, 0, At, B0); PG8_MMA(0, 1, At, B1); PG8_BAR; PG8_SCHED;
;                 PG8_LDA(At, 0, 1); PG8_STAGE(PG8_SB(0, 0), b2, vB2); PG8_STAGE(PG8_SB(0, 1), b2 + hB2, vB2); PG8_STAGE(PG8_SA(0, 0), a2, vA2);
;                 PG8_WAIT_V(8); PG8_WAIT_L(0); PG8_BAR; PG8_MMA(1, 0, At, B0); PG8_MMA(1, 1, At, B1); PG8_BAR; PG8_SCHED;
;                 PG8_LDB(B0, 1, 0); PG8_LDB(B1, 1, 1); PG8_SCHED; PG8_LDA(At, 1, 0); PG8_STAGE(PG8_SA(0, 1), a2 + hA2, vA2);
;                 PG8_WAIT_V(8); PG8_WAIT_L(0); PG8_BAR; PG8_MMA(0, 0, At, B0); PG8_MMA(0, 1, At, B1); PG8_BAR; PG8_SCHED;
;                 PG8_LDA(At, 1, 1); PG8_STAGE(PG8_SB(1, 0), b3, vB2); PG8_STAGE(PG8_SB(1, 1), b3 + hB2, vB2); PG8_STAGE(PG8_SA(1, 0), a3, vA2);
;                 PG8_WAIT_V(8); PG8_WAIT_L(0); PG8_BAR; PG8_MMA(1, 0, At, B0); PG8_MMA(1, 1, At, B1); PG8_BAR; PG8_SCHED;
;             }
	s_setprio 3
	s_waitcnt lgkmcnt(0)
	v_mfma_f32_16x16x32_bf16 v[62:65], v[144:147], v[176:179], v[62:65]
	v_mfma_f32_16x16x32_bf16 v[62:65], v[148:151], v[180:183], v[62:65]
	v_mfma_f32_16x16x32_bf16 v[58:61], v[152:155], v[176:179], v[58:61]
	v_mfma_f32_16x16x32_bf16 v[58:61], v[156:159], v[180:183], v[58:61]
	v_mfma_f32_16x16x32_bf16 v[46:49], v[144:147], v[184:187], v[46:49]
	v_mfma_f32_16x16x32_bf16 v[46:49], v[148:151], v[216:219], v[46:49]
	v_mfma_f32_16x16x32_bf16 v[42:45], v[152:155], v[184:187], v[42:45]
	v_mfma_f32_16x16x32_bf16 v[42:45], v[156:159], v[216:219], v[42:45]
	v_mfma_f32_16x16x32_bf16 v[30:33], v[144:147], v[220:223], v[30:33]
	v_mfma_f32_16x16x32_bf16 v[30:33], v[148:151], v[224:227], v[30:33]
	v_mfma_f32_16x16x32_bf16 v[22:25], v[152:155], v[220:223], v[22:25]
	v_mfma_f32_16x16x32_bf16 v[22:25], v[156:159], v[224:227], v[22:25]
	v_mfma_f32_16x16x32_bf16 v[14:17], v[144:147], v[230:233], v[14:17]
	v_mfma_f32_16x16x32_bf16 v[14:17], v[148:151], v[234:237], v[14:17]
	v_mfma_f32_16x16x32_bf16 v[6:9], v[152:155], v[230:233], v[6:9]
	v_mfma_f32_16x16x32_bf16 v[6:9], v[156:159], v[234:237], v[6:9]
	s_setprio 0
	s_setprio 3
	v_mfma_f32_16x16x32_bf16 v[54:57], v[160:163], v[176:179], v[54:57]
	v_mfma_f32_16x16x32_bf16 v[54:57], v[164:167], v[180:183], v[54:57]
	v_mfma_f32_16x16x32_bf16 v[50:53], v[168:171], v[176:179], v[50:53]
	v_mfma_f32_16x16x32_bf16 v[50:53], v[172:175], v[180:183], v[50:53]
	v_mfma_f32_16x16x32_bf16 v[38:41], v[160:163], v[184:187], v[38:41]
	v_mfma_f32_16x16x32_bf16 v[38:41], v[164:167], v[216:219], v[38:41]
	v_mfma_f32_16x16x32_bf16 v[34:37], v[168:171], v[184:187], v[34:37]
	v_mfma_f32_16x16x32_bf16 v[34:37], v[172:175], v[216:219], v[34:37]
	v_mfma_f32_16x16x32_bf16 v[26:29], v[160:163], v[220:223], v[26:29]
	v_mfma_f32_16x16x32_bf16 v[26:29], v[164:167], v[224:227], v[26:29]
	v_mfma_f32_16x16x32_bf16 v[18:21], v[168:171], v[220:223], v[18:21]
	v_mfma_f32_16x16x32_bf16 v[18:21], v[172:175], v[224:227], v[18:21]
	v_mfma_f32_16x16x32_bf16 v[10:13], v[160:163], v[230:233], v[10:13]
	v_mfma_f32_16x16x32_bf16 v[10:13], v[164:167], v[234:237], v[10:13]
	v_mfma_f32_16x16x32_bf16 v[2:5], v[168:171], v[230:233], v[2:5]
	v_mfma_f32_16x16x32_bf16 v[2:5], v[172:175], v[234:237], v[2:5]
	s_setprio 0
	s_barrier
	s_add_i32 s60, 0, 0x18000
	v_add_u32_e32 v0, s60, v208
	v_add_u32_e32 v131, s60, v209
	ds_read_b128 v[144:147], v0
	ds_read_b128 v[148:151], v131
	v_add_u32_e32 v0, s66, v208
	s_add_i32 s61, 0, 0x1c000
	v_add_u32_e32 v131, s66, v209
	ds_read_b128 v[152:155], v0
	ds_read_b128 v[156:159], v131
	v_add_u32_e32 v0, s61, v208
	v_add_u32_e32 v131, s61, v209
	ds_read_b128 v[160:163], v0
	ds_read_b128 v[164:167], v131
	v_add_u32_e32 v0, s67, v208
	v_add_u32_e32 v131, s67, v209
	ds_read_b128 v[168:171], v0
	ds_read_b128 v[172:175], v131
	s_add_u32 s48, s58, s92
	s_addc_u32 s49, s59, s91
	s_mov_b32 m0, s34
	ds_read_b128 v[176:179], v212 offset:32768
	ds_read_b128 v[180:183], v212 offset:34816
	ds_read_b128 v[184:187], v213 offset:32768
	ds_read_b128 v[216:219], v213 offset:34816
	ds_read_b128 v[220:223], v212 offset:36864
	ds_read_b128 v[224:227], v212 offset:38912
	ds_read_b128 v[230:233], v213 offset:36864
	ds_read_b128 v[234:237], v213 offset:38912
	global_load_lds_dwordx4 v138, s[48:49]
	s_mov_b32 m0, s35
	s_nop 0
	global_load_lds_dwordx4 v140, s[48:49]
	s_waitcnt vmcnt(8)
	s_waitcnt lgkmcnt(0)
	s_barrier
	s_setprio 3
	s_waitcnt lgkmcnt(0)
	v_mfma_f32_16x16x32_bf16 v[126:129], v[144:147], v[176:179], v[126:129]
	v_mfma_f32_16x16x32_bf16 v[126:129], v[148:151], v[184:187], v[126:129]
	v_mfma_f32_16x16x32_bf16 v[122:125], v[152:155], v[176:179], v[122:125]
	v_mfma_f32_16x16x32_bf16 v[122:125], v[156:159], v[184:187], v[122:125]
	v_mfma_f32_16x16x32_bf16 v[110:113], v[144:147], v[180:183], v[110:113]
	v_mfma_f32_16x16x32_bf16 v[110:113], v[148:151], v[216:219], v[110:113]
	v_mfma_f32_16x16x32_bf16 v[106:109], v[152:155], v[180:183], v[106:109]
	v_mfma_f32_16x16x32_bf16 v[106:109], v[156:159], v[216:219], v[106:109]
	v_mfma_f32_16x16x32_bf16 v[94:97], v[144:147], v[220:223], v[94:97]
	v_mfma_f32_16x16x32_bf16 v[94:97], v[148:151], v[230:233], v[94:97]
	v_mfma_f32_16x16x32_bf16 v[90:93], v[152:155], v[220:223], v[90:93]
	v_mfma_f32_16x16x32_bf16 v[90:93], v[156:159], v[230:233], v[90:93]
	v_mfma_f32_16x16x32_bf16 v[78:81], v[144:147], v[224:227], v[78:81]
	v_mfma_f32_16x16x32_bf16 v[78:81], v[148:151], v[234:237], v[78:81]
	v_mfma_f32_16x16x32_bf16 v[74:77], v[152:155], v[224:227], v[74:77]
	v_mfma_f32_16x16x32_bf16 v[74:77], v[156:159], v[234:237], v[74:77]
	s_setprio 0
	s_setprio 3
	v_mfma_f32_16x16x32_bf16 v[118:121], v[160:163], v[176:179], v[118:121]
	v_mfma_f32_16x16x32_bf16 v[118:121], v[164:167], v[184:187], v[118:121]
	v_mfma_f32_16x16x32_bf16 v[114:117], v[168:171], v[176:179], v[114:117]
	v_mfma_f32_16x16x32_bf16 v[114:117], v[172:175], v[184:187], v[114:117]
	v_mfma_f32_16x16x32_bf16 v[102:105], v[160:163], v[180:183], v[102:105]
	v_mfma_f32_16x16x32_bf16 v[102:105], v[164:167], v[216:219], v[102:105]
	v_mfma_f32_16x16x32_bf16 v[98:101], v[168:171], v[180:183], v[98:101]
	v_mfma_f32_16x16x32_bf16 v[98:101], v[172:175], v[216:219], v[98:101]
	v_mfma_f32_16x16x32_bf16 v[86:89], v[160:163], v[220:223], v[86:89]
	v_mfma_f32_16x16x32_bf16 v[86:89], v[164:167], v[230:233], v[86:89]
	v_mfma_f32_16x16x32_bf16 v[82:85], v[168:171], v[220:223], v[82:85]
	v_mfma_f32_16x16x32_bf16 v[82:85], v[172:175], v[230:233], v[82:85]
	v_mfma_f32_16x16x32_bf16 v[70:73], v[160:163], v[224:227], v[70:73]
	v_mfma_f32_16x16x32_bf16 v[70:73], v[164:167], v[234:237], v[70:73]
	v_mfma_f32_16x16x32_bf16 v[66:69], v[168:171], v[224:227], v[66:69]
	v_mfma_f32_16x16x32_bf16 v[66:69], v[172:175], v[234:237], v[66:69]
	s_setprio 0
	s_barrier
; #define PG8_WAIT_V(n) asm volatile("s_waitcnt vmcnt(" #n ")" ::: "memory")
; #define PG8_WAIT_L(n) asm volatile("s_waitcnt lgkmcnt(" #n ")" ::: "memory")
;     __device__ __forceinline__ void mid(Acc& acc, const Unit& u, int s, int wr, int wc, int fr, int fq) const {
;         int lo = (wr * 4 + wc) * 8192 + (fq * 16 + fr) * 16; asm volatile("" : "+v"(lo));
;         const unsigned char* gp = gate + ((size_t)(u.pm * 48 + s * 16 + u.pn) << 16) + lo;
;         u32x4 G[8][2];
; #pragma unroll
; template <class Epi, class Sched, class GemmT>
; __device__ __forceinline__ void gemm_phase(LAS unsigned char* lds, const GemmT& g, const Sched& S, const Epi& E, const int wid) {
;     ...
;             for (int t = 0; t < nt; t += 2) {
;                 const bool last = (t == nt - 2);
;                 const char* a1 = cA + (size_t)(t + 1) * kstep;
;                 const char* a2 = last ? ns.A : cA + (size_t)(t + 2) * kstep; const char* b2 = last ? ns.B : cB + (size_t)(t + 2) * kstep;
;                 const char* a3 = a2 + kstep; const char* b3 = b2 + kstep;
;                 unsigned vA2[2], vB2[2];
; #pragma unroll
;                 for (int i = 0; i < 2; ++i) { vA2[i] = last ? nvA[i] : voffA[i]; vB2[i] = last ? nvB[i] : voffB[i]; }
;                 const size_t hA2 = last ? nhA : hstepA, hB2 = last ? nhB : hstepB;
;                 PG8_LDB(B0, 0, 0); PG8_LDB(B1, 0, 1); PG8_SCHED; PG8_LDA(At, 0, 0); PG8_STAGE(PG8_SA(1, 1), a1 + hstepA, voffA);
;                 PG8_WAIT_V(8); PG8_WAIT_L(0); PG8_BAR; PG8_MMA(0, 0, At, B0); PG8_MMA(0, 1, At, B1); PG8_BAR; PG8_SCHED;
;                 PG8_LDA(At, 0, 1); PG8_STAGE(PG8_SB(0, 0), b2, vB2); PG8_STAGE(PG8_SB(0, 1), b2 + hB2, vB2); PG8_STAGE(PG8_SA(0, 0), a2, vA2);
;                 PG8_WAIT_V(8); PG8_WAIT_L(0); PG8_BAR; PG8_MMA(1, 0, At, B0); PG8_MMA(1, 1, At, B1); PG8_BAR; PG8_SCHED;
;                 PG8_LDB(B0, 1, 0); PG8_LDB(B1, 1, 1); PG8_SCHED; PG8_LDA(At, 1, 0); PG8_STAGE(PG8_SA(0, 1), a2 + hA2, vA2);
;                 PG8_WAIT_V(8); PG8_WAIT_L(0); PG8_BAR; PG8_MMA(0, 0, At, B0); PG8_MMA(0, 1, At, B1); PG8_BAR; PG8_SCHED;
;                 PG8_LDA(At, 1, 1); PG8_STAGE(PG8_SB(1, 0), b3, vB2); PG8_STAGE(PG8_SB(1, 1), b3 + hB2, vB2); PG8_STAGE(PG8_SA(1, 0), a3, vA2);
;                 PG8_WAIT_V(8); PG8_WAIT_L(0); PG8_BAR; PG8_MMA(1, 0, At, B0); PG8_MMA(1, 1, At, B1); PG8_BAR; PG8_SCHED;
;             }
	s_add_i32 s48, s60, s68
	v_lshl_add_u64 v[202:203], v[202:203], 0, s[20:21]
	s_mov_b32 m0, s48
	ds_read_b128 v[138:141], v212 offset:49152
	ds_read_b128 v[176:179], v212 offset:51200
	ds_read_b128 v[180:183], v213 offset:49152
	ds_read_b128 v[184:187], v213 offset:51200
	ds_read_b128 v[216:219], v212 offset:53248
	ds_read_b128 v[220:223], v212 offset:55296
	ds_read_b128 v[224:227], v213 offset:53248
	ds_read_b128 v[230:233], v213 offset:55296
	global_load_lds_dwordx4 v[202:203], off
	v_lshl_add_u64 v[202:203], v[238:239], 0, s[20:21]
	s_add_i32 m0, s48, 0x2000
	s_add_i32 s48, s61, s68
	global_load_lds_dwordx4 v[202:203], off
	v_lshl_add_u64 v[202:203], v[240:241], 0, s[20:21]
	s_mov_b32 m0, s48
	v_lshl_add_u64 v[188:189], v[188:189], 0, s[20:21]
	global_load_lds_dwordx4 v[202:203], off
	v_lshl_add_u64 v[202:203], v[242:243], 0, s[20:21]
	s_add_i32 m0, s48, 0x2000
	s_nop 0
	global_load_lds_dwordx4 v[202:203], off
	s_mov_b32 m0, s54
	s_nop 0
	global_load_lds_dwordx4 v[188:189], off
	v_lshl_add_u64 v[188:189], v[244:245], 0, s[20:21]
	s_mov_b32 m0, s55
	s_nop 0
	global_load_lds_dwordx4 v[188:189], off
	s_waitcnt vmcnt(8)
	s_waitcnt lgkmcnt(0)
	s_barrier
	s_setprio 3
	s_waitcnt lgkmcnt(0)
	v_mfma_f32_16x16x32_bf16 v[62:65], v[144:147], v[138:141], v[62:65]
	v_mfma_f32_16x16x32_bf16 v[62:65], v[148:151], v[180:183], v[62:65]
	v_mfma_f32_16x16x32_bf16 v[58:61], v[152:155], v[138:141], v[58:61]
	v_mfma_f32_16x16x32_bf16 v[58:61], v[156:159], v[180:183], v[58:61]
	v_mfma_f32_16x16x32_bf16 v[46:49], v[144:147], v[176:179], v[46:49]
	v_mfma_f32_16x16x32_bf16 v[46:49], v[148:151], v[184:187], v[46:49]
	v_mfma_f32_16x16x32_bf16 v[42:45], v[152:155], v[176:179], v[42:45]
	v_mfma_f32_16x16x32_bf16 v[42:45], v[156:159], v[184:187], v[42:45]
	v_mfma_f32_16x16x32_bf16 v[30:33], v[144:147], v[216:219], v[30:33]
	v_mfma_f32_16x16x32_bf16 v[30:33], v[148:151], v[224:227], v[30:33]
	v_mfma_f32_16x16x32_bf16 v[22:25], v[152:155], v[216:219], v[22:25]
	v_mfma_f32_16x16x32_bf16 v[22:25], v[156:159], v[224:227], v[22:25]
	v_mfma_f32_16x16x32_bf16 v[14:17], v[144:147], v[220:223], v[14:17]
	v_mfma_f32_16x16x32_bf16 v[14:17], v[148:151], v[230:233], v[14:17]
	v_mfma_f32_16x16x32_bf16 v[6:9], v[152:155], v[220:223], v[6:9]
	v_mfma_f32_16x16x32_bf16 v[6:9], v[156:159], v[230:233], v[6:9]
	s_setprio 0
	s_setprio 3
	v_mfma_f32_16x16x32_bf16 v[54:57], v[160:163], v[138:141], v[54:57]
	v_mfma_f32_16x16x32_bf16 v[54:57], v[164:167], v[180:183], v[54:57]
	v_mfma_f32_16x16x32_bf16 v[50:53], v[168:171], v[138:141], v[50:53]
	v_mfma_f32_16x16x32_bf16 v[50:53], v[172:175], v[180:183], v[50:53]
	v_mfma_f32_16x16x32_bf16 v[38:41], v[160:163], v[176:179], v[38:41]
	v_mfma_f32_16x16x32_bf16 v[38:41], v[164:167], v[184:187], v[38:41]
	v_mfma_f32_16x16x32_bf16 v[34:37], v[168:171], v[176:179], v[34:37]
	v_mfma_f32_16x16x32_bf16 v[34:37], v[172:175], v[184:187], v[34:37]
	v_mfma_f32_16x16x32_bf16 v[26:29], v[160:163], v[216:219], v[26:29]
	v_mfma_f32_16x16x32_bf16 v[26:29], v[164:167], v[224:227], v[26:29]
	v_mfma_f32_16x16x32_bf16 v[18:21], v[168:171], v[216:219], v[18:21]
	v_mfma_f32_16x16x32_bf16 v[18:21], v[172:175], v[224:227], v[18:21]
	v_mfma_f32_16x16x32_bf16 v[10:13], v[160:163], v[220:223], v[10:13]
	v_mfma_f32_16x16x32_bf16 v[10:13], v[164:167], v[230:233], v[10:13]
	v_mfma_f32_16x16x32_bf16 v[2:5], v[168:171], v[220:223], v[2:5]
	v_mfma_f32_16x16x32_bf16 v[2:5], v[172:175], v[230:233], v[2:5]
	s_setprio 0
	s_barrier
	s_add_u32 s56, s56, 0x100
	s_addc_u32 s57, s57, 0
	s_cmp_ge_u32 s90, s42
	s_cbranch_scc0 .LBB0_764
	s_and_b64 vcc, exec, s[52:53]
	s_cbranch_vccz .LBB0_767
	s_lshl_b32 s42, s83, 4
	s_add_i32 s42, s82, s42
	s_ashr_i32 s43, s42, 31
	s_lshl_b64 s[42:43], s[42:43], 16
	v_mov_b32_e32 v130, v210
	s_add_u32 s42, s22, s42
	s_addc_u32 s43, s23, s43
	v_ashrrev_i32_e32 v131, 31, v130
	v_lshl_add_u64 v[130:131], s[42:43], 0, v[130:131]
	v_add_co_u32_e32 v132, vcc, s69, v130
	s_mov_b32 s42, 0x101000
	s_nop 0
	v_addc_co_u32_e32 v133, vcc, 0, v131, vcc
	global_load_dwordx4 v[186:189], v[130:131], off nt
	v_add_co_u32_e32 v134, vcc, s42, v130
	s_movk_i32 s42, 0x1000
	s_nop 0
	v_addc_co_u32_e32 v135, vcc, 0, v131, vcc
	global_load_dwordx4 v[216:219], v[134:135], off offset:-4096 nt
	global_load_dwordx4 v[178:181], v[130:131], off offset:1024 nt
	global_load_dwordx4 v[182:185], v[132:133], off offset:1024 nt
	global_load_dwordx4 v[170:173], v[130:131], off offset:2048 nt
	global_load_dwordx4 v[174:177], v[132:133], off offset:2048 nt
	global_load_dwordx4 v[162:165], v[130:131], off offset:3072 nt
	global_load_dwordx4 v[166:169], v[132:133], off offset:3072 nt
	v_add_co_u32_e32 v130, vcc, s42, v130
	s_waitcnt vmcnt(0)
;     __device__ __forceinline__ void mid(Acc& acc, const Unit& u, int s, int wr, int wc, int fr, int fq) const {
;     ...
;         for (int i = 0; i < 8; ++i) { const int ai = i >> 2, m = i & 3;
; #pragma unroll
;             for (int bj = 0; bj < 2; ++bj) {
;                 const u32x4 ga = G[i][0], gb = G[i][1];
;                 const u32x2 wa = bj == 0 ? (u32x2){ga.x, ga.y} : (u32x2){ga.z, ga.w}, wb = bj == 0 ? (u32x2){gb.x, gb.y} : (u32x2){gb.z, gb.w};
;                 float fa[8], fb[8]; gate_unpack8(wa, fa); gate_unpack8(wb, fb);
; #pragma unroll
;                 for (int e = 0; e < 8; ++e) fa[e] = fa[e] * __builtin_amdgcn_rcpf(fb[e]);
;                 f32x4& v0 = acc[ai][bj][m][0]; f32x4& v1 = acc[ai][bj][m][1];
;                 v0[0] *= fa[0]; v0[1] *= fa[1]; v0[2] *= fa[2]; v0[3] *= fa[3]; v1[0] *= fa[4]; v1[1] *= fa[5]; v1[2] *= fa[6]; v1[3] *= fa[7]; }
	v_cvt_f32_ubyte0_e32 v0, v216
	v_addc_co_u32_e32 v131, vcc, 0, v131, vcc
	global_load_dwordx4 v[154:157], v[130:131], off nt
	global_load_dwordx4 v[158:161], v[134:135], off nt
	global_load_dwordx4 v[146:149], v[130:131], off offset:1024 nt
	global_load_dwordx4 v[150:153], v[134:135], off offset:1024 nt
	global_load_dwordx4 v[138:141], v[130:131], off offset:2048 nt
	global_load_dwordx4 v[142:145], v[134:135], off offset:2048 nt
	s_nop 0
	global_load_dwordx4 v[130:133], v[130:131], off offset:3072 nt
	s_nop 0
	global_load_dwordx4 v[134:137], v[134:135], off offset:3072 nt
	v_cvt_f32_ubyte1_e32 v203, v216
	v_cvt_f32_ubyte2_e32 v215, v216
	v_cvt_f32_ubyte3_e32 v220, v216
	v_cvt_f32_ubyte0_e32 v221, v217
	v_cvt_f32_ubyte1_e32 v222, v217
	v_cvt_f32_ubyte2_e32 v223, v217
	v_cvt_f32_ubyte3_e32 v224, v217
	v_rcp_iflag_f32_e32 v202, v0
	v_rcp_iflag_f32_e32 v203, v203
	v_rcp_iflag_f32_e32 v216, v215
	v_rcp_iflag_f32_e32 v217, v220
	v_rcp_iflag_f32_e32 v220, v221
	v_rcp_iflag_f32_e32 v221, v222
	v_rcp_iflag_f32_e32 v222, v223
	v_rcp_iflag_f32_e32 v223, v224
	v_cvt_f32_ubyte3_e32 v225, v186
	v_cvt_f32_ubyte2_e32 v224, v186
	v_cvt_f32_ubyte1_e32 v227, v186
	v_cvt_f32_ubyte0_e32 v226, v186
	v_pk_mul_f32 v[202:203], v[202:203], v[226:227]
	v_pk_mul_f32 v[216:217], v[216:217], v[224:225]
	v_pk_mul_f32 v[126:127], v[126:127], v[202:203]
	v_pk_mul_f32 v[128:129], v[128:129], v[216:217]
	v_cvt_f32_ubyte3_e32 v203, v187
	v_cvt_f32_ubyte2_e32 v202, v187
	v_cvt_f32_ubyte1_e32 v217, v187
	v_cvt_f32_ubyte0_e32 v216, v187
	v_pk_mul_f32 v[186:187], v[220:221], v[216:217]
	v_pk_mul_f32 v[202:203], v[222:223], v[202:203]
	v_pk_mul_f32 v[122:123], v[122:123], v[186:187]
	v_pk_mul_f32 v[124:125], v[124:125], v[202:203]
	v_cvt_f32_ubyte0_e32 v0, v218
	v_cvt_f32_ubyte1_e32 v186, v218
	v_cvt_f32_ubyte2_e32 v187, v218
	v_cvt_f32_ubyte3_e32 v202, v218
	v_cvt_f32_ubyte0_e32 v203, v219
	v_cvt_f32_ubyte1_e32 v215, v219
	v_cvt_f32_ubyte2_e32 v220, v219
	v_cvt_f32_ubyte3_e32 v221, v219
	v_rcp_iflag_f32_e32 v216, v0
	v_rcp_iflag_f32_e32 v217, v186
	v_rcp_iflag_f32_e32 v218, v187
	v_rcp_iflag_f32_e32 v219, v202
	v_rcp_iflag_f32_e32 v202, v203
	v_rcp_iflag_f32_e32 v203, v215
	v_rcp_iflag_f32_e32 v186, v220
	v_rcp_iflag_f32_e32 v187, v221
	v_cvt_f32_ubyte3_e32 v221, v188
	v_cvt_f32_ubyte2_e32 v220, v188
	v_cvt_f32_ubyte1_e32 v223, v188
	v_cvt_f32_ubyte0_e32 v222, v188
	v_pk_mul_f32 v[216:217], v[216:217], v[222:223]
	v_pk_mul_f32 v[218:219], v[218:219], v[220:221]
	v_pk_mul_f32 v[118:119], v[118:119], v[216:217]
	v_pk_mul_f32 v[120:121], v[120:121], v[218:219]
	v_cvt_f32_ubyte3_e32 v217, v189
	v_cvt_f32_ubyte2_e32 v216, v189
	v_cvt_f32_ubyte1_e32 v219, v189
	v_cvt_f32_ubyte0_e32 v218, v189
	v_pk_mul_f32 v[188:189], v[202:203], v[218:219]
	v_pk_mul_f32 v[186:187], v[186:187], v[216:217]
	v_pk_mul_f32 v[114:115], v[114:115], v[188:189]
	v_pk_mul_f32 v[116:117], v[116:117], v[186:187]
	v_cvt_f32_ubyte0_e32 v0, v182
	v_cvt_f32_ubyte1_e32 v186, v182
	v_cvt_f32_ubyte2_e32 v187, v182
	v_cvt_f32_ubyte3_e32 v188, v182
	v_cvt_f32_ubyte0_e32 v189, v183
	v_cvt_f32_ubyte1_e32 v202, v183
	v_cvt_f32_ubyte2_e32 v203, v183
	v_cvt_f32_ubyte3_e32 v215, v183
	v_rcp_iflag_f32_e32 v182, v0
	v_rcp_iflag_f32_e32 v183, v186
	v_rcp_iflag_f32_e32 v186, v187
	v_rcp_iflag_f32_e32 v187, v188
	v_rcp_iflag_f32_e32 v188, v189
	v_rcp_iflag_f32_e32 v189, v202
	v_rcp_iflag_f32_e32 v202, v203
	v_rcp_iflag_f32_e32 v203, v215
	v_cvt_f32_ubyte3_e32 v217, v178
	v_cvt_f32_ubyte2_e32 v216, v178
	v_cvt_f32_ubyte1_e32 v219, v178
	v_cvt_f32_ubyte0_e32 v218, v178
	v_pk_mul_f32 v[182:183], v[182:183], v[218:219]
	v_pk_mul_f32 v[186:187], v[186:187], v[216:217]
	v_pk_mul_f32 v[110:111], v[110:111], v[182:183]
	v_pk_mul_f32 v[112:113], v[112:113], v[186:187]
	v_cvt_f32_ubyte3_e32 v183, v179
	v_cvt_f32_ubyte2_e32 v182, v179
	v_cvt_f32_ubyte1_e32 v187, v179
	v_cvt_f32_ubyte0_e32 v186, v179
	v_pk_mul_f32 v[178:179], v[188:189], v[186:187]
	v_pk_mul_f32 v[182:183], v[202:203], v[182:183]
	v_pk_mul_f32 v[106:107], v[106:107], v[178:179]
	v_pk_mul_f32 v[108:109], v[108:109], v[182:183]
	v_cvt_f32_ubyte0_e32 v0, v184
	v_cvt_f32_ubyte1_e32 v179, v184
	v_cvt_f32_ubyte2_e32 v182, v184
	v_cvt_f32_ubyte3_e32 v183, v184
	v_rcp_iflag_f32_e32 v178, v0
	v_rcp_iflag_f32_e32 v179, v179
	v_rcp_iflag_f32_e32 v182, v182
	v_rcp_iflag_f32_e32 v183, v183
	v_cvt_f32_ubyte0_e32 v184, v185
	v_cvt_f32_ubyte1_e32 v186, v185
	v_cvt_f32_ubyte2_e32 v187, v185
	v_cvt_f32_ubyte3_e32 v188, v185
	v_rcp_iflag_f32_e32 v184, v184
	v_rcp_iflag_f32_e32 v185, v186
	v_rcp_iflag_f32_e32 v186, v187
	v_rcp_iflag_f32_e32 v187, v188
	v_cvt_f32_ubyte3_e32 v189, v180
	v_cvt_f32_ubyte2_e32 v188, v180
	v_cvt_f32_ubyte1_e32 v203, v180
	v_cvt_f32_ubyte0_e32 v202, v180
	v_pk_mul_f32 v[178:179], v[178:179], v[202:203]
	v_pk_mul_f32 v[182:183], v[182:183], v[188:189]
	v_pk_mul_f32 v[102:103], v[102:103], v[178:179]
	v_pk_mul_f32 v[104:105], v[104:105], v[182:183]
	v_cvt_f32_ubyte3_e32 v179, v181
	v_cvt_f32_ubyte2_e32 v178, v181
	v_cvt_f32_ubyte1_e32 v183, v181
	v_cvt_f32_ubyte0_e32 v182, v181
	v_pk_mul_f32 v[180:181], v[184:185], v[182:183]
	v_pk_mul_f32 v[178:179], v[186:187], v[178:179]
	v_pk_mul_f32 v[98:99], v[98:99], v[180:181]
	v_pk_mul_f32 v[100:101], v[100:101], v[178:179]
	v_cvt_f32_ubyte0_e32 v0, v174
	v_cvt_f32_ubyte1_e32 v178, v174
	v_cvt_f32_ubyte2_e32 v179, v174
	v_cvt_f32_ubyte3_e32 v180, v174
	v_cvt_f32_ubyte0_e32 v181, v175
	v_cvt_f32_ubyte1_e32 v182, v175
	v_cvt_f32_ubyte2_e32 v183, v175
	v_cvt_f32_ubyte3_e32 v184, v175
	v_rcp_iflag_f32_e32 v174, v0
	v_rcp_iflag_f32_e32 v175, v178
	v_rcp_iflag_f32_e32 v178, v179
	v_rcp_iflag_f32_e32 v179, v180
	v_rcp_iflag_f32_e32 v180, v181
;     __device__ __forceinline__ void mid(Acc& acc, const Unit& u, int s, int wr, int wc, int fr, int fq) const {
;     ...
;         for (int i = 0; i < 8; ++i) { const int ai = i >> 2, m = i & 3;
; #pragma unroll
;             for (int bj = 0; bj < 2; ++bj) {
;                 const u32x4 ga = G[i][0], gb = G[i][1];
;                 const u32x2 wa = bj == 0 ? (u32x2){ga.x, ga.y} : (u32x2){ga.z, ga.w}, wb = bj == 0 ? (u32x2){gb.x, gb.y} : (u32x2){gb.z, gb.w};
;                 float fa[8], fb[8]; gate_unpack8(wa, fa); gate_unpack8(wb, fb);
; #pragma unroll
;                 for (int e = 0; e < 8; ++e) fa[e] = fa[e] * __builtin_amdgcn_rcpf(fb[e]);
;                 f32x4& v0 = acc[ai][bj][m][0]; f32x4& v1 = acc[ai][bj][m][1];
;                 v0[0] *= fa[0]; v0[1] *= fa[1]; v0[2] *= fa[2]; v0[3] *= fa[3]; v1[0] *= fa[4]; v1[1] *= fa[5]; v1[2] *= fa[6]; v1[3] *= fa[7]; }
	v_rcp_iflag_f32_e32 v181, v182
	v_rcp_iflag_f32_e32 v182, v183
	v_rcp_iflag_f32_e32 v183, v184
	v_cvt_f32_ubyte3_e32 v185, v170
	v_cvt_f32_ubyte2_e32 v184, v170
	v_cvt_f32_ubyte1_e32 v187, v170
	v_cvt_f32_ubyte0_e32 v186, v170
	v_pk_mul_f32 v[174:175], v[174:175], v[186:187]
	v_pk_mul_f32 v[178:179], v[178:179], v[184:185]
	v_pk_mul_f32 v[94:95], v[94:95], v[174:175]
	v_pk_mul_f32 v[96:97], v[96:97], v[178:179]
	v_cvt_f32_ubyte3_e32 v175, v171
	v_cvt_f32_ubyte2_e32 v174, v171
	v_cvt_f32_ubyte1_e32 v179, v171
	v_cvt_f32_ubyte0_e32 v178, v171
	v_pk_mul_f32 v[170:171], v[180:181], v[178:179]
	v_pk_mul_f32 v[174:175], v[182:183], v[174:175]
	v_pk_mul_f32 v[90:91], v[90:91], v[170:171]
	v_pk_mul_f32 v[92:93], v[92:93], v[174:175]
	v_cvt_f32_ubyte0_e32 v0, v176
	v_cvt_f32_ubyte1_e32 v171, v176
	v_cvt_f32_ubyte2_e32 v174, v176
	v_cvt_f32_ubyte3_e32 v175, v176
	v_rcp_iflag_f32_e32 v170, v0
	v_rcp_iflag_f32_e32 v171, v171
	v_rcp_iflag_f32_e32 v174, v174
	v_rcp_iflag_f32_e32 v175, v175
	v_cvt_f32_ubyte0_e32 v176, v177
	v_cvt_f32_ubyte1_e32 v178, v177
	v_cvt_f32_ubyte2_e32 v179, v177
	v_cvt_f32_ubyte3_e32 v180, v177
	v_rcp_iflag_f32_e32 v176, v176
	v_rcp_iflag_f32_e32 v177, v178
	v_rcp_iflag_f32_e32 v178, v179
	v_rcp_iflag_f32_e32 v179, v180
	v_cvt_f32_ubyte3_e32 v181, v172
	v_cvt_f32_ubyte2_e32 v180, v172
	v_cvt_f32_ubyte1_e32 v183, v172
	v_cvt_f32_ubyte0_e32 v182, v172
	v_pk_mul_f32 v[170:171], v[170:171], v[182:183]
	v_pk_mul_f32 v[174:175], v[174:175], v[180:181]
	v_pk_mul_f32 v[86:87], v[86:87], v[170:171]
	v_pk_mul_f32 v[88:89], v[88:89], v[174:175]
	v_cvt_f32_ubyte3_e32 v171, v173
	v_cvt_f32_ubyte2_e32 v170, v173
	v_cvt_f32_ubyte1_e32 v175, v173
	v_cvt_f32_ubyte0_e32 v174, v173
	v_pk_mul_f32 v[172:173], v[176:177], v[174:175]
	v_pk_mul_f32 v[170:171], v[178:179], v[170:171]
	v_pk_mul_f32 v[82:83], v[82:83], v[172:173]
	v_pk_mul_f32 v[84:85], v[84:85], v[170:171]
	v_cvt_f32_ubyte0_e32 v0, v166
	v_cvt_f32_ubyte1_e32 v170, v166
	v_cvt_f32_ubyte2_e32 v171, v166
	v_cvt_f32_ubyte3_e32 v172, v166
	v_cvt_f32_ubyte0_e32 v173, v167
	v_cvt_f32_ubyte1_e32 v174, v167
	v_cvt_f32_ubyte2_e32 v175, v167
	v_cvt_f32_ubyte3_e32 v176, v167
	v_rcp_iflag_f32_e32 v166, v0
	v_rcp_iflag_f32_e32 v167, v170
	v_rcp_iflag_f32_e32 v170, v171
	v_rcp_iflag_f32_e32 v171, v172
	v_rcp_iflag_f32_e32 v172, v173
	v_rcp_iflag_f32_e32 v173, v174
	v_rcp_iflag_f32_e32 v174, v175
	v_rcp_iflag_f32_e32 v175, v176
	v_cvt_f32_ubyte3_e32 v177, v162
	v_cvt_f32_ubyte2_e32 v176, v162
	v_cvt_f32_ubyte1_e32 v179, v162
	v_cvt_f32_ubyte0_e32 v178, v162
	v_pk_mul_f32 v[166:167], v[166:167], v[178:179]
	v_pk_mul_f32 v[170:171], v[170:171], v[176:177]
	v_pk_mul_f32 v[78:79], v[78:79], v[166:167]
	v_pk_mul_f32 v[80:81], v[80:81], v[170:171]
	v_cvt_f32_ubyte3_e32 v167, v163
	v_cvt_f32_ubyte2_e32 v166, v163
	v_cvt_f32_ubyte1_e32 v171, v163
	v_cvt_f32_ubyte0_e32 v170, v163
	v_pk_mul_f32 v[162:163], v[172:173], v[170:171]
	v_pk_mul_f32 v[166:167], v[174:175], v[166:167]
	v_pk_mul_f32 v[74:75], v[74:75], v[162:163]
	v_pk_mul_f32 v[76:77], v[76:77], v[166:167]
	v_cvt_f32_ubyte0_e32 v0, v168
	v_cvt_f32_ubyte1_e32 v163, v168
	v_cvt_f32_ubyte2_e32 v166, v168
	v_cvt_f32_ubyte3_e32 v167, v168
	v_rcp_iflag_f32_e32 v162, v0
	v_rcp_iflag_f32_e32 v163, v163
	v_rcp_iflag_f32_e32 v166, v166
	v_rcp_iflag_f32_e32 v167, v167
	v_cvt_f32_ubyte0_e32 v168, v169
	v_cvt_f32_ubyte1_e32 v170, v169
	v_cvt_f32_ubyte2_e32 v171, v169
	v_cvt_f32_ubyte3_e32 v172, v169
	v_rcp_iflag_f32_e32 v168, v168
	v_rcp_iflag_f32_e32 v169, v170
	v_rcp_iflag_f32_e32 v170, v171
	v_rcp_iflag_f32_e32 v171, v172
	v_cvt_f32_ubyte3_e32 v173, v164
	v_cvt_f32_ubyte2_e32 v172, v164
	v_cvt_f32_ubyte1_e32 v175, v164
	v_cvt_f32_ubyte0_e32 v174, v164
	v_pk_mul_f32 v[162:163], v[162:163], v[174:175]
	v_pk_mul_f32 v[166:167], v[166:167], v[172:173]
	v_pk_mul_f32 v[70:71], v[70:71], v[162:163]
	v_pk_mul_f32 v[72:73], v[72:73], v[166:167]
	v_cvt_f32_ubyte3_e32 v163, v165
	v_cvt_f32_ubyte2_e32 v162, v165
	v_cvt_f32_ubyte1_e32 v167, v165
	v_cvt_f32_ubyte0_e32 v166, v165
	v_pk_mul_f32 v[164:165], v[168:169], v[166:167]
	v_pk_mul_f32 v[162:163], v[170:171], v[162:163]
	v_pk_mul_f32 v[66:67], v[66:67], v[164:165]
	v_pk_mul_f32 v[68:69], v[68:69], v[162:163]
	s_waitcnt vmcnt(6)
	v_cvt_f32_ubyte0_e32 v0, v158
	v_cvt_f32_ubyte1_e32 v162, v158
	v_cvt_f32_ubyte2_e32 v163, v158
	v_cvt_f32_ubyte3_e32 v164, v158
	v_cvt_f32_ubyte0_e32 v165, v159
	v_cvt_f32_ubyte1_e32 v166, v159
	v_cvt_f32_ubyte2_e32 v167, v159
	v_cvt_f32_ubyte3_e32 v168, v159
	v_rcp_iflag_f32_e32 v158, v0
	v_rcp_iflag_f32_e32 v159, v162
	v_rcp_iflag_f32_e32 v162, v163
	v_rcp_iflag_f32_e32 v163, v164
	v_rcp_iflag_f32_e32 v164, v165
	v_rcp_iflag_f32_e32 v165, v166
	v_rcp_iflag_f32_e32 v166, v167
	v_rcp_iflag_f32_e32 v167, v168
	v_cvt_f32_ubyte3_e32 v169, v154
	v_cvt_f32_ubyte2_e32 v168, v154
	v_cvt_f32_ubyte1_e32 v171, v154
	v_cvt_f32_ubyte0_e32 v170, v154
	v_pk_mul_f32 v[158:159], v[158:159], v[170:171]
	v_pk_mul_f32 v[162:163], v[162:163], v[168:169]
	v_pk_mul_f32 v[62:63], v[62:63], v[158:159]
	v_pk_mul_f32 v[64:65], v[64:65], v[162:163]
	v_cvt_f32_ubyte3_e32 v159, v155
	v_cvt_f32_ubyte2_e32 v158, v155
	v_cvt_f32_ubyte1_e32 v163, v155
	v_cvt_f32_ubyte0_e32 v162, v155
	v_pk_mul_f32 v[154:155], v[164:165], v[162:163]
	v_pk_mul_f32 v[158:159], v[166:167], v[158:159]
	v_pk_mul_f32 v[58:59], v[58:59], v[154:155]
	v_pk_mul_f32 v[60:61], v[60:61], v[158:159]
	v_cvt_f32_ubyte0_e32 v0, v160
	v_cvt_f32_ubyte1_e32 v155, v160
	v_cvt_f32_ubyte2_e32 v158, v160
	v_cvt_f32_ubyte3_e32 v159, v160
	v_rcp_iflag_f32_e32 v154, v0
	v_rcp_iflag_f32_e32 v155, v155
	v_rcp_iflag_f32_e32 v158, v158
	v_rcp_iflag_f32_e32 v159, v159
	v_cvt_f32_ubyte0_e32 v160, v161
	v_cvt_f32_ubyte1_e32 v162, v161
	v_cvt_f32_ubyte2_e32 v163, v161
	v_cvt_f32_ubyte3_e32 v164, v161
	v_rcp_iflag_f32_e32 v160, v160
	v_rcp_iflag_f32_e32 v161, v162
	v_rcp_iflag_f32_e32 v162, v163
	v_rcp_iflag_f32_e32 v163, v164
	v_cvt_f32_ubyte3_e32 v165, v156
	v_cvt_f32_ubyte2_e32 v164, v156
	v_cvt_f32_ubyte1_e32 v167, v156
	v_cvt_f32_ubyte0_e32 v166, v156
	v_pk_mul_f32 v[154:155], v[154:155], v[166:167]
	v_pk_mul_f32 v[158:159], v[158:159], v[164:165]
	v_pk_mul_f32 v[54:55], v[54:55], v[154:155]
	v_pk_mul_f32 v[56:57], v[56:57], v[158:159]
	v_cvt_f32_ubyte3_e32 v155, v157
	v_cvt_f32_ubyte2_e32 v154, v157
	v_cvt_f32_ubyte1_e32 v159, v157
	v_cvt_f32_ubyte0_e32 v158, v157
	v_pk_mul_f32 v[156:157], v[160:161], v[158:159]
	v_pk_mul_f32 v[154:155], v[162:163], v[154:155]
	v_pk_mul_f32 v[50:51], v[50:51], v[156:157]
	v_pk_mul_f32 v[52:53], v[52:53], v[154:155]
	s_waitcnt vmcnt(4)
;     __device__ __forceinline__ void mid(Acc& acc, const Unit& u, int s, int wr, int wc, int fr, int fq) const {
;     ...
;         for (int i = 0; i < 8; ++i) { const int ai = i >> 2, m = i & 3;
; #pragma unroll
;             for (int bj = 0; bj < 2; ++bj) {
;                 const u32x4 ga = G[i][0], gb = G[i][1];
;                 const u32x2 wa = bj == 0 ? (u32x2){ga.x, ga.y} : (u32x2){ga.z, ga.w}, wb = bj == 0 ? (u32x2){gb.x, gb.y} : (u32x2){gb.z, gb.w};
;                 float fa[8], fb[8]; gate_unpack8(wa, fa); gate_unpack8(wb, fb);
; #pragma unroll
;                 for (int e = 0; e < 8; ++e) fa[e] = fa[e] * __builtin_amdgcn_rcpf(fb[e]);
;                 f32x4& v0 = acc[ai][bj][m][0]; f32x4& v1 = acc[ai][bj][m][1];
;                 v0[0] *= fa[0]; v0[1] *= fa[1]; v0[2] *= fa[2]; v0[3] *= fa[3]; v1[0] *= fa[4]; v1[1] *= fa[5]; v1[2] *= fa[6]; v1[3] *= fa[7]; }
	v_cvt_f32_ubyte0_e32 v0, v150
	v_cvt_f32_ubyte1_e32 v154, v150
	v_cvt_f32_ubyte2_e32 v155, v150
	v_cvt_f32_ubyte3_e32 v156, v150
	v_cvt_f32_ubyte0_e32 v157, v151
	v_cvt_f32_ubyte1_e32 v158, v151
	v_cvt_f32_ubyte2_e32 v159, v151
	v_cvt_f32_ubyte3_e32 v160, v151
	v_rcp_iflag_f32_e32 v150, v0
	v_rcp_iflag_f32_e32 v151, v154
	v_rcp_iflag_f32_e32 v154, v155
	v_rcp_iflag_f32_e32 v155, v156
	v_rcp_iflag_f32_e32 v156, v157
	v_rcp_iflag_f32_e32 v157, v158
	v_rcp_iflag_f32_e32 v158, v159
	v_rcp_iflag_f32_e32 v159, v160
	v_cvt_f32_ubyte3_e32 v161, v146
	v_cvt_f32_ubyte2_e32 v160, v146
	v_cvt_f32_ubyte1_e32 v163, v146
	v_cvt_f32_ubyte0_e32 v162, v146
	v_pk_mul_f32 v[150:151], v[150:151], v[162:163]
	v_pk_mul_f32 v[154:155], v[154:155], v[160:161]
	v_pk_mul_f32 v[46:47], v[46:47], v[150:151]
	v_pk_mul_f32 v[48:49], v[48:49], v[154:155]
	v_cvt_f32_ubyte3_e32 v151, v147
	v_cvt_f32_ubyte2_e32 v150, v147
	v_cvt_f32_ubyte1_e32 v155, v147
	v_cvt_f32_ubyte0_e32 v154, v147
	v_pk_mul_f32 v[146:147], v[156:157], v[154:155]
	v_pk_mul_f32 v[150:151], v[158:159], v[150:151]
	v_pk_mul_f32 v[42:43], v[42:43], v[146:147]
	v_pk_mul_f32 v[44:45], v[44:45], v[150:151]
	v_cvt_f32_ubyte0_e32 v0, v152
	v_cvt_f32_ubyte1_e32 v147, v152
	v_cvt_f32_ubyte2_e32 v150, v152
	v_cvt_f32_ubyte3_e32 v151, v152
	v_rcp_iflag_f32_e32 v146, v0
	v_rcp_iflag_f32_e32 v147, v147
	v_rcp_iflag_f32_e32 v150, v150
	v_rcp_iflag_f32_e32 v151, v151
	v_cvt_f32_ubyte0_e32 v152, v153
	v_cvt_f32_ubyte1_e32 v154, v153
	v_cvt_f32_ubyte2_e32 v155, v153
	v_cvt_f32_ubyte3_e32 v156, v153
	v_rcp_iflag_f32_e32 v152, v152
	v_rcp_iflag_f32_e32 v153, v154
	v_rcp_iflag_f32_e32 v154, v155
	v_rcp_iflag_f32_e32 v155, v156
	v_cvt_f32_ubyte3_e32 v157, v148
	v_cvt_f32_ubyte2_e32 v156, v148
	v_cvt_f32_ubyte1_e32 v159, v148
	v_cvt_f32_ubyte0_e32 v158, v148
	v_pk_mul_f32 v[146:147], v[146:147], v[158:159]
	v_pk_mul_f32 v[150:151], v[150:151], v[156:157]
	v_pk_mul_f32 v[38:39], v[38:39], v[146:147]
	v_pk_mul_f32 v[40:41], v[40:41], v[150:151]
	v_cvt_f32_ubyte3_e32 v147, v149
	v_cvt_f32_ubyte2_e32 v146, v149
	v_cvt_f32_ubyte1_e32 v151, v149
	v_cvt_f32_ubyte0_e32 v150, v149
	v_pk_mul_f32 v[148:149], v[152:153], v[150:151]
	v_pk_mul_f32 v[146:147], v[154:155], v[146:147]
	v_pk_mul_f32 v[34:35], v[34:35], v[148:149]
	v_pk_mul_f32 v[36:37], v[36:37], v[146:147]
	s_waitcnt vmcnt(2)
	v_cvt_f32_ubyte0_e32 v0, v142
	v_cvt_f32_ubyte1_e32 v146, v142
	v_cvt_f32_ubyte2_e32 v147, v142
	v_cvt_f32_ubyte3_e32 v148, v142
	v_cvt_f32_ubyte0_e32 v149, v143
	v_cvt_f32_ubyte1_e32 v150, v143
	v_cvt_f32_ubyte2_e32 v151, v143
	v_cvt_f32_ubyte3_e32 v152, v143
	v_rcp_iflag_f32_e32 v142, v0
	v_rcp_iflag_f32_e32 v143, v146
	v_rcp_iflag_f32_e32 v146, v147
	v_rcp_iflag_f32_e32 v147, v148
	v_rcp_iflag_f32_e32 v148, v149
	v_rcp_iflag_f32_e32 v149, v150
	v_rcp_iflag_f32_e32 v150, v151
	v_rcp_iflag_f32_e32 v151, v152
	v_cvt_f32_ubyte3_e32 v153, v138
	v_cvt_f32_ubyte2_e32 v152, v138
	v_cvt_f32_ubyte1_e32 v155, v138
	v_cvt_f32_ubyte0_e32 v154, v138
	v_pk_mul_f32 v[142:143], v[142:143], v[154:155]
	v_pk_mul_f32 v[146:147], v[146:147], v[152:153]
	v_pk_mul_f32 v[30:31], v[30:31], v[142:143]
	v_pk_mul_f32 v[32:33], v[32:33], v[146:147]
	v_cvt_f32_ubyte3_e32 v143, v139
	v_cvt_f32_ubyte2_e32 v142, v139
	v_cvt_f32_ubyte1_e32 v147, v139
	v_cvt_f32_ubyte0_e32 v146, v139
	v_pk_mul_f32 v[138:139], v[148:149], v[146:147]
	v_pk_mul_f32 v[142:143], v[150:151], v[142:143]
	v_pk_mul_f32 v[22:23], v[22:23], v[138:139]
	v_pk_mul_f32 v[24:25], v[24:25], v[142:143]
	v_cvt_f32_ubyte0_e32 v0, v144
	v_cvt_f32_ubyte1_e32 v139, v144
	v_cvt_f32_ubyte2_e32 v142, v144
	v_cvt_f32_ubyte3_e32 v143, v144
	v_rcp_iflag_f32_e32 v138, v0
	v_rcp_iflag_f32_e32 v139, v139
	v_rcp_iflag_f32_e32 v142, v142
	v_rcp_iflag_f32_e32 v143, v143
	v_cvt_f32_ubyte0_e32 v144, v145
	v_cvt_f32_ubyte1_e32 v146, v145
	v_cvt_f32_ubyte2_e32 v147, v145
	v_cvt_f32_ubyte3_e32 v148, v145
	v_rcp_iflag_f32_e32 v144, v144
	v_rcp_iflag_f32_e32 v145, v146
	v_rcp_iflag_f32_e32 v146, v147
	v_rcp_iflag_f32_e32 v147, v148
	v_cvt_f32_ubyte3_e32 v149, v140
	v_cvt_f32_ubyte2_e32 v148, v140
	v_cvt_f32_ubyte1_e32 v151, v140
	v_cvt_f32_ubyte0_e32 v150, v140
	v_pk_mul_f32 v[138:139], v[138:139], v[150:151]
	v_pk_mul_f32 v[142:143], v[142:143], v[148:149]
	v_pk_mul_f32 v[26:27], v[26:27], v[138:139]
	v_pk_mul_f32 v[28:29], v[28:29], v[142:143]
	v_cvt_f32_ubyte3_e32 v139, v141
	v_cvt_f32_ubyte2_e32 v138, v141
	v_cvt_f32_ubyte1_e32 v143, v141
	v_cvt_f32_ubyte0_e32 v142, v141
	v_pk_mul_f32 v[140:141], v[144:145], v[142:143]
	v_pk_mul_f32 v[138:139], v[146:147], v[138:139]
	v_pk_mul_f32 v[18:19], v[18:19], v[140:141]
	v_pk_mul_f32 v[20:21], v[20:21], v[138:139]
	s_waitcnt vmcnt(0)
	v_cvt_f32_ubyte0_e32 v0, v134
	v_cvt_f32_ubyte1_e32 v138, v134
	v_cvt_f32_ubyte2_e32 v139, v134
	v_cvt_f32_ubyte3_e32 v140, v134
	v_cvt_f32_ubyte0_e32 v141, v135
	v_cvt_f32_ubyte1_e32 v142, v135
	v_cvt_f32_ubyte2_e32 v143, v135
	v_cvt_f32_ubyte3_e32 v144, v135
	v_rcp_iflag_f32_e32 v134, v0
	v_rcp_iflag_f32_e32 v135, v138
	v_rcp_iflag_f32_e32 v138, v139
	v_rcp_iflag_f32_e32 v139, v140
	v_rcp_iflag_f32_e32 v140, v141
	v_rcp_iflag_f32_e32 v141, v142
	v_rcp_iflag_f32_e32 v142, v143
	v_rcp_iflag_f32_e32 v143, v144
	v_cvt_f32_ubyte3_e32 v145, v130
	v_cvt_f32_ubyte2_e32 v144, v130
	v_cvt_f32_ubyte1_e32 v147, v130
	v_cvt_f32_ubyte0_e32 v146, v130
	v_pk_mul_f32 v[134:135], v[134:135], v[146:147]
	v_pk_mul_f32 v[138:139], v[138:139], v[144:145]
	v_pk_mul_f32 v[14:15], v[14:15], v[134:135]
	v_pk_mul_f32 v[16:17], v[16:17], v[138:139]
	v_cvt_f32_ubyte3_e32 v135, v131
	v_cvt_f32_ubyte2_e32 v134, v131
	v_cvt_f32_ubyte1_e32 v139, v131
	v_cvt_f32_ubyte0_e32 v138, v131
	v_pk_mul_f32 v[130:131], v[140:141], v[138:139]
	v_pk_mul_f32 v[134:135], v[142:143], v[134:135]
	v_pk_mul_f32 v[6:7], v[6:7], v[130:131]
	v_pk_mul_f32 v[8:9], v[8:9], v[134:135]
	v_cvt_f32_ubyte0_e32 v0, v136
	v_cvt_f32_ubyte1_e32 v131, v136
	v_cvt_f32_ubyte2_e32 v134, v136
	v_cvt_f32_ubyte3_e32 v135, v136
	v_rcp_iflag_f32_e32 v130, v0
	v_rcp_iflag_f32_e32 v131, v131
	v_rcp_iflag_f32_e32 v134, v134
	v_rcp_iflag_f32_e32 v135, v135
	v_cvt_f32_ubyte0_e32 v136, v137
	v_cvt_f32_ubyte1_e32 v138, v137
	v_cvt_f32_ubyte2_e32 v139, v137
	v_cvt_f32_ubyte3_e32 v140, v137
	v_rcp_iflag_f32_e32 v136, v136
	v_rcp_iflag_f32_e32 v137, v138
	v_rcp_iflag_f32_e32 v138, v139
	v_rcp_iflag_f32_e32 v139, v140
	v_cvt_f32_ubyte3_e32 v141, v132
	v_cvt_f32_ubyte2_e32 v140, v132
	v_cvt_f32_ubyte1_e32 v143, v132
	v_cvt_f32_ubyte0_e32 v142, v132
	v_pk_mul_f32 v[130:131], v[130:131], v[142:143]
	v_pk_mul_f32 v[134:135], v[134:135], v[140:141]
	v_pk_mul_f32 v[10:11], v[10:11], v[130:131]
	v_pk_mul_f32 v[12:13], v[12:13], v[134:135]
	v_cvt_f32_ubyte3_e32 v131, v133
	v_cvt_f32_ubyte2_e32 v130, v133
	v_cvt_f32_ubyte1_e32 v135, v133
	v_cvt_f32_ubyte0_e32 v134, v133
	v_pk_mul_f32 v[132:133], v[136:137], v[134:135]
	v_pk_mul_f32 v[130:131], v[138:139], v[130:131]
	v_pk_mul_f32 v[2:3], v[2:3], v[132:133]
	v_pk_mul_f32 v[4:5], v[4:5], v[130:131]

; #define PG8_STAGE(bufoff, gbase, voff) do { _Pragma("unroll") for (int _i = 0; _i < 2; ++_i) \
;         __builtin_amdgcn_global_load_lds((const unsigned*)((const char*)(gbase) + (voff)[_i]), (LAS unsigned*)(lds + (bufoff) + ldsw + _i * 8192), 16, 0, 0); } while (0)
; #define PG8_LDA(dst, b, h) do { _Pragma("unroll") for (int m = 0; m < 4; ++m) _Pragma("unroll") for (int k = 0; k < 2; ++k) dst[m][k] = *(const LAS bf16x8*)(lds + PG8_SA(b, h) + aoffk[k] + m * 2048); } while (0)
; template <class Epi, class Sched, class GemmT>
; __device__ __forceinline__ void gemm_phase(LAS unsigned char* lds, const GemmT& g, const Sched& S, const Epi& E, const int wid) {
;     ...
;             for (int t = 0; t < nt; t += 2) {
;                 const bool last = (t == nt - 2);
;                 const char* a1 = cA + (size_t)(t + 1) * kstep;
;                 const char* a2 = last ? ns.A : cA + (size_t)(t + 2) * kstep; const char* b2 = last ? ns.B : cB + (size_t)(t + 2) * kstep;
;                 const char* a3 = a2 + kstep; const char* b3 = b2 + kstep;
;                 unsigned vA2[2], vB2[2];
; #pragma unroll
;                 for (int i = 0; i < 2; ++i) { vA2[i] = last ? nvA[i] : voffA[i]; vB2[i] = last ? nvB[i] : voffB[i]; }
;                 const size_t hA2 = last ? nhA : hstepA, hB2 = last ? nhB : hstepB;
;                 PG8_LDB(B0, 0, 0); PG8_LDB(B1, 0, 1); PG8_SCHED; PG8_LDA(At, 0, 0); PG8_STAGE(PG8_SA(1, 1), a1 + hstepA, voffA);
;                 PG8_WAIT_V(8); PG8_WAIT_L(0); PG8_BAR; PG8_MMA(0, 0, At, B0); PG8_MMA(0, 1, At, B1); PG8_BAR; PG8_SCHED;
;                 PG8_LDA(At, 0, 1); PG8_STAGE(PG8_SB(0, 0), b2, vB2); PG8_STAGE(PG8_SB(0, 1), b2 + hB2, vB2); PG8_STAGE(PG8_SA(0, 0), a2, vA2);
;                 PG8_WAIT_V(8); PG8_WAIT_L(0); PG8_BAR; PG8_MMA(1, 0, At, B0); PG8_MMA(1, 1, At, B1); PG8_BAR; PG8_SCHED;
;                 PG8_LDB(B0, 1, 0); PG8_LDB(B1, 1, 1); PG8_SCHED; PG8_LDA(At, 1, 0); PG8_STAGE(PG8_SA(0, 1), a2 + hA2, vA2);
;                 PG8_WAIT_V(8); PG8_WAIT_L(0); PG8_BAR; PG8_MMA(0, 0, At, B0); PG8_MMA(0, 1, At, B1); PG8_BAR; PG8_SCHED;
;                 PG8_LDA(At, 1, 1); PG8_STAGE(PG8_SB(1, 0), b3, vB2); PG8_STAGE(PG8_SB(1, 1), b3 + hB2, vB2); PG8_STAGE(PG8_SA(1, 0), a3, vA2);
;                 PG8_WAIT_V(8); PG8_WAIT_L(0); PG8_BAR; PG8_MMA(1, 0, At, B0); PG8_MMA(1, 1, At, B1); PG8_BAR; PG8_SCHED;
;             }
.LBB0_846:
	ds_read_b128 v[128:131], v194
	ds_read_b128 v[132:135], v195
	ds_read_b128 v[136:139], v196
	ds_read_b128 v[140:143], v197
	ds_read_b128 v[144:147], v198
	ds_read_b128 v[148:151], v199
	ds_read_b128 v[152:155], v200
	ds_read_b128 v[168:171], v201
	s_add_u32 s44, s42, 0xfff00080
	s_addc_u32 s45, s43, -1
	s_cmp_eq_u32 s62, 60
	s_cselect_b32 s51, s37, s45
	s_cselect_b32 s50, s36, s44
	s_cselect_b32 s45, s59, s61
	s_cselect_b32 s44, s41, s60
	v_lshl_add_u64 v[188:189], s[42:43], 0, v[156:157]
	s_add_i32 m0, s14, 0xc000
	ds_read_b128 v[172:175], v202
	ds_read_b128 v[176:179], v202 offset:2048
	ds_read_b128 v[180:183], v203
	ds_read_b128 v[184:187], v203 offset:2048
	ds_read_b128 v[208:211], v202 offset:4096
	ds_read_b128 v[212:215], v202 offset:6144
	ds_read_b128 v[216:219], v203 offset:4096
	ds_read_b128 v[220:223], v203 offset:6144
	global_load_lds_dwordx4 v[188:189], off
	v_lshl_add_u64 v[188:189], s[42:43], 0, v[160:161]
	s_add_i32 m0, s14, 0xe000
	s_nop 0
	global_load_lds_dwordx4 v[188:189], off
	s_waitcnt vmcnt(8)
	s_waitcnt lgkmcnt(0)
	s_barrier
	s_setprio 3
	s_waitcnt lgkmcnt(0)
	v_mfma_f32_16x16x32_bf16 v[124:127], v[128:131], v[172:175], v[124:127]
	v_mfma_f32_16x16x32_bf16 v[124:127], v[132:135], v[180:183], v[124:127]
	v_mfma_f32_16x16x32_bf16 v[120:123], v[136:139], v[172:175], v[120:123]
	v_mfma_f32_16x16x32_bf16 v[120:123], v[140:143], v[180:183], v[120:123]
	v_mfma_f32_16x16x32_bf16 v[108:111], v[128:131], v[176:179], v[108:111]
	v_mfma_f32_16x16x32_bf16 v[108:111], v[132:135], v[184:187], v[108:111]
	v_mfma_f32_16x16x32_bf16 v[104:107], v[136:139], v[176:179], v[104:107]
	v_mfma_f32_16x16x32_bf16 v[104:107], v[140:143], v[184:187], v[104:107]
	v_mfma_f32_16x16x32_bf16 v[92:95], v[128:131], v[208:211], v[92:95]
	v_mfma_f32_16x16x32_bf16 v[92:95], v[132:135], v[216:219], v[92:95]
	v_mfma_f32_16x16x32_bf16 v[88:91], v[136:139], v[208:211], v[88:91]
	v_mfma_f32_16x16x32_bf16 v[88:91], v[140:143], v[216:219], v[88:91]
	v_mfma_f32_16x16x32_bf16 v[76:79], v[128:131], v[212:215], v[76:79]
	v_mfma_f32_16x16x32_bf16 v[76:79], v[132:135], v[220:223], v[76:79]
	v_mfma_f32_16x16x32_bf16 v[72:75], v[136:139], v[212:215], v[72:75]
	v_mfma_f32_16x16x32_bf16 v[72:75], v[140:143], v[220:223], v[72:75]
	s_setprio 0
	s_setprio 3
	v_mfma_f32_16x16x32_bf16 v[116:119], v[144:147], v[172:175], v[116:119]
	v_mfma_f32_16x16x32_bf16 v[116:119], v[148:151], v[180:183], v[116:119]
	v_mfma_f32_16x16x32_bf16 v[112:115], v[152:155], v[172:175], v[112:115]
	v_mfma_f32_16x16x32_bf16 v[112:115], v[168:171], v[180:183], v[112:115]
	v_mfma_f32_16x16x32_bf16 v[100:103], v[144:147], v[176:179], v[100:103]
	v_mfma_f32_16x16x32_bf16 v[100:103], v[148:151], v[184:187], v[100:103]
	v_mfma_f32_16x16x32_bf16 v[96:99], v[152:155], v[176:179], v[96:99]
	v_mfma_f32_16x16x32_bf16 v[96:99], v[168:171], v[184:187], v[96:99]
	v_mfma_f32_16x16x32_bf16 v[84:87], v[144:147], v[208:211], v[84:87]
	v_mfma_f32_16x16x32_bf16 v[84:87], v[148:151], v[216:219], v[84:87]
	v_mfma_f32_16x16x32_bf16 v[80:83], v[152:155], v[208:211], v[80:83]
	v_mfma_f32_16x16x32_bf16 v[80:83], v[168:171], v[216:219], v[80:83]
	v_mfma_f32_16x16x32_bf16 v[68:71], v[144:147], v[212:215], v[68:71]
	v_mfma_f32_16x16x32_bf16 v[68:71], v[148:151], v[220:223], v[68:71]
	v_mfma_f32_16x16x32_bf16 v[64:67], v[152:155], v[212:215], v[64:67]
	v_mfma_f32_16x16x32_bf16 v[64:67], v[168:171], v[220:223], v[64:67]
	s_setprio 0
	s_barrier
	s_add_i32 s48, s54, s68
	v_lshl_add_u64 v[188:189], s[44:45], 0, v[158:159]
	s_mov_b32 m0, s48
	ds_read_b128 v[172:175], v202 offset:16384
	ds_read_b128 v[176:179], v202 offset:18432
	ds_read_b128 v[180:183], v203 offset:16384
	ds_read_b128 v[184:187], v203 offset:18432
	ds_read_b128 v[208:211], v202 offset:20480
	ds_read_b128 v[212:215], v202 offset:22528
	ds_read_b128 v[216:219], v203 offset:20480
	ds_read_b128 v[220:223], v203 offset:22528
	global_load_lds_dwordx4 v[188:189], off
	s_add_i32 m0, s48, 0x2000
	s_add_u32 s48, s44, 0x100000
	v_lshl_add_u64 v[224:225], s[44:45], 0, v[162:163]
	s_addc_u32 s49, s45, 0
	s_add_i32 s63, s55, s68
	global_load_lds_dwordx4 v[224:225], off
	v_lshl_add_u64 v[226:227], s[48:49], 0, v[158:159]
	s_mov_b32 m0, s63
	v_lshl_add_u64 v[230:231], s[50:51], 0, v[160:161]
	global_load_lds_dwordx4 v[226:227], off
	v_lshl_add_u64 v[226:227], s[48:49], 0, v[162:163]
	s_add_i32 m0, s63, 0x2000
	s_nop 0
	global_load_lds_dwordx4 v[226:227], off
	v_lshl_add_u64 v[226:227], s[50:51], 0, v[156:157]
	s_mov_b32 m0, s14
	s_nop 0
	global_load_lds_dwordx4 v[226:227], off
	s_mov_b32 m0, s15
	s_nop 0
	global_load_lds_dwordx4 v[230:231], off
	s_waitcnt vmcnt(8)
	s_waitcnt lgkmcnt(0)
	s_barrier
; #define PG8_STAGE(bufoff, gbase, voff) do { _Pragma("unroll") for (int _i = 0; _i < 2; ++_i) \
;         __builtin_amdgcn_global_load_lds((const unsigned*)((const char*)(gbase) + (voff)[_i]), (LAS unsigned*)(lds + (bufoff) + ldsw + _i * 8192), 16, 0, 0); } while (0)
; #define PG8_LDA(dst, b, h) do { _Pragma("unroll") for (int m = 0; m < 4; ++m) _Pragma("unroll") for (int k = 0; k < 2; ++k) dst[m][k] = *(const LAS bf16x8*)(lds + PG8_SA(b, h) + aoffk[k] + m * 2048); } while (0)
; template <class Epi, class Sched, class GemmT>
; __device__ __forceinline__ void gemm_phase(LAS unsigned char* lds, const GemmT& g, const Sched& S, const Epi& E, const int wid) {
;     ...
;             for (int t = 0; t < nt; t += 2) {
;                 const bool last = (t == nt - 2);
;                 const char* a1 = cA + (size_t)(t + 1) * kstep;
;                 const char* a2 = last ? ns.A : cA + (size_t)(t + 2) * kstep; const char* b2 = last ? ns.B : cB + (size_t)(t + 2) * kstep;
;                 const char* a3 = a2 + kstep; const char* b3 = b2 + kstep;
;                 unsigned vA2[2], vB2[2];
; #pragma unroll
;                 for (int i = 0; i < 2; ++i) { vA2[i] = last ? nvA[i] : voffA[i]; vB2[i] = last ? nvB[i] : voffB[i]; }
;                 const size_t hA2 = last ? nhA : hstepA, hB2 = last ? nhB : hstepB;
;                 PG8_LDB(B0, 0, 0); PG8_LDB(B1, 0, 1); PG8_SCHED; PG8_LDA(At, 0, 0); PG8_STAGE(PG8_SA(1, 1), a1 + hstepA, voffA);
;                 PG8_WAIT_V(8); PG8_WAIT_L(0); PG8_BAR; PG8_MMA(0, 0, At, B0); PG8_MMA(0, 1, At, B1); PG8_BAR; PG8_SCHED;
;                 PG8_LDA(At, 0, 1); PG8_STAGE(PG8_SB(0, 0), b2, vB2); PG8_STAGE(PG8_SB(0, 1), b2 + hB2, vB2); PG8_STAGE(PG8_SA(0, 0), a2, vA2);
;                 PG8_WAIT_V(8); PG8_WAIT_L(0); PG8_BAR; PG8_MMA(1, 0, At, B0); PG8_MMA(1, 1, At, B1); PG8_BAR; PG8_SCHED;
;                 PG8_LDB(B0, 1, 0); PG8_LDB(B1, 1, 1); PG8_SCHED; PG8_LDA(At, 1, 0); PG8_STAGE(PG8_SA(0, 1), a2 + hA2, vA2);
;                 PG8_WAIT_V(8); PG8_WAIT_L(0); PG8_BAR; PG8_MMA(0, 0, At, B0); PG8_MMA(0, 1, At, B1); PG8_BAR; PG8_SCHED;
;                 PG8_LDA(At, 1, 1); PG8_STAGE(PG8_SB(1, 0), b3, vB2); PG8_STAGE(PG8_SB(1, 1), b3 + hB2, vB2); PG8_STAGE(PG8_SA(1, 0), a3, vA2);
;                 PG8_WAIT_V(8); PG8_WAIT_L(0); PG8_BAR; PG8_MMA(1, 0, At, B0); PG8_MMA(1, 1, At, B1); PG8_BAR; PG8_SCHED;
;             }
	s_setprio 3
	s_waitcnt lgkmcnt(0)
	v_mfma_f32_16x16x32_bf16 v[52:55], v[128:131], v[172:175], v[52:55]
	v_mfma_f32_16x16x32_bf16 v[52:55], v[132:135], v[180:183], v[52:55]
	v_mfma_f32_16x16x32_bf16 v[48:51], v[136:139], v[172:175], v[48:51]
	v_mfma_f32_16x16x32_bf16 v[48:51], v[140:143], v[180:183], v[48:51]
	v_mfma_f32_16x16x32_bf16 v[36:39], v[128:131], v[176:179], v[36:39]
	v_mfma_f32_16x16x32_bf16 v[36:39], v[132:135], v[184:187], v[36:39]
	v_mfma_f32_16x16x32_bf16 v[32:35], v[136:139], v[176:179], v[32:35]
	v_mfma_f32_16x16x32_bf16 v[32:35], v[140:143], v[184:187], v[32:35]
	v_mfma_f32_16x16x32_bf16 v[20:23], v[128:131], v[208:211], v[20:23]
	v_mfma_f32_16x16x32_bf16 v[20:23], v[132:135], v[216:219], v[20:23]
	v_mfma_f32_16x16x32_bf16 v[16:19], v[136:139], v[208:211], v[16:19]
	v_mfma_f32_16x16x32_bf16 v[16:19], v[140:143], v[216:219], v[16:19]
	v_mfma_f32_16x16x32_bf16 v[4:7], v[128:131], v[212:215], v[4:7]
	v_mfma_f32_16x16x32_bf16 v[4:7], v[132:135], v[220:223], v[4:7]
	v_mfma_f32_16x16x32_bf16 v[0:3], v[136:139], v[212:215], v[0:3]
	v_mfma_f32_16x16x32_bf16 v[0:3], v[140:143], v[220:223], v[0:3]
	s_setprio 0
	s_setprio 3
	v_mfma_f32_16x16x32_bf16 v[60:63], v[144:147], v[172:175], v[60:63]
	v_mfma_f32_16x16x32_bf16 v[60:63], v[148:151], v[180:183], v[60:63]
	v_mfma_f32_16x16x32_bf16 v[56:59], v[152:155], v[172:175], v[56:59]
	v_mfma_f32_16x16x32_bf16 v[56:59], v[168:171], v[180:183], v[56:59]
	v_mfma_f32_16x16x32_bf16 v[44:47], v[144:147], v[176:179], v[44:47]
	v_mfma_f32_16x16x32_bf16 v[44:47], v[148:151], v[184:187], v[44:47]
	v_mfma_f32_16x16x32_bf16 v[40:43], v[152:155], v[176:179], v[40:43]
	v_mfma_f32_16x16x32_bf16 v[40:43], v[168:171], v[184:187], v[40:43]
	v_mfma_f32_16x16x32_bf16 v[28:31], v[144:147], v[208:211], v[28:31]
	v_mfma_f32_16x16x32_bf16 v[28:31], v[148:151], v[216:219], v[28:31]
	v_mfma_f32_16x16x32_bf16 v[24:27], v[152:155], v[208:211], v[24:27]
	v_mfma_f32_16x16x32_bf16 v[24:27], v[168:171], v[216:219], v[24:27]
	v_mfma_f32_16x16x32_bf16 v[12:15], v[144:147], v[212:215], v[12:15]
	v_mfma_f32_16x16x32_bf16 v[12:15], v[148:151], v[220:223], v[12:15]
	v_mfma_f32_16x16x32_bf16 v[8:11], v[152:155], v[212:215], v[8:11]
	v_mfma_f32_16x16x32_bf16 v[8:11], v[168:171], v[220:223], v[8:11]
	s_setprio 0
	s_barrier
	s_add_i32 s63, 0, 0x18000
	s_add_i32 s64, 0, 0x1c000
	v_add_u32_e32 v128, s63, v191
	v_add_u32_e32 v132, s63, v192
	v_add_u32_e32 v144, s64, v191
	v_add_u32_e32 v148, s64, v192
	ds_read_b128 v[128:131], v128
	ds_read_b128 v[132:135], v132
	ds_read_b128 v[136:139], v204
	ds_read_b128 v[140:143], v205
	ds_read_b128 v[144:147], v144
	ds_read_b128 v[148:151], v148
	ds_read_b128 v[152:155], v206
	ds_read_b128 v[168:171], v207
	s_add_u32 s48, s50, 0x100000
	s_addc_u32 s49, s51, 0
	s_mov_b32 m0, s22
	v_lshl_add_u64 v[232:233], s[48:49], 0, v[156:157]
	ds_read_b128 v[172:175], v202 offset:32768
	ds_read_b128 v[176:179], v202 offset:34816
	ds_read_b128 v[180:183], v203 offset:32768
	ds_read_b128 v[184:187], v203 offset:34816
	ds_read_b128 v[208:211], v202 offset:36864
	ds_read_b128 v[212:215], v202 offset:38912
	ds_read_b128 v[216:219], v203 offset:36864
	ds_read_b128 v[220:223], v203 offset:38912
	global_load_lds_dwordx4 v[232:233], off
	v_lshl_add_u64 v[232:233], s[48:49], 0, v[160:161]
	s_mov_b32 m0, s23
	s_nop 0
	global_load_lds_dwordx4 v[232:233], off
	s_waitcnt vmcnt(8)
	s_waitcnt lgkmcnt(0)
	s_barrier
	s_setprio 3
	s_waitcnt lgkmcnt(0)
	v_mfma_f32_16x16x32_bf16 v[124:127], v[128:131], v[172:175], v[124:127]
	v_mfma_f32_16x16x32_bf16 v[124:127], v[132:135], v[180:183], v[124:127]
	v_mfma_f32_16x16x32_bf16 v[120:123], v[136:139], v[172:175], v[120:123]
	v_mfma_f32_16x16x32_bf16 v[120:123], v[140:143], v[180:183], v[120:123]
	v_mfma_f32_16x16x32_bf16 v[108:111], v[128:131], v[176:179], v[108:111]
	v_mfma_f32_16x16x32_bf16 v[108:111], v[132:135], v[184:187], v[108:111]
	v_mfma_f32_16x16x32_bf16 v[104:107], v[136:139], v[176:179], v[104:107]
	v_mfma_f32_16x16x32_bf16 v[104:107], v[140:143], v[184:187], v[104:107]
	v_mfma_f32_16x16x32_bf16 v[92:95], v[128:131], v[208:211], v[92:95]
	v_mfma_f32_16x16x32_bf16 v[92:95], v[132:135], v[216:219], v[92:95]
	v_mfma_f32_16x16x32_bf16 v[88:91], v[136:139], v[208:211], v[88:91]
	v_mfma_f32_16x16x32_bf16 v[88:91], v[140:143], v[216:219], v[88:91]
	v_mfma_f32_16x16x32_bf16 v[76:79], v[128:131], v[212:215], v[76:79]
	v_mfma_f32_16x16x32_bf16 v[76:79], v[132:135], v[220:223], v[76:79]
	v_mfma_f32_16x16x32_bf16 v[72:75], v[136:139], v[212:215], v[72:75]
	v_mfma_f32_16x16x32_bf16 v[72:75], v[140:143], v[220:223], v[72:75]
	s_setprio 0
	s_setprio 3
	v_mfma_f32_16x16x32_bf16 v[116:119], v[144:147], v[172:175], v[116:119]
	v_mfma_f32_16x16x32_bf16 v[116:119], v[148:151], v[180:183], v[116:119]
	v_mfma_f32_16x16x32_bf16 v[112:115], v[152:155], v[172:175], v[112:115]
	v_mfma_f32_16x16x32_bf16 v[112:115], v[168:171], v[180:183], v[112:115]
	v_mfma_f32_16x16x32_bf16 v[100:103], v[144:147], v[176:179], v[100:103]
	v_mfma_f32_16x16x32_bf16 v[100:103], v[148:151], v[184:187], v[100:103]
	v_mfma_f32_16x16x32_bf16 v[96:99], v[152:155], v[176:179], v[96:99]
	v_mfma_f32_16x16x32_bf16 v[96:99], v[168:171], v[184:187], v[96:99]
	v_mfma_f32_16x16x32_bf16 v[84:87], v[144:147], v[208:211], v[84:87]
	v_mfma_f32_16x16x32_bf16 v[84:87], v[148:151], v[216:219], v[84:87]
	v_mfma_f32_16x16x32_bf16 v[80:83], v[152:155], v[208:211], v[80:83]
	v_mfma_f32_16x16x32_bf16 v[80:83], v[168:171], v[216:219], v[80:83]
	v_mfma_f32_16x16x32_bf16 v[68:71], v[144:147], v[212:215], v[68:71]
	v_mfma_f32_16x16x32_bf16 v[68:71], v[148:151], v[220:223], v[68:71]
	v_mfma_f32_16x16x32_bf16 v[64:67], v[152:155], v[212:215], v[64:67]
	v_mfma_f32_16x16x32_bf16 v[64:67], v[168:171], v[220:223], v[64:67]
	s_setprio 0
	s_barrier
; #define PG8_STAGE(bufoff, gbase, voff) do { _Pragma("unroll") for (int _i = 0; _i < 2; ++_i) \
;         __builtin_amdgcn_global_load_lds((const unsigned*)((const char*)(gbase) + (voff)[_i]), (LAS unsigned*)(lds + (bufoff) + ldsw + _i * 8192), 16, 0, 0); } while (0)
; #define PG8_LDA(dst, b, h) do { _Pragma("unroll") for (int m = 0; m < 4; ++m) _Pragma("unroll") for (int k = 0; k < 2; ++k) dst[m][k] = *(const LAS bf16x8*)(lds + PG8_SA(b, h) + aoffk[k] + m * 2048); } while (0)
; template <class Epi, class Sched, class GemmT>
; __device__ __forceinline__ void gemm_phase(LAS unsigned char* lds, const GemmT& g, const Sched& S, const Epi& E, const int wid) {
;     ...
;             for (int t = 0; t < nt; t += 2) {
;                 const bool last = (t == nt - 2);
;                 const char* a1 = cA + (size_t)(t + 1) * kstep;
;                 const char* a2 = last ? ns.A : cA + (size_t)(t + 2) * kstep; const char* b2 = last ? ns.B : cB + (size_t)(t + 2) * kstep;
;                 const char* a3 = a2 + kstep; const char* b3 = b2 + kstep;
;                 unsigned vA2[2], vB2[2];
; #pragma unroll
;                 for (int i = 0; i < 2; ++i) { vA2[i] = last ? nvA[i] : voffA[i]; vB2[i] = last ? nvB[i] : voffB[i]; }
;                 const size_t hA2 = last ? nhA : hstepA, hB2 = last ? nhB : hstepB;
;                 PG8_LDB(B0, 0, 0); PG8_LDB(B1, 0, 1); PG8_SCHED; PG8_LDA(At, 0, 0); PG8_STAGE(PG8_SA(1, 1), a1 + hstepA, voffA);
;                 PG8_WAIT_V(8); PG8_WAIT_L(0); PG8_BAR; PG8_MMA(0, 0, At, B0); PG8_MMA(0, 1, At, B1); PG8_BAR; PG8_SCHED;
;                 PG8_LDA(At, 0, 1); PG8_STAGE(PG8_SB(0, 0), b2, vB2); PG8_STAGE(PG8_SB(0, 1), b2 + hB2, vB2); PG8_STAGE(PG8_SA(0, 0), a2, vA2);
;                 PG8_WAIT_V(8); PG8_WAIT_L(0); PG8_BAR; PG8_MMA(1, 0, At, B0); PG8_MMA(1, 1, At, B1); PG8_BAR; PG8_SCHED;
;                 PG8_LDB(B0, 1, 0); PG8_LDB(B1, 1, 1); PG8_SCHED; PG8_LDA(At, 1, 0); PG8_STAGE(PG8_SA(0, 1), a2 + hA2, vA2);
;                 PG8_WAIT_V(8); PG8_WAIT_L(0); PG8_BAR; PG8_MMA(0, 0, At, B0); PG8_MMA(0, 1, At, B1); PG8_BAR; PG8_SCHED;
;                 PG8_LDA(At, 1, 1); PG8_STAGE(PG8_SB(1, 0), b3, vB2); PG8_STAGE(PG8_SB(1, 1), b3 + hB2, vB2); PG8_STAGE(PG8_SA(1, 0), a3, vA2);
;                 PG8_WAIT_V(8); PG8_WAIT_L(0); PG8_BAR; PG8_MMA(1, 0, At, B0); PG8_MMA(1, 1, At, B1); PG8_BAR; PG8_SCHED;
;             }
	s_add_i32 s48, s63, s68
	v_lshl_add_u64 v[188:189], v[188:189], 0, s[18:19]
	s_mov_b32 m0, s48
	ds_read_b128 v[172:175], v202 offset:49152
	ds_read_b128 v[176:179], v202 offset:51200
	ds_read_b128 v[180:183], v203 offset:49152
	ds_read_b128 v[184:187], v203 offset:51200
	ds_read_b128 v[208:211], v202 offset:53248
	ds_read_b128 v[212:215], v202 offset:55296
	ds_read_b128 v[216:219], v203 offset:53248
	ds_read_b128 v[220:223], v203 offset:55296
	global_load_lds_dwordx4 v[188:189], off
	s_add_i32 m0, s48, 0x2000
	s_add_u32 s44, s44, 0x100080
	v_lshl_add_u64 v[188:189], v[224:225], 0, s[18:19]
	s_addc_u32 s45, s45, 0
	s_add_i32 s48, s64, s68
	global_load_lds_dwordx4 v[188:189], off
	v_lshl_add_u64 v[188:189], s[44:45], 0, v[158:159]
	s_mov_b32 m0, s48
	s_nop 0
	global_load_lds_dwordx4 v[188:189], off
	v_lshl_add_u64 v[188:189], s[44:45], 0, v[162:163]
	s_add_i32 m0, s48, 0x2000
	s_nop 0
	global_load_lds_dwordx4 v[188:189], off
	v_lshl_add_u64 v[188:189], v[226:227], 0, s[18:19]
	s_mov_b32 m0, s34
	s_nop 0
	global_load_lds_dwordx4 v[188:189], off
	v_lshl_add_u64 v[188:189], v[230:231], 0, s[18:19]
	s_mov_b32 m0, s35
	s_nop 0
	global_load_lds_dwordx4 v[188:189], off
	s_waitcnt vmcnt(8)
	s_waitcnt lgkmcnt(0)
	s_barrier
	s_setprio 3
	s_waitcnt lgkmcnt(0)
	v_mfma_f32_16x16x32_bf16 v[52:55], v[128:131], v[172:175], v[52:55]
	v_mfma_f32_16x16x32_bf16 v[52:55], v[132:135], v[180:183], v[52:55]
	v_mfma_f32_16x16x32_bf16 v[48:51], v[136:139], v[172:175], v[48:51]
	v_mfma_f32_16x16x32_bf16 v[48:51], v[140:143], v[180:183], v[48:51]
	v_mfma_f32_16x16x32_bf16 v[36:39], v[128:131], v[176:179], v[36:39]
	v_mfma_f32_16x16x32_bf16 v[36:39], v[132:135], v[184:187], v[36:39]
	v_mfma_f32_16x16x32_bf16 v[32:35], v[136:139], v[176:179], v[32:35]
	v_mfma_f32_16x16x32_bf16 v[32:35], v[140:143], v[184:187], v[32:35]
	v_mfma_f32_16x16x32_bf16 v[20:23], v[128:131], v[208:211], v[20:23]
	v_mfma_f32_16x16x32_bf16 v[20:23], v[132:135], v[216:219], v[20:23]
	v_mfma_f32_16x16x32_bf16 v[16:19], v[136:139], v[208:211], v[16:19]
	v_mfma_f32_16x16x32_bf16 v[16:19], v[140:143], v[216:219], v[16:19]
	v_mfma_f32_16x16x32_bf16 v[4:7], v[128:131], v[212:215], v[4:7]
	v_mfma_f32_16x16x32_bf16 v[4:7], v[132:135], v[220:223], v[4:7]
	v_mfma_f32_16x16x32_bf16 v[0:3], v[136:139], v[212:215], v[0:3]
	v_mfma_f32_16x16x32_bf16 v[0:3], v[140:143], v[220:223], v[0:3]
	s_setprio 0
	s_setprio 3
	v_mfma_f32_16x16x32_bf16 v[60:63], v[144:147], v[172:175], v[60:63]
	v_mfma_f32_16x16x32_bf16 v[60:63], v[148:151], v[180:183], v[60:63]
	v_mfma_f32_16x16x32_bf16 v[56:59], v[152:155], v[172:175], v[56:59]
	v_mfma_f32_16x16x32_bf16 v[56:59], v[168:171], v[180:183], v[56:59]
	v_mfma_f32_16x16x32_bf16 v[44:47], v[144:147], v[176:179], v[44:47]
	v_mfma_f32_16x16x32_bf16 v[44:47], v[148:151], v[184:187], v[44:47]
	v_mfma_f32_16x16x32_bf16 v[40:43], v[152:155], v[176:179], v[40:43]
	v_mfma_f32_16x16x32_bf16 v[40:43], v[168:171], v[184:187], v[40:43]
	v_mfma_f32_16x16x32_bf16 v[28:31], v[144:147], v[208:211], v[28:31]
	v_mfma_f32_16x16x32_bf16 v[28:31], v[148:151], v[216:219], v[28:31]
	v_mfma_f32_16x16x32_bf16 v[24:27], v[152:155], v[208:211], v[24:27]
	v_mfma_f32_16x16x32_bf16 v[24:27], v[168:171], v[216:219], v[24:27]
	v_mfma_f32_16x16x32_bf16 v[12:15], v[144:147], v[212:215], v[12:15]
	v_mfma_f32_16x16x32_bf16 v[12:15], v[148:151], v[220:223], v[12:15]
	v_mfma_f32_16x16x32_bf16 v[8:11], v[152:155], v[212:215], v[8:11]
	v_mfma_f32_16x16x32_bf16 v[8:11], v[168:171], v[220:223], v[8:11]
	s_setprio 0
	s_barrier
	s_add_i32 s62, s62, 2
	s_add_u32 s42, s42, 0x100
	s_addc_u32 s43, s43, 0
	s_add_u32 s60, s60, 0x100
	s_addc_u32 s61, s61, 0
	s_cmp_gt_u32 s62, 61
	s_cbranch_scc0 .LBB0_846
	s_and_b64 vcc, exec, s[20:21]
	s_cbranch_vccz .LBB0_849
	s_barrier

; #define PG8_STAGE(bufoff, gbase, voff) do { _Pragma("unroll") for (int _i = 0; _i < 2; ++_i) \
;         __builtin_amdgcn_global_load_lds((const unsigned*)((const char*)(gbase) + (voff)[_i]), (LAS unsigned*)(lds + (bufoff) + ldsw + _i * 8192), 16, 0, 0); } while (0)
; #define PG8_LDA(dst, b, h) do { _Pragma("unroll") for (int m = 0; m < 4; ++m) _Pragma("unroll") for (int k = 0; k < 2; ++k) dst[m][k] = *(const LAS bf16x8*)(lds + PG8_SA(b, h) + aoffk[k] + m * 2048); } while (0)
; template <class Epi, class Sched, class GemmT>
; __device__ __forceinline__ void gemm_phase(LAS unsigned char* lds, const GemmT& g, const Sched& S, const Epi& E, const int wid) {
;     ...
;             for (int t = 0; t < nt; t += 2) {
;                 const bool last = (t == nt - 2);
;                 const char* a1 = cA + (size_t)(t + 1) * kstep;
;                 const char* a2 = last ? ns.A : cA + (size_t)(t + 2) * kstep; const char* b2 = last ? ns.B : cB + (size_t)(t + 2) * kstep;
;                 const char* a3 = a2 + kstep; const char* b3 = b2 + kstep;
;                 unsigned vA2[2], vB2[2];
; #pragma unroll
;                 for (int i = 0; i < 2; ++i) { vA2[i] = last ? nvA[i] : voffA[i]; vB2[i] = last ? nvB[i] : voffB[i]; }
;                 const size_t hA2 = last ? nhA : hstepA, hB2 = last ? nhB : hstepB;
;                 PG8_LDB(B0, 0, 0); PG8_LDB(B1, 0, 1); PG8_SCHED; PG8_LDA(At, 0, 0); PG8_STAGE(PG8_SA(1, 1), a1 + hstepA, voffA);
;                 PG8_WAIT_V(8); PG8_WAIT_L(0); PG8_BAR; PG8_MMA(0, 0, At, B0); PG8_MMA(0, 1, At, B1); PG8_BAR; PG8_SCHED;
;                 PG8_LDA(At, 0, 1); PG8_STAGE(PG8_SB(0, 0), b2, vB2); PG8_STAGE(PG8_SB(0, 1), b2 + hB2, vB2); PG8_STAGE(PG8_SA(0, 0), a2, vA2);
;                 PG8_WAIT_V(8); PG8_WAIT_L(0); PG8_BAR; PG8_MMA(1, 0, At, B0); PG8_MMA(1, 1, At, B1); PG8_BAR; PG8_SCHED;
;                 PG8_LDB(B0, 1, 0); PG8_LDB(B1, 1, 1); PG8_SCHED; PG8_LDA(At, 1, 0); PG8_STAGE(PG8_SA(0, 1), a2 + hA2, vA2);
;                 PG8_WAIT_V(8); PG8_WAIT_L(0); PG8_BAR; PG8_MMA(0, 0, At, B0); PG8_MMA(0, 1, At, B1); PG8_BAR; PG8_SCHED;
;                 PG8_LDA(At, 1, 1); PG8_STAGE(PG8_SB(1, 0), b3, vB2); PG8_STAGE(PG8_SB(1, 1), b3 + hB2, vB2); PG8_STAGE(PG8_SA(1, 0), a3, vA2);
;                 PG8_WAIT_V(8); PG8_WAIT_L(0); PG8_BAR; PG8_MMA(1, 0, At, B0); PG8_MMA(1, 1, At, B1); PG8_BAR; PG8_SCHED;
;             }
.LBB0_936:
	ds_read_b128 v[12:15], v223
	ds_read_b128 v[132:135], v224
	ds_read_b128 v[136:139], v225
	ds_read_b128 v[140:143], v226
	ds_read_b128 v[144:147], v227
	ds_read_b128 v[148:151], v229
	ds_read_b128 v[152:155], v230
	ds_read_b128 v[156:159], v231
	s_add_u32 s66, s64, 0xfff00080
	s_addc_u32 s67, s65, -1
	s_cmp_eq_u32 s81, 60
	s_cselect_b32 s71, s57, s67
	s_cselect_b32 s70, s56, s66
	s_cselect_b32 s67, s77, s79
	s_cselect_b32 s66, s63, s78
	v_lshl_add_u64 v[204:205], s[64:65], 0, v[176:177]
	s_add_i32 m0, s14, 0xc000
	ds_read_b128 v[160:163], v232
	ds_read_b128 v[164:167], v232 offset:2048
	ds_read_b128 v[168:171], v233
	ds_read_b128 v[172:175], v233 offset:2048
	ds_read_b128 v[188:191], v232 offset:4096
	ds_read_b128 v[192:195], v232 offset:6144
	ds_read_b128 v[196:199], v233 offset:4096
	ds_read_b128 v[200:203], v233 offset:6144
	global_load_lds_dwordx4 v[204:205], off
	v_lshl_add_u64 v[204:205], s[64:65], 0, v[180:181]
	s_add_i32 m0, s14, 0xe000
	s_nop 0
	global_load_lds_dwordx4 v[204:205], off
	s_waitcnt vmcnt(8)
	s_waitcnt lgkmcnt(0)
	s_barrier
	s_setprio 3
	s_waitcnt lgkmcnt(0)
	v_mfma_f32_16x16x32_bf16 v[124:127], v[12:15], v[160:163], v[124:127]
	v_mfma_f32_16x16x32_bf16 v[124:127], v[132:135], v[168:171], v[124:127]
	v_mfma_f32_16x16x32_bf16 v[120:123], v[136:139], v[160:163], v[120:123]
	v_mfma_f32_16x16x32_bf16 v[120:123], v[140:143], v[168:171], v[120:123]
	v_mfma_f32_16x16x32_bf16 v[40:43], v[12:15], v[164:167], v[40:43]
	v_mfma_f32_16x16x32_bf16 v[40:43], v[132:135], v[172:175], v[40:43]
	v_mfma_f32_16x16x32_bf16 v[104:107], v[136:139], v[164:167], v[104:107]
	v_mfma_f32_16x16x32_bf16 v[104:107], v[140:143], v[172:175], v[104:107]
	v_mfma_f32_16x16x32_bf16 v[32:35], v[12:15], v[188:191], v[32:35]
	v_mfma_f32_16x16x32_bf16 v[32:35], v[132:135], v[196:199], v[32:35]
	v_mfma_f32_16x16x32_bf16 v[96:99], v[136:139], v[188:191], v[96:99]
	v_mfma_f32_16x16x32_bf16 v[96:99], v[140:143], v[196:199], v[96:99]
	v_mfma_f32_16x16x32_bf16 v[112:115], v[12:15], v[192:195], v[112:115]
	v_mfma_f32_16x16x32_bf16 v[112:115], v[132:135], v[200:203], v[112:115]
	v_mfma_f32_16x16x32_bf16 v[92:95], v[136:139], v[192:195], v[92:95]
	v_mfma_f32_16x16x32_bf16 v[92:95], v[140:143], v[200:203], v[92:95]
	s_setprio 0
	s_setprio 3
	v_mfma_f32_16x16x32_bf16 v[68:71], v[144:147], v[160:163], v[68:71]
	v_mfma_f32_16x16x32_bf16 v[68:71], v[148:151], v[168:171], v[68:71]
	v_mfma_f32_16x16x32_bf16 v[60:63], v[152:155], v[160:163], v[60:63]
	v_mfma_f32_16x16x32_bf16 v[60:63], v[156:159], v[168:171], v[60:63]
	v_mfma_f32_16x16x32_bf16 v[76:79], v[144:147], v[164:167], v[76:79]
	v_mfma_f32_16x16x32_bf16 v[76:79], v[148:151], v[172:175], v[76:79]
	v_mfma_f32_16x16x32_bf16 v[20:23], v[152:155], v[164:167], v[20:23]
	v_mfma_f32_16x16x32_bf16 v[20:23], v[156:159], v[172:175], v[20:23]
	v_mfma_f32_16x16x32_bf16 v[72:75], v[144:147], v[188:191], v[72:75]
	v_mfma_f32_16x16x32_bf16 v[72:75], v[148:151], v[196:199], v[72:75]
	v_mfma_f32_16x16x32_bf16 v[16:19], v[152:155], v[188:191], v[16:19]
	v_mfma_f32_16x16x32_bf16 v[16:19], v[156:159], v[196:199], v[16:19]
	v_mfma_f32_16x16x32_bf16 v[84:87], v[144:147], v[192:195], v[84:87]
	v_mfma_f32_16x16x32_bf16 v[84:87], v[148:151], v[200:203], v[84:87]
	v_mfma_f32_16x16x32_bf16 v[80:83], v[152:155], v[192:195], v[80:83]
	v_mfma_f32_16x16x32_bf16 v[80:83], v[156:159], v[200:203], v[80:83]
	s_setprio 0
	s_barrier
	s_add_i32 s80, s69, s68
	v_lshl_add_u64 v[204:205], s[66:67], 0, v[178:179]
	s_mov_b32 m0, s80
	ds_read_b128 v[160:163], v232 offset:16384
	ds_read_b128 v[164:167], v232 offset:18432
	ds_read_b128 v[168:171], v233 offset:16384
	ds_read_b128 v[172:175], v233 offset:18432
	ds_read_b128 v[188:191], v232 offset:20480
	ds_read_b128 v[192:195], v232 offset:22528
	ds_read_b128 v[196:199], v233 offset:20480
	ds_read_b128 v[200:203], v233 offset:22528
	global_load_lds_dwordx4 v[204:205], off
	s_add_i32 m0, s80, 0x2000
	s_add_u32 s82, s66, 0x100000
	v_lshl_add_u64 v[206:207], s[66:67], 0, v[182:183]
	s_addc_u32 s83, s67, 0
	s_add_i32 s80, s72, s68
	global_load_lds_dwordx4 v[206:207], off
	v_lshl_add_u64 v[240:241], s[82:83], 0, v[178:179]
	s_mov_b32 m0, s80
	v_lshl_add_u64 v[242:243], s[70:71], 0, v[180:181]
	global_load_lds_dwordx4 v[240:241], off
	v_lshl_add_u64 v[240:241], s[82:83], 0, v[182:183]
	s_add_i32 m0, s80, 0x2000
	s_nop 0
	global_load_lds_dwordx4 v[240:241], off
	v_lshl_add_u64 v[240:241], s[70:71], 0, v[176:177]
	s_mov_b32 m0, s14
	s_nop 0
	global_load_lds_dwordx4 v[240:241], off
	s_mov_b32 m0, s15
	s_nop 0
	global_load_lds_dwordx4 v[242:243], off
	s_waitcnt vmcnt(8)
	s_waitcnt lgkmcnt(0)
	s_barrier
; #define PG8_STAGE(bufoff, gbase, voff) do { _Pragma("unroll") for (int _i = 0; _i < 2; ++_i) \
;         __builtin_amdgcn_global_load_lds((const unsigned*)((const char*)(gbase) + (voff)[_i]), (LAS unsigned*)(lds + (bufoff) + ldsw + _i * 8192), 16, 0, 0); } while (0)
; #define PG8_LDA(dst, b, h) do { _Pragma("unroll") for (int m = 0; m < 4; ++m) _Pragma("unroll") for (int k = 0; k < 2; ++k) dst[m][k] = *(const LAS bf16x8*)(lds + PG8_SA(b, h) + aoffk[k] + m * 2048); } while (0)
; template <class Epi, class Sched, class GemmT>
; __device__ __forceinline__ void gemm_phase(LAS unsigned char* lds, const GemmT& g, const Sched& S, const Epi& E, const int wid) {
;     ...
;             for (int t = 0; t < nt; t += 2) {
;                 const bool last = (t == nt - 2);
;                 const char* a1 = cA + (size_t)(t + 1) * kstep;
;                 const char* a2 = last ? ns.A : cA + (size_t)(t + 2) * kstep; const char* b2 = last ? ns.B : cB + (size_t)(t + 2) * kstep;
;                 const char* a3 = a2 + kstep; const char* b3 = b2 + kstep;
;                 unsigned vA2[2], vB2[2];
; #pragma unroll
;                 for (int i = 0; i < 2; ++i) { vA2[i] = last ? nvA[i] : voffA[i]; vB2[i] = last ? nvB[i] : voffB[i]; }
;                 const size_t hA2 = last ? nhA : hstepA, hB2 = last ? nhB : hstepB;
;                 PG8_LDB(B0, 0, 0); PG8_LDB(B1, 0, 1); PG8_SCHED; PG8_LDA(At, 0, 0); PG8_STAGE(PG8_SA(1, 1), a1 + hstepA, voffA);
;                 PG8_WAIT_V(8); PG8_WAIT_L(0); PG8_BAR; PG8_MMA(0, 0, At, B0); PG8_MMA(0, 1, At, B1); PG8_BAR; PG8_SCHED;
;                 PG8_LDA(At, 0, 1); PG8_STAGE(PG8_SB(0, 0), b2, vB2); PG8_STAGE(PG8_SB(0, 1), b2 + hB2, vB2); PG8_STAGE(PG8_SA(0, 0), a2, vA2);
;                 PG8_WAIT_V(8); PG8_WAIT_L(0); PG8_BAR; PG8_MMA(1, 0, At, B0); PG8_MMA(1, 1, At, B1); PG8_BAR; PG8_SCHED;
;                 PG8_LDB(B0, 1, 0); PG8_LDB(B1, 1, 1); PG8_SCHED; PG8_LDA(At, 1, 0); PG8_STAGE(PG8_SA(0, 1), a2 + hA2, vA2);
;                 PG8_WAIT_V(8); PG8_WAIT_L(0); PG8_BAR; PG8_MMA(0, 0, At, B0); PG8_MMA(0, 1, At, B1); PG8_BAR; PG8_SCHED;
;                 PG8_LDA(At, 1, 1); PG8_STAGE(PG8_SB(1, 0), b3, vB2); PG8_STAGE(PG8_SB(1, 1), b3 + hB2, vB2); PG8_STAGE(PG8_SA(1, 0), a3, vA2);
;                 PG8_WAIT_V(8); PG8_WAIT_L(0); PG8_BAR; PG8_MMA(1, 0, At, B0); PG8_MMA(1, 1, At, B1); PG8_BAR; PG8_SCHED;
;             }
	s_setprio 3
	s_waitcnt lgkmcnt(0)
	v_mfma_f32_16x16x32_bf16 v[56:59], v[12:15], v[160:163], v[56:59]
	v_mfma_f32_16x16x32_bf16 v[56:59], v[132:135], v[168:171], v[56:59]
	v_mfma_f32_16x16x32_bf16 v[108:111], v[136:139], v[160:163], v[108:111]
	v_mfma_f32_16x16x32_bf16 v[108:111], v[140:143], v[168:171], v[108:111]
	v_mfma_f32_16x16x32_bf16 v[36:39], v[12:15], v[164:167], v[36:39]
	v_mfma_f32_16x16x32_bf16 v[36:39], v[132:135], v[172:175], v[36:39]
	v_mfma_f32_16x16x32_bf16 v[100:103], v[136:139], v[164:167], v[100:103]
	v_mfma_f32_16x16x32_bf16 v[100:103], v[140:143], v[172:175], v[100:103]
	v_mfma_f32_16x16x32_bf16 v[28:31], v[12:15], v[188:191], v[28:31]
	v_mfma_f32_16x16x32_bf16 v[28:31], v[132:135], v[196:199], v[28:31]
	v_mfma_f32_16x16x32_bf16 v[88:91], v[136:139], v[188:191], v[88:91]
	v_mfma_f32_16x16x32_bf16 v[88:91], v[140:143], v[196:199], v[88:91]
	v_mfma_f32_16x16x32_bf16 v[24:27], v[136:139], v[192:195], v[24:27]
	v_mfma_f32_16x16x32_bf16 v[24:27], v[140:143], v[200:203], v[24:27]
	v_mfma_f32_16x16x32_bf16 v[12:15], v[12:15], v[192:195], v[64:67]
	v_mfma_f32_16x16x32_bf16 v[12:15], v[132:135], v[200:203], v[12:15]
	s_setprio 0
	s_setprio 3
	v_mfma_f32_16x16x32_bf16 v[64:67], v[144:147], v[192:195], v[116:119]
	v_mfma_f32_16x16x32_bf16 v[116:119], v[148:151], v[200:203], v[64:67]
	v_mfma_f32_16x16x32_bf16 v[44:47], v[144:147], v[160:163], v[44:47]
	v_mfma_f32_16x16x32_bf16 v[44:47], v[148:151], v[168:171], v[44:47]
	v_mfma_f32_16x16x32_bf16 v[0:3], v[152:155], v[160:163], v[0:3]
	v_mfma_f32_16x16x32_bf16 v[0:3], v[156:159], v[168:171], v[0:3]
	v_mfma_f32_16x16x32_bf16 v[48:51], v[144:147], v[164:167], v[48:51]
	v_mfma_f32_16x16x32_bf16 v[48:51], v[148:151], v[172:175], v[48:51]
	v_mfma_f32_16x16x32_bf16 v[4:7], v[152:155], v[164:167], v[4:7]
	v_mfma_f32_16x16x32_bf16 v[4:7], v[156:159], v[172:175], v[4:7]
	v_mfma_f32_16x16x32_bf16 v[52:55], v[144:147], v[188:191], v[52:55]
	v_mfma_f32_16x16x32_bf16 v[52:55], v[148:151], v[196:199], v[52:55]
	v_mfma_f32_16x16x32_bf16 v[8:11], v[152:155], v[188:191], v[8:11]
	v_mfma_f32_16x16x32_bf16 v[8:11], v[156:159], v[196:199], v[8:11]
	v_mfma_f32_16x16x32_bf16 v[64:67], v[152:155], v[192:195], v[128:131]
	v_mfma_f32_16x16x32_bf16 v[128:131], v[156:159], v[200:203], v[64:67]
	s_setprio 0
	s_barrier
	s_add_i32 s80, 0, 0x18000
	s_add_i32 s82, 0, 0x1c000
	v_add_u32_e32 v64, s80, v210
	v_add_u32_e32 v132, s80, v211
	v_add_u32_e32 v144, s82, v210
	v_add_u32_e32 v148, s82, v211
	ds_read_b128 v[64:67], v64
	ds_read_b128 v[132:135], v132
	ds_read_b128 v[136:139], v234
	ds_read_b128 v[140:143], v235
	ds_read_b128 v[144:147], v144
	ds_read_b128 v[148:151], v148
	ds_read_b128 v[152:155], v236
	ds_read_b128 v[156:159], v237
	s_add_u32 s70, s70, 0x100000
	s_addc_u32 s71, s71, 0
	s_mov_b32 m0, s23
	v_lshl_add_u64 v[244:245], s[70:71], 0, v[176:177]
	ds_read_b128 v[160:163], v232 offset:32768
	ds_read_b128 v[164:167], v232 offset:34816
	ds_read_b128 v[168:171], v233 offset:32768
	ds_read_b128 v[172:175], v233 offset:34816
	ds_read_b128 v[188:191], v232 offset:36864
	ds_read_b128 v[192:195], v232 offset:38912
	ds_read_b128 v[196:199], v233 offset:36864
	ds_read_b128 v[200:203], v233 offset:38912
	global_load_lds_dwordx4 v[244:245], off
	v_lshl_add_u64 v[244:245], s[70:71], 0, v[180:181]
	s_mov_b32 m0, s34
	s_nop 0
	global_load_lds_dwordx4 v[244:245], off
	s_waitcnt vmcnt(8)
	s_waitcnt lgkmcnt(0)
	s_barrier
	s_setprio 3
	s_waitcnt lgkmcnt(0)
	v_mfma_f32_16x16x32_bf16 v[124:127], v[64:67], v[160:163], v[124:127]
	v_mfma_f32_16x16x32_bf16 v[124:127], v[132:135], v[168:171], v[124:127]
	v_mfma_f32_16x16x32_bf16 v[120:123], v[136:139], v[160:163], v[120:123]
	v_mfma_f32_16x16x32_bf16 v[120:123], v[140:143], v[168:171], v[120:123]
	v_mfma_f32_16x16x32_bf16 v[40:43], v[64:67], v[164:167], v[40:43]
	v_mfma_f32_16x16x32_bf16 v[40:43], v[132:135], v[172:175], v[40:43]
	v_mfma_f32_16x16x32_bf16 v[104:107], v[136:139], v[164:167], v[104:107]
	v_mfma_f32_16x16x32_bf16 v[104:107], v[140:143], v[172:175], v[104:107]
	v_mfma_f32_16x16x32_bf16 v[32:35], v[64:67], v[188:191], v[32:35]
	v_mfma_f32_16x16x32_bf16 v[32:35], v[132:135], v[196:199], v[32:35]
	v_mfma_f32_16x16x32_bf16 v[96:99], v[136:139], v[188:191], v[96:99]
	v_mfma_f32_16x16x32_bf16 v[96:99], v[140:143], v[196:199], v[96:99]
	v_mfma_f32_16x16x32_bf16 v[112:115], v[64:67], v[192:195], v[112:115]
	v_mfma_f32_16x16x32_bf16 v[112:115], v[132:135], v[200:203], v[112:115]
	v_mfma_f32_16x16x32_bf16 v[92:95], v[136:139], v[192:195], v[92:95]
	v_mfma_f32_16x16x32_bf16 v[92:95], v[140:143], v[200:203], v[92:95]
	s_setprio 0
	s_setprio 3
	v_mfma_f32_16x16x32_bf16 v[68:71], v[144:147], v[160:163], v[68:71]
	v_mfma_f32_16x16x32_bf16 v[68:71], v[148:151], v[168:171], v[68:71]
	v_mfma_f32_16x16x32_bf16 v[60:63], v[152:155], v[160:163], v[60:63]
	v_mfma_f32_16x16x32_bf16 v[60:63], v[156:159], v[168:171], v[60:63]
	v_mfma_f32_16x16x32_bf16 v[76:79], v[144:147], v[164:167], v[76:79]
	v_mfma_f32_16x16x32_bf16 v[76:79], v[148:151], v[172:175], v[76:79]
	v_mfma_f32_16x16x32_bf16 v[20:23], v[152:155], v[164:167], v[20:23]
	v_mfma_f32_16x16x32_bf16 v[20:23], v[156:159], v[172:175], v[20:23]
	v_mfma_f32_16x16x32_bf16 v[72:75], v[144:147], v[188:191], v[72:75]
	v_mfma_f32_16x16x32_bf16 v[72:75], v[148:151], v[196:199], v[72:75]
	v_mfma_f32_16x16x32_bf16 v[16:19], v[152:155], v[188:191], v[16:19]
	v_mfma_f32_16x16x32_bf16 v[16:19], v[156:159], v[196:199], v[16:19]
	v_mfma_f32_16x16x32_bf16 v[84:87], v[144:147], v[192:195], v[84:87]
	v_mfma_f32_16x16x32_bf16 v[84:87], v[148:151], v[200:203], v[84:87]
	v_mfma_f32_16x16x32_bf16 v[80:83], v[152:155], v[192:195], v[80:83]
	v_mfma_f32_16x16x32_bf16 v[80:83], v[156:159], v[200:203], v[80:83]
	s_setprio 0
	s_barrier
; #define PG8_STAGE(bufoff, gbase, voff) do { _Pragma("unroll") for (int _i = 0; _i < 2; ++_i) \
;         __builtin_amdgcn_global_load_lds((const unsigned*)((const char*)(gbase) + (voff)[_i]), (LAS unsigned*)(lds + (bufoff) + ldsw + _i * 8192), 16, 0, 0); } while (0)
; #define PG8_LDA(dst, b, h) do { _Pragma("unroll") for (int m = 0; m < 4; ++m) _Pragma("unroll") for (int k = 0; k < 2; ++k) dst[m][k] = *(const LAS bf16x8*)(lds + PG8_SA(b, h) + aoffk[k] + m * 2048); } while (0)
; template <class Epi, class Sched, class GemmT>
; __device__ __forceinline__ void gemm_phase(LAS unsigned char* lds, const GemmT& g, const Sched& S, const Epi& E, const int wid) {
;     ...
;             for (int t = 0; t < nt; t += 2) {
;                 const bool last = (t == nt - 2);
;                 const char* a1 = cA + (size_t)(t + 1) * kstep;
;                 const char* a2 = last ? ns.A : cA + (size_t)(t + 2) * kstep; const char* b2 = last ? ns.B : cB + (size_t)(t + 2) * kstep;
;                 const char* a3 = a2 + kstep; const char* b3 = b2 + kstep;
;                 unsigned vA2[2], vB2[2];
; #pragma unroll
;                 for (int i = 0; i < 2; ++i) { vA2[i] = last ? nvA[i] : voffA[i]; vB2[i] = last ? nvB[i] : voffB[i]; }
;                 const size_t hA2 = last ? nhA : hstepA, hB2 = last ? nhB : hstepB;
;                 PG8_LDB(B0, 0, 0); PG8_LDB(B1, 0, 1); PG8_SCHED; PG8_LDA(At, 0, 0); PG8_STAGE(PG8_SA(1, 1), a1 + hstepA, voffA);
;                 PG8_WAIT_V(8); PG8_WAIT_L(0); PG8_BAR; PG8_MMA(0, 0, At, B0); PG8_MMA(0, 1, At, B1); PG8_BAR; PG8_SCHED;
;                 PG8_LDA(At, 0, 1); PG8_STAGE(PG8_SB(0, 0), b2, vB2); PG8_STAGE(PG8_SB(0, 1), b2 + hB2, vB2); PG8_STAGE(PG8_SA(0, 0), a2, vA2);
;                 PG8_WAIT_V(8); PG8_WAIT_L(0); PG8_BAR; PG8_MMA(1, 0, At, B0); PG8_MMA(1, 1, At, B1); PG8_BAR; PG8_SCHED;
;                 PG8_LDB(B0, 1, 0); PG8_LDB(B1, 1, 1); PG8_SCHED; PG8_LDA(At, 1, 0); PG8_STAGE(PG8_SA(0, 1), a2 + hA2, vA2);
;                 PG8_WAIT_V(8); PG8_WAIT_L(0); PG8_BAR; PG8_MMA(0, 0, At, B0); PG8_MMA(0, 1, At, B1); PG8_BAR; PG8_SCHED;
;                 PG8_LDA(At, 1, 1); PG8_STAGE(PG8_SB(1, 0), b3, vB2); PG8_STAGE(PG8_SB(1, 1), b3 + hB2, vB2); PG8_STAGE(PG8_SA(1, 0), a3, vA2);
;                 PG8_WAIT_V(8); PG8_WAIT_L(0); PG8_BAR; PG8_MMA(1, 0, At, B0); PG8_MMA(1, 1, At, B1); PG8_BAR; PG8_SCHED;
;             }
	s_add_i32 s70, s80, s68
	v_lshl_add_u64 v[204:205], v[204:205], 0, s[38:39]
	s_mov_b32 m0, s70
	ds_read_b128 v[160:163], v232 offset:49152
	ds_read_b128 v[164:167], v232 offset:51200
	ds_read_b128 v[168:171], v233 offset:49152
	ds_read_b128 v[172:175], v233 offset:51200
	ds_read_b128 v[188:191], v232 offset:53248
	ds_read_b128 v[192:195], v232 offset:55296
	ds_read_b128 v[196:199], v233 offset:53248
	ds_read_b128 v[200:203], v233 offset:55296
	global_load_lds_dwordx4 v[204:205], off
	s_add_i32 m0, s70, 0x2000
	s_add_u32 s66, s66, 0x100080
	v_lshl_add_u64 v[204:205], v[206:207], 0, s[38:39]
	s_addc_u32 s67, s67, 0
	s_add_i32 s70, s82, s68
	global_load_lds_dwordx4 v[204:205], off
	v_lshl_add_u64 v[204:205], s[66:67], 0, v[178:179]
	s_mov_b32 m0, s70
	s_nop 0
	global_load_lds_dwordx4 v[204:205], off
	v_lshl_add_u64 v[204:205], s[66:67], 0, v[182:183]
	s_add_i32 m0, s70, 0x2000
	s_nop 0
	global_load_lds_dwordx4 v[204:205], off
	v_lshl_add_u64 v[204:205], v[240:241], 0, s[38:39]
	s_mov_b32 m0, s54
	s_nop 0
	global_load_lds_dwordx4 v[204:205], off
	v_lshl_add_u64 v[204:205], v[242:243], 0, s[38:39]
	s_mov_b32 m0, s55
	s_nop 0
	global_load_lds_dwordx4 v[204:205], off
	s_waitcnt vmcnt(8)
	s_waitcnt lgkmcnt(0)
	s_barrier
	s_setprio 3
	s_waitcnt lgkmcnt(0)
	v_mfma_f32_16x16x32_bf16 v[12:15], v[64:67], v[192:195], v[12:15]
	v_mfma_f32_16x16x32_bf16 v[56:59], v[64:67], v[160:163], v[56:59]
	v_mfma_f32_16x16x32_bf16 v[56:59], v[132:135], v[168:171], v[56:59]
	v_mfma_f32_16x16x32_bf16 v[108:111], v[136:139], v[160:163], v[108:111]
	v_mfma_f32_16x16x32_bf16 v[108:111], v[140:143], v[168:171], v[108:111]
	v_mfma_f32_16x16x32_bf16 v[36:39], v[64:67], v[164:167], v[36:39]
	v_mfma_f32_16x16x32_bf16 v[36:39], v[132:135], v[172:175], v[36:39]
	v_mfma_f32_16x16x32_bf16 v[100:103], v[136:139], v[164:167], v[100:103]
	v_mfma_f32_16x16x32_bf16 v[100:103], v[140:143], v[172:175], v[100:103]
	v_mfma_f32_16x16x32_bf16 v[28:31], v[64:67], v[188:191], v[28:31]
	v_mfma_f32_16x16x32_bf16 v[28:31], v[132:135], v[196:199], v[28:31]
	v_mfma_f32_16x16x32_bf16 v[88:91], v[136:139], v[188:191], v[88:91]
	v_mfma_f32_16x16x32_bf16 v[88:91], v[140:143], v[196:199], v[88:91]
	v_mfma_f32_16x16x32_bf16 v[64:67], v[132:135], v[200:203], v[12:15]
	v_mfma_f32_16x16x32_bf16 v[12:15], v[136:139], v[192:195], v[24:27]
	v_mfma_f32_16x16x32_bf16 v[24:27], v[140:143], v[200:203], v[12:15]
	s_setprio 0
	s_setprio 3
	v_mfma_f32_16x16x32_bf16 v[12:15], v[144:147], v[160:163], v[44:47]
	v_mfma_f32_16x16x32_bf16 v[44:47], v[148:151], v[168:171], v[12:15]
	v_mfma_f32_16x16x32_bf16 v[0:3], v[152:155], v[160:163], v[0:3]
	v_mfma_f32_16x16x32_bf16 v[0:3], v[156:159], v[168:171], v[0:3]
	v_mfma_f32_16x16x32_bf16 v[4:7], v[152:155], v[164:167], v[4:7]
	v_mfma_f32_16x16x32_bf16 v[4:7], v[156:159], v[172:175], v[4:7]
	v_mfma_f32_16x16x32_bf16 v[12:15], v[144:147], v[164:167], v[48:51]
	v_mfma_f32_16x16x32_bf16 v[48:51], v[148:151], v[172:175], v[12:15]
	v_mfma_f32_16x16x32_bf16 v[8:11], v[152:155], v[188:191], v[8:11]
	v_mfma_f32_16x16x32_bf16 v[8:11], v[156:159], v[196:199], v[8:11]
	v_mfma_f32_16x16x32_bf16 v[12:15], v[144:147], v[188:191], v[52:55]
	v_mfma_f32_16x16x32_bf16 v[52:55], v[148:151], v[196:199], v[12:15]
	v_mfma_f32_16x16x32_bf16 v[12:15], v[144:147], v[192:195], v[116:119]
	v_mfma_f32_16x16x32_bf16 v[116:119], v[148:151], v[200:203], v[12:15]
	v_mfma_f32_16x16x32_bf16 v[12:15], v[152:155], v[192:195], v[128:131]
	v_mfma_f32_16x16x32_bf16 v[128:131], v[156:159], v[200:203], v[12:15]
	s_setprio 0
	s_barrier
	s_add_i32 s81, s81, 2
	s_add_u32 s64, s64, 0x100
	s_addc_u32 s65, s65, 0
	s_add_u32 s78, s78, 0x100
	s_addc_u32 s79, s79, 0
	s_cmp_gt_u32 s81, 61
	s_cbranch_scc0 .LBB0_936
	s_and_b64 vcc, exec, s[40:41]
	s_cbranch_vccz .LBB0_939
	s_barrier

; #define PG8_STAGE(bufoff, gbase, voff) do { _Pragma("unroll") for (int _i = 0; _i < 2; ++_i) \
;         __builtin_amdgcn_global_load_lds((const unsigned*)((const char*)(gbase) + (voff)[_i]), (LAS unsigned*)(lds + (bufoff) + ldsw + _i * 8192), 16, 0, 0); } while (0)
; #define PG8_LDA(dst, b, h) do { _Pragma("unroll") for (int m = 0; m < 4; ++m) _Pragma("unroll") for (int k = 0; k < 2; ++k) dst[m][k] = *(const LAS bf16x8*)(lds + PG8_SA(b, h) + aoffk[k] + m * 2048); } while (0)
; template <class Epi, class Sched, class GemmT>
; __device__ __forceinline__ void gemm_phase(LAS unsigned char* lds, const GemmT& g, const Sched& S, const Epi& E, const int wid) {
;     ...
;             for (int t = 0; t < nt; t += 2) {
;                 const bool last = (t == nt - 2);
;                 const char* a1 = cA + (size_t)(t + 1) * kstep;
;                 const char* a2 = last ? ns.A : cA + (size_t)(t + 2) * kstep; const char* b2 = last ? ns.B : cB + (size_t)(t + 2) * kstep;
;                 const char* a3 = a2 + kstep; const char* b3 = b2 + kstep;
;                 unsigned vA2[2], vB2[2];
; #pragma unroll
;                 for (int i = 0; i < 2; ++i) { vA2[i] = last ? nvA[i] : voffA[i]; vB2[i] = last ? nvB[i] : voffB[i]; }
;                 const size_t hA2 = last ? nhA : hstepA, hB2 = last ? nhB : hstepB;
;                 PG8_LDB(B0, 0, 0); PG8_LDB(B1, 0, 1); PG8_SCHED; PG8_LDA(At, 0, 0); PG8_STAGE(PG8_SA(1, 1), a1 + hstepA, voffA);
;                 PG8_WAIT_V(8); PG8_WAIT_L(0); PG8_BAR; PG8_MMA(0, 0, At, B0); PG8_MMA(0, 1, At, B1); PG8_BAR; PG8_SCHED;
;                 PG8_LDA(At, 0, 1); PG8_STAGE(PG8_SB(0, 0), b2, vB2); PG8_STAGE(PG8_SB(0, 1), b2 + hB2, vB2); PG8_STAGE(PG8_SA(0, 0), a2, vA2);
;                 PG8_WAIT_V(8); PG8_WAIT_L(0); PG8_BAR; PG8_MMA(1, 0, At, B0); PG8_MMA(1, 1, At, B1); PG8_BAR; PG8_SCHED;
;                 PG8_LDB(B0, 1, 0); PG8_LDB(B1, 1, 1); PG8_SCHED; PG8_LDA(At, 1, 0); PG8_STAGE(PG8_SA(0, 1), a2 + hA2, vA2);
;                 PG8_WAIT_V(8); PG8_WAIT_L(0); PG8_BAR; PG8_MMA(0, 0, At, B0); PG8_MMA(0, 1, At, B1); PG8_BAR; PG8_SCHED;
;                 PG8_LDA(At, 1, 1); PG8_STAGE(PG8_SB(1, 0), b3, vB2); PG8_STAGE(PG8_SB(1, 1), b3 + hB2, vB2); PG8_STAGE(PG8_SA(1, 0), a3, vA2);
;                 PG8_WAIT_V(8); PG8_WAIT_L(0); PG8_BAR; PG8_MMA(1, 0, At, B0); PG8_MMA(1, 1, At, B1); PG8_BAR; PG8_SCHED;
;             }
.LBB0_1096:
	ds_read_b128 v[128:131], v188
	ds_read_b128 v[132:135], v189
	ds_read_b128 v[136:139], v190
	ds_read_b128 v[140:143], v191
	ds_read_b128 v[144:147], v192
	ds_read_b128 v[148:151], v193
	ds_read_b128 v[152:155], v194
	ds_read_b128 v[156:159], v195
	s_add_u32 s24, s22, 0xffd50080
	s_addc_u32 s25, s23, -1
	s_cmpk_eq_i32 s56, 0xa8
	s_cselect_b32 s27, s19, s25
	s_cselect_b32 s26, s18, s24
	s_cselect_b32 s25, s53, s55
	s_cselect_b32 s24, s52, s54
	v_lshl_add_u64 v[222:223], s[22:23], 0, v[168:169]
	s_add_i32 m0, s34, 0xc000
	ds_read_b128 v[160:163], v196
	ds_read_b128 v[164:167], v196 offset:2048
	ds_read_b128 v[180:183], v197
	ds_read_b128 v[202:205], v197 offset:2048
	ds_read_b128 v[206:209], v196 offset:4096
	ds_read_b128 v[210:213], v196 offset:6144
	ds_read_b128 v[214:217], v197 offset:4096
	ds_read_b128 v[218:221], v197 offset:6144
	global_load_lds_dwordx4 v[222:223], off
	v_lshl_add_u64 v[222:223], s[22:23], 0, v[172:173]
	s_add_i32 m0, s34, 0xe000
	s_nop 0
	global_load_lds_dwordx4 v[222:223], off
	s_waitcnt vmcnt(8)
	s_waitcnt lgkmcnt(0)
	s_barrier
	s_setprio 3
	s_waitcnt lgkmcnt(0)
	v_mfma_f32_16x16x32_bf16 v[124:127], v[128:131], v[160:163], v[124:127]
	v_mfma_f32_16x16x32_bf16 v[124:127], v[132:135], v[180:183], v[124:127]
	v_mfma_f32_16x16x32_bf16 v[120:123], v[136:139], v[160:163], v[120:123]
	v_mfma_f32_16x16x32_bf16 v[120:123], v[140:143], v[180:183], v[120:123]
	v_mfma_f32_16x16x32_bf16 v[112:115], v[128:131], v[164:167], v[112:115]
	v_mfma_f32_16x16x32_bf16 v[112:115], v[132:135], v[202:205], v[112:115]
	v_mfma_f32_16x16x32_bf16 v[104:107], v[136:139], v[164:167], v[104:107]
	v_mfma_f32_16x16x32_bf16 v[104:107], v[140:143], v[202:205], v[104:107]
	v_mfma_f32_16x16x32_bf16 v[96:99], v[128:131], v[206:209], v[96:99]
	v_mfma_f32_16x16x32_bf16 v[96:99], v[132:135], v[214:217], v[96:99]
	v_mfma_f32_16x16x32_bf16 v[88:91], v[136:139], v[206:209], v[88:91]
	v_mfma_f32_16x16x32_bf16 v[88:91], v[140:143], v[214:217], v[88:91]
	v_mfma_f32_16x16x32_bf16 v[80:83], v[128:131], v[210:213], v[80:83]
	v_mfma_f32_16x16x32_bf16 v[80:83], v[132:135], v[218:221], v[80:83]
	v_mfma_f32_16x16x32_bf16 v[72:75], v[136:139], v[210:213], v[72:75]
	v_mfma_f32_16x16x32_bf16 v[72:75], v[140:143], v[218:221], v[72:75]
	s_setprio 0
	s_setprio 3
	v_mfma_f32_16x16x32_bf16 v[116:119], v[144:147], v[160:163], v[116:119]
	v_mfma_f32_16x16x32_bf16 v[116:119], v[148:151], v[180:183], v[116:119]
	v_mfma_f32_16x16x32_bf16 v[108:111], v[152:155], v[160:163], v[108:111]
	v_mfma_f32_16x16x32_bf16 v[108:111], v[156:159], v[180:183], v[108:111]
	v_mfma_f32_16x16x32_bf16 v[100:103], v[144:147], v[164:167], v[100:103]
	v_mfma_f32_16x16x32_bf16 v[100:103], v[148:151], v[202:205], v[100:103]
	v_mfma_f32_16x16x32_bf16 v[92:95], v[152:155], v[164:167], v[92:95]
	v_mfma_f32_16x16x32_bf16 v[92:95], v[156:159], v[202:205], v[92:95]
	v_mfma_f32_16x16x32_bf16 v[84:87], v[144:147], v[206:209], v[84:87]
	v_mfma_f32_16x16x32_bf16 v[84:87], v[148:151], v[214:217], v[84:87]
	v_mfma_f32_16x16x32_bf16 v[76:79], v[152:155], v[206:209], v[76:79]
	v_mfma_f32_16x16x32_bf16 v[76:79], v[156:159], v[214:217], v[76:79]
	v_mfma_f32_16x16x32_bf16 v[68:71], v[144:147], v[210:213], v[68:71]
	v_mfma_f32_16x16x32_bf16 v[68:71], v[148:151], v[218:221], v[68:71]
	v_mfma_f32_16x16x32_bf16 v[60:63], v[152:155], v[210:213], v[60:63]
	v_mfma_f32_16x16x32_bf16 v[60:63], v[156:159], v[218:221], v[60:63]
	s_setprio 0
	s_barrier
	s_add_i32 s57, s41, s68
	v_lshl_add_u64 v[222:223], s[24:25], 0, v[170:171]
	s_mov_b32 m0, s57
	ds_read_b128 v[160:163], v196 offset:16384
	ds_read_b128 v[164:167], v196 offset:18432
	ds_read_b128 v[180:183], v197 offset:16384
	ds_read_b128 v[202:205], v197 offset:18432
	ds_read_b128 v[206:209], v196 offset:20480
	ds_read_b128 v[210:213], v196 offset:22528
	ds_read_b128 v[214:217], v197 offset:20480
	ds_read_b128 v[218:221], v197 offset:22528
	global_load_lds_dwordx4 v[222:223], off
	s_add_i32 m0, s57, 0x2000
	s_add_u32 s58, s24, 0x2b0000
	v_lshl_add_u64 v[224:225], s[24:25], 0, v[174:175]
	s_addc_u32 s59, s25, 0
	s_add_i32 s57, s42, s68
	global_load_lds_dwordx4 v[224:225], off
	v_lshl_add_u64 v[226:227], s[58:59], 0, v[170:171]
	s_mov_b32 m0, s57
	v_lshl_add_u64 v[228:229], s[26:27], 0, v[172:173]
	global_load_lds_dwordx4 v[226:227], off
	v_lshl_add_u64 v[226:227], s[58:59], 0, v[174:175]
	s_add_i32 m0, s57, 0x2000
	s_nop 0
	global_load_lds_dwordx4 v[226:227], off
	v_lshl_add_u64 v[226:227], s[26:27], 0, v[168:169]
	s_mov_b32 m0, s34
	s_nop 0
	global_load_lds_dwordx4 v[226:227], off
	s_mov_b32 m0, s35
	s_nop 0
	global_load_lds_dwordx4 v[228:229], off
	s_waitcnt vmcnt(8)
	s_waitcnt lgkmcnt(0)
	s_barrier
; #define PG8_STAGE(bufoff, gbase, voff) do { _Pragma("unroll") for (int _i = 0; _i < 2; ++_i) \
;         __builtin_amdgcn_global_load_lds((const unsigned*)((const char*)(gbase) + (voff)[_i]), (LAS unsigned*)(lds + (bufoff) + ldsw + _i * 8192), 16, 0, 0); } while (0)
; #define PG8_LDA(dst, b, h) do { _Pragma("unroll") for (int m = 0; m < 4; ++m) _Pragma("unroll") for (int k = 0; k < 2; ++k) dst[m][k] = *(const LAS bf16x8*)(lds + PG8_SA(b, h) + aoffk[k] + m * 2048); } while (0)
; template <class Epi, class Sched, class GemmT>
; __device__ __forceinline__ void gemm_phase(LAS unsigned char* lds, const GemmT& g, const Sched& S, const Epi& E, const int wid) {
;     ...
;             for (int t = 0; t < nt; t += 2) {
;                 const bool last = (t == nt - 2);
;                 const char* a1 = cA + (size_t)(t + 1) * kstep;
;                 const char* a2 = last ? ns.A : cA + (size_t)(t + 2) * kstep; const char* b2 = last ? ns.B : cB + (size_t)(t + 2) * kstep;
;                 const char* a3 = a2 + kstep; const char* b3 = b2 + kstep;
;                 unsigned vA2[2], vB2[2];
; #pragma unroll
;                 for (int i = 0; i < 2; ++i) { vA2[i] = last ? nvA[i] : voffA[i]; vB2[i] = last ? nvB[i] : voffB[i]; }
;                 const size_t hA2 = last ? nhA : hstepA, hB2 = last ? nhB : hstepB;
;                 PG8_LDB(B0, 0, 0); PG8_LDB(B1, 0, 1); PG8_SCHED; PG8_LDA(At, 0, 0); PG8_STAGE(PG8_SA(1, 1), a1 + hstepA, voffA);
;                 PG8_WAIT_V(8); PG8_WAIT_L(0); PG8_BAR; PG8_MMA(0, 0, At, B0); PG8_MMA(0, 1, At, B1); PG8_BAR; PG8_SCHED;
;                 PG8_LDA(At, 0, 1); PG8_STAGE(PG8_SB(0, 0), b2, vB2); PG8_STAGE(PG8_SB(0, 1), b2 + hB2, vB2); PG8_STAGE(PG8_SA(0, 0), a2, vA2);
;                 PG8_WAIT_V(8); PG8_WAIT_L(0); PG8_BAR; PG8_MMA(1, 0, At, B0); PG8_MMA(1, 1, At, B1); PG8_BAR; PG8_SCHED;
;                 PG8_LDB(B0, 1, 0); PG8_LDB(B1, 1, 1); PG8_SCHED; PG8_LDA(At, 1, 0); PG8_STAGE(PG8_SA(0, 1), a2 + hA2, vA2);
;                 PG8_WAIT_V(8); PG8_WAIT_L(0); PG8_BAR; PG8_MMA(0, 0, At, B0); PG8_MMA(0, 1, At, B1); PG8_BAR; PG8_SCHED;
;                 PG8_LDA(At, 1, 1); PG8_STAGE(PG8_SB(1, 0), b3, vB2); PG8_STAGE(PG8_SB(1, 1), b3 + hB2, vB2); PG8_STAGE(PG8_SA(1, 0), a3, vA2);
;                 PG8_WAIT_V(8); PG8_WAIT_L(0); PG8_BAR; PG8_MMA(1, 0, At, B0); PG8_MMA(1, 1, At, B1); PG8_BAR; PG8_SCHED;
;             }
	s_setprio 3
	s_waitcnt lgkmcnt(0)
	v_mfma_f32_16x16x32_bf16 v[52:55], v[128:131], v[160:163], v[52:55]
	v_mfma_f32_16x16x32_bf16 v[52:55], v[132:135], v[180:183], v[52:55]
	v_mfma_f32_16x16x32_bf16 v[48:51], v[136:139], v[160:163], v[48:51]
	v_mfma_f32_16x16x32_bf16 v[48:51], v[140:143], v[180:183], v[48:51]
	v_mfma_f32_16x16x32_bf16 v[36:39], v[128:131], v[164:167], v[36:39]
	v_mfma_f32_16x16x32_bf16 v[36:39], v[132:135], v[202:205], v[36:39]
	v_mfma_f32_16x16x32_bf16 v[32:35], v[136:139], v[164:167], v[32:35]
	v_mfma_f32_16x16x32_bf16 v[32:35], v[140:143], v[202:205], v[32:35]
	v_mfma_f32_16x16x32_bf16 v[20:23], v[128:131], v[206:209], v[20:23]
	v_mfma_f32_16x16x32_bf16 v[20:23], v[132:135], v[214:217], v[20:23]
	v_mfma_f32_16x16x32_bf16 v[8:11], v[136:139], v[206:209], v[8:11]
	v_mfma_f32_16x16x32_bf16 v[8:11], v[140:143], v[214:217], v[8:11]
	v_mfma_f32_16x16x32_bf16 v[4:7], v[128:131], v[210:213], v[4:7]
	v_mfma_f32_16x16x32_bf16 v[4:7], v[132:135], v[218:221], v[4:7]
	v_mfma_f32_16x16x32_bf16 v[0:3], v[136:139], v[210:213], v[0:3]
	v_mfma_f32_16x16x32_bf16 v[0:3], v[140:143], v[218:221], v[0:3]
	s_setprio 0
	s_setprio 3
	v_mfma_f32_16x16x32_bf16 v[64:67], v[144:147], v[160:163], v[64:67]
	v_mfma_f32_16x16x32_bf16 v[64:67], v[148:151], v[180:183], v[64:67]
	v_mfma_f32_16x16x32_bf16 v[56:59], v[152:155], v[160:163], v[56:59]
	v_mfma_f32_16x16x32_bf16 v[56:59], v[156:159], v[180:183], v[56:59]
	v_mfma_f32_16x16x32_bf16 v[44:47], v[144:147], v[164:167], v[44:47]
	v_mfma_f32_16x16x32_bf16 v[44:47], v[148:151], v[202:205], v[44:47]
	v_mfma_f32_16x16x32_bf16 v[40:43], v[152:155], v[164:167], v[40:43]
	v_mfma_f32_16x16x32_bf16 v[40:43], v[156:159], v[202:205], v[40:43]
	v_mfma_f32_16x16x32_bf16 v[28:31], v[144:147], v[206:209], v[28:31]
	v_mfma_f32_16x16x32_bf16 v[28:31], v[148:151], v[214:217], v[28:31]
	v_mfma_f32_16x16x32_bf16 v[24:27], v[152:155], v[206:209], v[24:27]
	v_mfma_f32_16x16x32_bf16 v[24:27], v[156:159], v[214:217], v[24:27]
	v_mfma_f32_16x16x32_bf16 v[16:19], v[144:147], v[210:213], v[16:19]
	v_mfma_f32_16x16x32_bf16 v[16:19], v[148:151], v[218:221], v[16:19]
	v_mfma_f32_16x16x32_bf16 v[12:15], v[152:155], v[210:213], v[12:15]
	v_mfma_f32_16x16x32_bf16 v[12:15], v[156:159], v[218:221], v[12:15]
	s_setprio 0
	s_barrier
	s_add_i32 s57, 0, 0x18000
	s_add_i32 s58, 0, 0x1c000
	v_add_u32_e32 v128, s57, v185
	v_add_u32_e32 v132, s57, v186
	v_add_u32_e32 v144, s58, v185
	v_add_u32_e32 v148, s58, v186
	ds_read_b128 v[128:131], v128
	ds_read_b128 v[132:135], v132
	ds_read_b128 v[136:139], v198
	ds_read_b128 v[140:143], v199
	ds_read_b128 v[144:147], v144
	ds_read_b128 v[148:151], v148
	ds_read_b128 v[152:155], v200
	ds_read_b128 v[156:159], v201
	s_add_u32 s26, s26, 0x2b0000
	s_addc_u32 s27, s27, 0
	s_mov_b32 m0, s36
	v_lshl_add_u64 v[230:231], s[26:27], 0, v[168:169]
	ds_read_b128 v[160:163], v196 offset:32768
	ds_read_b128 v[164:167], v196 offset:34816
	ds_read_b128 v[180:183], v197 offset:32768
	ds_read_b128 v[202:205], v197 offset:34816
	ds_read_b128 v[206:209], v196 offset:36864
	ds_read_b128 v[210:213], v196 offset:38912
	ds_read_b128 v[214:217], v197 offset:36864
	ds_read_b128 v[218:221], v197 offset:38912
	global_load_lds_dwordx4 v[230:231], off
	v_lshl_add_u64 v[230:231], s[26:27], 0, v[172:173]
	s_mov_b32 m0, s37
	s_nop 0
	global_load_lds_dwordx4 v[230:231], off
	s_waitcnt vmcnt(8)
	s_waitcnt lgkmcnt(0)
	s_barrier
	s_setprio 3
	s_waitcnt lgkmcnt(0)
	v_mfma_f32_16x16x32_bf16 v[124:127], v[128:131], v[160:163], v[124:127]
	v_mfma_f32_16x16x32_bf16 v[124:127], v[132:135], v[180:183], v[124:127]
	v_mfma_f32_16x16x32_bf16 v[120:123], v[136:139], v[160:163], v[120:123]
	v_mfma_f32_16x16x32_bf16 v[120:123], v[140:143], v[180:183], v[120:123]
	v_mfma_f32_16x16x32_bf16 v[112:115], v[128:131], v[164:167], v[112:115]
	v_mfma_f32_16x16x32_bf16 v[112:115], v[132:135], v[202:205], v[112:115]
	v_mfma_f32_16x16x32_bf16 v[104:107], v[136:139], v[164:167], v[104:107]
	v_mfma_f32_16x16x32_bf16 v[104:107], v[140:143], v[202:205], v[104:107]
	v_mfma_f32_16x16x32_bf16 v[96:99], v[128:131], v[206:209], v[96:99]
	v_mfma_f32_16x16x32_bf16 v[96:99], v[132:135], v[214:217], v[96:99]
	v_mfma_f32_16x16x32_bf16 v[88:91], v[136:139], v[206:209], v[88:91]
	v_mfma_f32_16x16x32_bf16 v[88:91], v[140:143], v[214:217], v[88:91]
	v_mfma_f32_16x16x32_bf16 v[80:83], v[128:131], v[210:213], v[80:83]
	v_mfma_f32_16x16x32_bf16 v[80:83], v[132:135], v[218:221], v[80:83]
	v_mfma_f32_16x16x32_bf16 v[72:75], v[136:139], v[210:213], v[72:75]
	v_mfma_f32_16x16x32_bf16 v[72:75], v[140:143], v[218:221], v[72:75]
	s_setprio 0
	s_setprio 3
	v_mfma_f32_16x16x32_bf16 v[116:119], v[144:147], v[160:163], v[116:119]
	v_mfma_f32_16x16x32_bf16 v[116:119], v[148:151], v[180:183], v[116:119]
	v_mfma_f32_16x16x32_bf16 v[108:111], v[152:155], v[160:163], v[108:111]
	v_mfma_f32_16x16x32_bf16 v[108:111], v[156:159], v[180:183], v[108:111]
	v_mfma_f32_16x16x32_bf16 v[100:103], v[144:147], v[164:167], v[100:103]
	v_mfma_f32_16x16x32_bf16 v[100:103], v[148:151], v[202:205], v[100:103]
	v_mfma_f32_16x16x32_bf16 v[92:95], v[152:155], v[164:167], v[92:95]
	v_mfma_f32_16x16x32_bf16 v[92:95], v[156:159], v[202:205], v[92:95]
	v_mfma_f32_16x16x32_bf16 v[84:87], v[144:147], v[206:209], v[84:87]
	v_mfma_f32_16x16x32_bf16 v[84:87], v[148:151], v[214:217], v[84:87]
	v_mfma_f32_16x16x32_bf16 v[76:79], v[152:155], v[206:209], v[76:79]
	v_mfma_f32_16x16x32_bf16 v[76:79], v[156:159], v[214:217], v[76:79]
	v_mfma_f32_16x16x32_bf16 v[68:71], v[144:147], v[210:213], v[68:71]
	v_mfma_f32_16x16x32_bf16 v[68:71], v[148:151], v[218:221], v[68:71]
	v_mfma_f32_16x16x32_bf16 v[60:63], v[152:155], v[210:213], v[60:63]
	v_mfma_f32_16x16x32_bf16 v[60:63], v[156:159], v[218:221], v[60:63]
	s_setprio 0
	s_barrier
; #define PG8_STAGE(bufoff, gbase, voff) do { _Pragma("unroll") for (int _i = 0; _i < 2; ++_i) \
;         __builtin_amdgcn_global_load_lds((const unsigned*)((const char*)(gbase) + (voff)[_i]), (LAS unsigned*)(lds + (bufoff) + ldsw + _i * 8192), 16, 0, 0); } while (0)
; #define PG8_LDA(dst, b, h) do { _Pragma("unroll") for (int m = 0; m < 4; ++m) _Pragma("unroll") for (int k = 0; k < 2; ++k) dst[m][k] = *(const LAS bf16x8*)(lds + PG8_SA(b, h) + aoffk[k] + m * 2048); } while (0)
; #define PG8_LDB(dst, b, h) do { _Pragma("unroll") for (int n = 0; n < 2; ++n) _Pragma("unroll") for (int k = 0; k < 2; ++k) dst[n][k] = *(const LAS bf16x8*)(lds + PG8_SB(b, h) + boffk[k] + n * 2048); } while (0)
; #define PG8_WAIT_V(n) asm volatile("s_waitcnt vmcnt(" #n ")" ::: "memory")
; #define PG8_WAIT_L(n) asm volatile("s_waitcnt lgkmcnt(" #n ")" ::: "memory")
; #define PG8_BAR __builtin_amdgcn_s_barrier()
; #define PG8_SCHED __builtin_amdgcn_sched_barrier(0)
; template <class Epi, class Sched, class GemmT>
; __device__ __forceinline__ void gemm_phase(LAS unsigned char* lds, const GemmT& g, const Sched& S, const Epi& E, const int wid) {
;     ...
;                 PG8_LDB(B0, 0, 0); PG8_LDB(B1, 0, 1); PG8_SCHED; PG8_LDA(At, 0, 0); PG8_STAGE(PG8_SA(1, 1), a1 + hstepA, voffA);
;                 PG8_WAIT_V(8); PG8_WAIT_L(0); PG8_BAR; PG8_MMA(0, 0, At, B0); PG8_MMA(0, 1, At, B1); PG8_BAR; PG8_SCHED;
;                 PG8_LDA(At, 0, 1); PG8_STAGE(PG8_SB(0, 0), b2, vB2); PG8_STAGE(PG8_SB(0, 1), b2 + hB2, vB2); PG8_STAGE(PG8_SA(0, 0), a2, vA2);
;                 PG8_WAIT_V(8); PG8_WAIT_L(0); PG8_BAR; PG8_MMA(1, 0, At, B0); PG8_MMA(1, 1, At, B1); PG8_BAR; PG8_SCHED;
;                 PG8_LDB(B0, 1, 0); PG8_LDB(B1, 1, 1); PG8_SCHED; PG8_LDA(At, 1, 0); PG8_STAGE(PG8_SA(0, 1), a2 + hA2, vA2);
;                 PG8_WAIT_V(8); PG8_WAIT_L(0); PG8_BAR; PG8_MMA(0, 0, At, B0); PG8_MMA(0, 1, At, B1); PG8_BAR; PG8_SCHED;
;                 PG8_LDA(At, 1, 1); PG8_STAGE(PG8_SB(1, 0), b3, vB2); PG8_STAGE(PG8_SB(1, 1), b3 + hB2, vB2); PG8_STAGE(PG8_SA(1, 0), a3, vA2);
;                 PG8_WAIT_V(8); PG8_WAIT_L(0); PG8_BAR; PG8_MMA(1, 0, At, B0); PG8_MMA(1, 1, At, B1); PG8_BAR; PG8_SCHED;
	s_add_i32 s26, s57, s68
	v_lshl_add_u64 v[222:223], v[222:223], 0, s[6:7]
	s_mov_b32 m0, s26
	ds_read_b128 v[160:163], v196 offset:49152
	ds_read_b128 v[164:167], v196 offset:51200
	ds_read_b128 v[180:183], v197 offset:49152
	ds_read_b128 v[202:205], v197 offset:51200
	ds_read_b128 v[206:209], v196 offset:53248
	ds_read_b128 v[210:213], v196 offset:55296
	ds_read_b128 v[214:217], v197 offset:53248
	ds_read_b128 v[218:221], v197 offset:55296
	global_load_lds_dwordx4 v[222:223], off
	s_add_i32 m0, s26, 0x2000
	s_add_u32 s24, s24, 0x2b0080
	v_lshl_add_u64 v[222:223], v[224:225], 0, s[6:7]
	s_addc_u32 s25, s25, 0
	s_add_i32 s26, s58, s68
	global_load_lds_dwordx4 v[222:223], off
	v_lshl_add_u64 v[222:223], s[24:25], 0, v[170:171]
	s_mov_b32 m0, s26
	s_nop 0
	global_load_lds_dwordx4 v[222:223], off
	v_lshl_add_u64 v[222:223], s[24:25], 0, v[174:175]
	s_add_i32 m0, s26, 0x2000
	s_nop 0
	global_load_lds_dwordx4 v[222:223], off
	v_lshl_add_u64 v[222:223], v[226:227], 0, s[6:7]
	s_mov_b32 m0, s39
	s_nop 0
	global_load_lds_dwordx4 v[222:223], off
	v_lshl_add_u64 v[222:223], v[228:229], 0, s[6:7]
	s_mov_b32 m0, s40
	s_nop 0
	global_load_lds_dwordx4 v[222:223], off
	s_waitcnt vmcnt(8)
	s_waitcnt lgkmcnt(0)
	s_barrier
	s_setprio 3
	s_waitcnt lgkmcnt(0)
	v_mfma_f32_16x16x32_bf16 v[52:55], v[128:131], v[160:163], v[52:55]
	v_mfma_f32_16x16x32_bf16 v[52:55], v[132:135], v[180:183], v[52:55]
	v_mfma_f32_16x16x32_bf16 v[48:51], v[136:139], v[160:163], v[48:51]
	v_mfma_f32_16x16x32_bf16 v[48:51], v[140:143], v[180:183], v[48:51]
	v_mfma_f32_16x16x32_bf16 v[36:39], v[128:131], v[164:167], v[36:39]
	v_mfma_f32_16x16x32_bf16 v[36:39], v[132:135], v[202:205], v[36:39]
	v_mfma_f32_16x16x32_bf16 v[32:35], v[136:139], v[164:167], v[32:35]
	v_mfma_f32_16x16x32_bf16 v[32:35], v[140:143], v[202:205], v[32:35]
	v_mfma_f32_16x16x32_bf16 v[20:23], v[128:131], v[206:209], v[20:23]
	v_mfma_f32_16x16x32_bf16 v[20:23], v[132:135], v[214:217], v[20:23]
	v_mfma_f32_16x16x32_bf16 v[8:11], v[136:139], v[206:209], v[8:11]
	v_mfma_f32_16x16x32_bf16 v[8:11], v[140:143], v[214:217], v[8:11]
	v_mfma_f32_16x16x32_bf16 v[4:7], v[128:131], v[210:213], v[4:7]
	v_mfma_f32_16x16x32_bf16 v[4:7], v[132:135], v[218:221], v[4:7]
	v_mfma_f32_16x16x32_bf16 v[0:3], v[136:139], v[210:213], v[0:3]
	v_mfma_f32_16x16x32_bf16 v[0:3], v[140:143], v[218:221], v[0:3]
	s_setprio 0
	s_setprio 3
	v_mfma_f32_16x16x32_bf16 v[64:67], v[144:147], v[160:163], v[64:67]
	v_mfma_f32_16x16x32_bf16 v[64:67], v[148:151], v[180:183], v[64:67]
	v_mfma_f32_16x16x32_bf16 v[56:59], v[152:155], v[160:163], v[56:59]
	v_mfma_f32_16x16x32_bf16 v[56:59], v[156:159], v[180:183], v[56:59]
	v_mfma_f32_16x16x32_bf16 v[44:47], v[144:147], v[164:167], v[44:47]
	v_mfma_f32_16x16x32_bf16 v[44:47], v[148:151], v[202:205], v[44:47]
	v_mfma_f32_16x16x32_bf16 v[40:43], v[152:155], v[164:167], v[40:43]
	v_mfma_f32_16x16x32_bf16 v[40:43], v[156:159], v[202:205], v[40:43]
	v_mfma_f32_16x16x32_bf16 v[28:31], v[144:147], v[206:209], v[28:31]
	v_mfma_f32_16x16x32_bf16 v[28:31], v[148:151], v[214:217], v[28:31]
	v_mfma_f32_16x16x32_bf16 v[24:27], v[152:155], v[206:209], v[24:27]
	v_mfma_f32_16x16x32_bf16 v[24:27], v[156:159], v[214:217], v[24:27]
	v_mfma_f32_16x16x32_bf16 v[16:19], v[144:147], v[210:213], v[16:19]
	v_mfma_f32_16x16x32_bf16 v[16:19], v[148:151], v[218:221], v[16:19]
	v_mfma_f32_16x16x32_bf16 v[12:15], v[152:155], v[210:213], v[12:15]
	v_mfma_f32_16x16x32_bf16 v[12:15], v[156:159], v[218:221], v[12:15]
	s_setprio 0
	s_barrier
	s_add_i32 s56, s56, 2
	s_add_u32 s22, s22, 0x100
	s_addc_u32 s23, s23, 0
	s_add_u32 s54, s54, 0x100
	s_addc_u32 s55, s55, 0
	s_cmpk_gt_u32 s56, 0xa9
	s_cbranch_scc0 .LBB0_1096
	s_and_b64 vcc, exec, s[8:9]
	s_cbranch_vccz .LBB0_1099
	s_barrier
